# k6 without the VOP3P dot2 chain form in the PEER u-side (dot2c + zero-init movs kept)
# baseline (speedup 1.0000x reference)
; #define P4_FOR16(M) M(0) M(1) M(2) M(3) M(4) M(5) M(6) M(7) M(8) M(9) M(10) M(11) M(12) M(13) M(14) M(15)
; #define P4_U(i) { P4_DOT(b##i, part[i]); const int nk_ = __builtin_amdgcn_readlane(ksel, nb + i); P4_LOAD(b##i, Ug, nk_); }
; #define P4_U(i) { P4_DOT(b##i, part[i]); const int nk_ = __builtin_amdgcn_readlane(kn, i); P4_LOAD(b##i, nbase, nk_); }
; __device__ __forceinline__ void peer_gather_f4p(const float* X, const int* __restrict__ IDX, const float* __restrict__ G, ...
;     ...
; #pragma unroll 1
;         for (int bt = 0; bt < 7; ++bt) {
;             const int ksel = (bt + 1 < 4) ? k0 : k1;
;             const int nb = (16 * (bt + 1)) & 63;
;     ...
;             P4_FOR16(P4_U)
;     ...
;             P4_RED(bt);
;         }
.LBB0_533:
	s_mov_b32 s87, s86
	s_waitcnt vmcnt(15)
	v_cvt_scalef32_pk_bf16_fp4 v48, v64, 1.0
	v_mov_b32_e32 v56, 0
	v_cvt_scalef32_pk_bf16_fp4 v50, v64, 1.0 op_sel:[1,0,0]
	v_cvt_scalef32_pk_bf16_fp4 v52, v64, 1.0 op_sel:[0,1,0]
	v_cvt_scalef32_pk_bf16_fp4 v54, v64, 1.0 op_sel:[1,1,0]
	v_dot2c_f32_bf16_e32 v56, v48, v6
	v_mov_b32_e32 v48, 0
	v_dot2c_f32_bf16_e32 v48, v50, v4
	v_dot2c_f32_bf16_e32 v56, v52, v10
	s_cmp_lt_u32 s29, 3
	v_dot2c_f32_bf16_e32 v48, v54, v8
	v_cvt_scalef32_pk_bf16_fp4 v50, v65, 1.0
	v_cvt_scalef32_pk_bf16_fp4 v52, v65, 1.0 op_sel:[1,0,0]
	v_cvt_scalef32_pk_bf16_fp4 v54, v65, 1.0 op_sel:[0,1,0]
	v_cvt_scalef32_pk_bf16_fp4 v58, v65, 1.0 op_sel:[1,1,0]
	s_cselect_b64 s[50:51], -1, 0
	v_dot2c_f32_bf16_e32 v56, v50, v14
	v_dot2c_f32_bf16_e32 v48, v52, v12
	s_waitcnt lgkmcnt(1)
	v_cndmask_b32_e64 v46, v39, v38, s[50:51]
	v_dot2c_f32_bf16_e32 v56, v54, v18
	v_dot2c_f32_bf16_e32 v48, v58, v16
	v_cvt_scalef32_pk_bf16_fp4 v50, v66, 1.0
	v_cvt_scalef32_pk_bf16_fp4 v52, v66, 1.0 op_sel:[1,0,0]
	v_cvt_scalef32_pk_bf16_fp4 v54, v66, 1.0 op_sel:[0,1,0]
	v_cvt_scalef32_pk_bf16_fp4 v58, v66, 1.0 op_sel:[1,1,0]
	s_add_i32 s12, s28, -15
	v_dot2c_f32_bf16_e32 v56, v50, v22
	v_dot2c_f32_bf16_e32 v48, v52, v20
	v_readlane_b32 s12, v46, s12
	v_dot2c_f32_bf16_e32 v56, v54, v26
	v_dot2c_f32_bf16_e32 v48, v58, v24
	v_cvt_scalef32_pk_bf16_fp4 v50, v67, 1.0
	v_cvt_scalef32_pk_bf16_fp4 v52, v67, 1.0 op_sel:[1,0,0]
	v_cvt_scalef32_pk_bf16_fp4 v54, v67, 1.0 op_sel:[0,1,0]
	v_cvt_scalef32_pk_bf16_fp4 v58, v67, 1.0 op_sel:[1,1,0]
	s_lshr_b32 s12, s12, 7
	v_dot2c_f32_bf16_e32 v56, v50, v30
	v_dot2c_f32_bf16_e32 v48, v52, v28
	s_mov_b32 s13, s86
	v_dot2c_f32_bf16_e32 v56, v54, v36
	v_dot2c_f32_bf16_e32 v48, v58, v34
	s_lshl_b64 s[12:13], s[12:13], 10
	s_nop 2
	v_readfirstlane_b32 s100, v40
	v_readfirstlane_b32 s101, v41
	v_subrev_u32_e32 v207, s100, v40
	v_add_f32_e32 v47, v56, v48
	s_add_u32 s12, s12, s100
	s_addc_u32 s13, s13, s101
	global_load_dwordx4 v[64:67], v207, s[12:13]
	s_waitcnt vmcnt(15)
	v_cvt_scalef32_pk_bf16_fp4 v48, v68, 1.0
	v_mov_b32_e32 v56, 0
	v_cvt_scalef32_pk_bf16_fp4 v50, v68, 1.0 op_sel:[1,0,0]
	v_cvt_scalef32_pk_bf16_fp4 v52, v68, 1.0 op_sel:[0,1,0]
	v_cvt_scalef32_pk_bf16_fp4 v54, v68, 1.0 op_sel:[1,1,0]
	v_dot2c_f32_bf16_e32 v56, v48, v6
	v_mov_b32_e32 v48, 0
	v_dot2c_f32_bf16_e32 v48, v50, v4
	v_dot2c_f32_bf16_e32 v56, v52, v10
	s_add_i32 s12, s28, -14
	v_dot2c_f32_bf16_e32 v48, v54, v8
	v_cvt_scalef32_pk_bf16_fp4 v50, v69, 1.0
	v_cvt_scalef32_pk_bf16_fp4 v52, v69, 1.0 op_sel:[1,0,0]
	v_cvt_scalef32_pk_bf16_fp4 v54, v69, 1.0 op_sel:[0,1,0]
	v_cvt_scalef32_pk_bf16_fp4 v58, v69, 1.0 op_sel:[1,1,0]
	v_readlane_b32 s12, v46, s12
	v_dot2c_f32_bf16_e32 v56, v50, v14
	v_dot2c_f32_bf16_e32 v48, v52, v12
	s_lshr_b32 s12, s12, 7
	v_dot2c_f32_bf16_e32 v56, v54, v18
	v_dot2c_f32_bf16_e32 v48, v58, v16
	v_cvt_scalef32_pk_bf16_fp4 v50, v70, 1.0
	v_cvt_scalef32_pk_bf16_fp4 v52, v70, 1.0 op_sel:[1,0,0]
	v_cvt_scalef32_pk_bf16_fp4 v54, v70, 1.0 op_sel:[0,1,0]
	v_cvt_scalef32_pk_bf16_fp4 v58, v70, 1.0 op_sel:[1,1,0]
	s_mov_b32 s13, s86
	v_dot2c_f32_bf16_e32 v56, v50, v22
	v_dot2c_f32_bf16_e32 v48, v52, v20
	s_lshl_b64 s[12:13], s[12:13], 10
	v_dot2c_f32_bf16_e32 v56, v54, v26
	v_dot2c_f32_bf16_e32 v48, v58, v24
	v_cvt_scalef32_pk_bf16_fp4 v50, v71, 1.0
	v_cvt_scalef32_pk_bf16_fp4 v52, v71, 1.0 op_sel:[1,0,0]
	v_cvt_scalef32_pk_bf16_fp4 v54, v71, 1.0 op_sel:[0,1,0]
	v_cvt_scalef32_pk_bf16_fp4 v58, v71, 1.0 op_sel:[1,1,0]
	v_mov_b32_e32 v100, 0
	v_dot2c_f32_bf16_e32 v56, v50, v30
	v_dot2c_f32_bf16_e32 v48, v52, v28
	v_mov_b32_e32 v42, 0
	v_dot2c_f32_bf16_e32 v56, v54, v36
	v_dot2c_f32_bf16_e32 v48, v58, v34
	v_mov_b32_e32 v58, 0
	s_nop 2
	v_add_f32_e32 v48, v56, v48
	s_add_u32 s12, s12, s100
	s_addc_u32 s13, s13, s101
	global_load_dwordx4 v[68:71], v207, s[12:13]
	s_waitcnt vmcnt(15)
	v_cvt_scalef32_pk_bf16_fp4 v50, v72, 1.0
	v_cvt_scalef32_pk_bf16_fp4 v52, v72, 1.0 op_sel:[1,0,0]
	v_cvt_scalef32_pk_bf16_fp4 v54, v72, 1.0 op_sel:[0,1,0]
	v_cvt_scalef32_pk_bf16_fp4 v56, v72, 1.0 op_sel:[1,1,0]
	s_add_i32 s12, s28, -13
	v_dot2c_f32_bf16_e32 v58, v50, v6
	v_mov_b32_e32 v50, 0
	v_dot2c_f32_bf16_e32 v50, v52, v4
	v_dot2c_f32_bf16_e32 v58, v54, v10
	v_readlane_b32 s12, v46, s12
	v_dot2c_f32_bf16_e32 v50, v56, v8
	v_cvt_scalef32_pk_bf16_fp4 v52, v73, 1.0
	v_cvt_scalef32_pk_bf16_fp4 v54, v73, 1.0 op_sel:[1,0,0]
	v_cvt_scalef32_pk_bf16_fp4 v56, v73, 1.0 op_sel:[0,1,0]
	v_cvt_scalef32_pk_bf16_fp4 v60, v73, 1.0 op_sel:[1,1,0]
	s_lshr_b32 s12, s12, 7
	v_dot2c_f32_bf16_e32 v58, v52, v14
	v_dot2c_f32_bf16_e32 v50, v54, v12
	s_mov_b32 s13, s86
	v_dot2c_f32_bf16_e32 v58, v56, v18
	v_dot2c_f32_bf16_e32 v50, v60, v16
	v_cvt_scalef32_pk_bf16_fp4 v52, v74, 1.0
	v_cvt_scalef32_pk_bf16_fp4 v54, v74, 1.0 op_sel:[1,0,0]
	v_cvt_scalef32_pk_bf16_fp4 v56, v74, 1.0 op_sel:[0,1,0]
	v_cvt_scalef32_pk_bf16_fp4 v60, v74, 1.0 op_sel:[1,1,0]
	s_lshl_b64 s[12:13], s[12:13], 10
	v_dot2c_f32_bf16_e32 v58, v52, v22
	v_dot2c_f32_bf16_e32 v50, v54, v20
	s_nop 0
	v_dot2c_f32_bf16_e32 v58, v56, v26
	v_dot2c_f32_bf16_e32 v50, v60, v24
	v_cvt_scalef32_pk_bf16_fp4 v52, v75, 1.0
	v_cvt_scalef32_pk_bf16_fp4 v54, v75, 1.0 op_sel:[1,0,0]
	v_cvt_scalef32_pk_bf16_fp4 v56, v75, 1.0 op_sel:[0,1,0]
	v_cvt_scalef32_pk_bf16_fp4 v60, v75, 1.0 op_sel:[1,1,0]
	s_nop 0
	v_dot2c_f32_bf16_e32 v58, v52, v30
	v_dot2c_f32_bf16_e32 v50, v54, v28
	s_nop 0
	v_dot2c_f32_bf16_e32 v58, v56, v36
	v_dot2c_f32_bf16_e32 v50, v60, v34
	s_nop 0
	s_nop 2
	v_add_f32_e32 v49, v58, v50
	s_add_u32 s12, s12, s100
	s_addc_u32 s13, s13, s101
	global_load_dwordx4 v[72:75], v207, s[12:13]
	s_waitcnt vmcnt(15)
; #define P4_FOR16(M) M(0) M(1) M(2) M(3) M(4) M(5) M(6) M(7) M(8) M(9) M(10) M(11) M(12) M(13) M(14) M(15)
; #define P4_U(i) { P4_DOT(b##i, part[i]); const int nk_ = __builtin_amdgcn_readlane(ksel, nb + i); P4_LOAD(b##i, Ug, nk_); }
; #define P4_U(i) { P4_DOT(b##i, part[i]); const int nk_ = __builtin_amdgcn_readlane(kn, i); P4_LOAD(b##i, nbase, nk_); }
; __device__ __forceinline__ void peer_gather_f4p(const float* X, const int* __restrict__ IDX, const float* __restrict__ G, ...
;     ...
; #pragma unroll 1
;         for (int bt = 0; bt < 7; ++bt) {
;             const int ksel = (bt + 1 < 4) ? k0 : k1;
;             const int nb = (16 * (bt + 1)) & 63;
;     ...
;             P4_FOR16(P4_U)
;     ...
;             P4_RED(bt);
;         }
	v_cvt_scalef32_pk_bf16_fp4 v50, v76, 1.0
	v_mov_b32_e32 v58, 0
	v_cvt_scalef32_pk_bf16_fp4 v52, v76, 1.0 op_sel:[1,0,0]
	v_cvt_scalef32_pk_bf16_fp4 v54, v76, 1.0 op_sel:[0,1,0]
	v_cvt_scalef32_pk_bf16_fp4 v56, v76, 1.0 op_sel:[1,1,0]
	v_dot2c_f32_bf16_e32 v58, v50, v6
	v_mov_b32_e32 v50, 0
	v_dot2c_f32_bf16_e32 v50, v52, v4
	v_dot2c_f32_bf16_e32 v58, v54, v10
	s_add_i32 s12, s28, -12
	v_dot2c_f32_bf16_e32 v50, v56, v8
	v_cvt_scalef32_pk_bf16_fp4 v52, v77, 1.0
	v_cvt_scalef32_pk_bf16_fp4 v54, v77, 1.0 op_sel:[1,0,0]
	v_cvt_scalef32_pk_bf16_fp4 v56, v77, 1.0 op_sel:[0,1,0]
	v_cvt_scalef32_pk_bf16_fp4 v60, v77, 1.0 op_sel:[1,1,0]
	v_readlane_b32 s12, v46, s12
	v_dot2c_f32_bf16_e32 v58, v52, v14
	v_dot2c_f32_bf16_e32 v50, v54, v12
	s_lshr_b32 s12, s12, 7
	v_dot2c_f32_bf16_e32 v58, v56, v18
	v_dot2c_f32_bf16_e32 v50, v60, v16
	v_cvt_scalef32_pk_bf16_fp4 v52, v78, 1.0
	v_cvt_scalef32_pk_bf16_fp4 v54, v78, 1.0 op_sel:[1,0,0]
	v_cvt_scalef32_pk_bf16_fp4 v56, v78, 1.0 op_sel:[0,1,0]
	v_cvt_scalef32_pk_bf16_fp4 v60, v78, 1.0 op_sel:[1,1,0]
	s_mov_b32 s13, s86
	v_dot2c_f32_bf16_e32 v58, v52, v22
	v_dot2c_f32_bf16_e32 v50, v54, v20
	s_lshl_b64 s[12:13], s[12:13], 10
	v_dot2c_f32_bf16_e32 v58, v56, v26
	v_dot2c_f32_bf16_e32 v50, v60, v24
	v_cvt_scalef32_pk_bf16_fp4 v52, v79, 1.0
	v_cvt_scalef32_pk_bf16_fp4 v54, v79, 1.0 op_sel:[1,0,0]
	v_cvt_scalef32_pk_bf16_fp4 v56, v79, 1.0 op_sel:[0,1,0]
	v_cvt_scalef32_pk_bf16_fp4 v60, v79, 1.0 op_sel:[1,1,0]
	s_nop 0
	v_dot2c_f32_bf16_e32 v58, v52, v30
	v_dot2c_f32_bf16_e32 v50, v54, v28
	s_nop 0
	v_dot2c_f32_bf16_e32 v58, v56, v36
	v_dot2c_f32_bf16_e32 v50, v60, v34
	v_mov_b32_e32 v60, 0
	s_nop 2
	v_add_f32_e32 v50, v58, v50
	s_add_u32 s12, s12, s100
	s_addc_u32 s13, s13, s101
	global_load_dwordx4 v[76:79], v207, s[12:13]
	s_waitcnt vmcnt(15)
	v_cvt_scalef32_pk_bf16_fp4 v52, v80, 1.0
	v_cvt_scalef32_pk_bf16_fp4 v54, v80, 1.0 op_sel:[1,0,0]
	v_cvt_scalef32_pk_bf16_fp4 v56, v80, 1.0 op_sel:[0,1,0]
	v_cvt_scalef32_pk_bf16_fp4 v58, v80, 1.0 op_sel:[1,1,0]
	s_add_i32 s12, s28, -11
	v_dot2c_f32_bf16_e32 v60, v52, v6
	v_mov_b32_e32 v52, 0
	v_dot2c_f32_bf16_e32 v52, v54, v4
	v_dot2c_f32_bf16_e32 v60, v56, v10
	v_readlane_b32 s12, v46, s12
	v_dot2c_f32_bf16_e32 v52, v58, v8
	v_cvt_scalef32_pk_bf16_fp4 v54, v81, 1.0
	v_cvt_scalef32_pk_bf16_fp4 v56, v81, 1.0 op_sel:[1,0,0]
	v_cvt_scalef32_pk_bf16_fp4 v58, v81, 1.0 op_sel:[0,1,0]
	v_cvt_scalef32_pk_bf16_fp4 v62, v81, 1.0 op_sel:[1,1,0]
	s_lshr_b32 s12, s12, 7
	v_dot2c_f32_bf16_e32 v60, v54, v14
	v_dot2c_f32_bf16_e32 v52, v56, v12
	s_mov_b32 s13, s86
	v_dot2c_f32_bf16_e32 v60, v58, v18
	v_dot2c_f32_bf16_e32 v52, v62, v16
	v_cvt_scalef32_pk_bf16_fp4 v54, v82, 1.0
	v_cvt_scalef32_pk_bf16_fp4 v56, v82, 1.0 op_sel:[1,0,0]
	v_cvt_scalef32_pk_bf16_fp4 v58, v82, 1.0 op_sel:[0,1,0]
	v_cvt_scalef32_pk_bf16_fp4 v62, v82, 1.0 op_sel:[1,1,0]
	s_lshl_b64 s[12:13], s[12:13], 10
	v_dot2c_f32_bf16_e32 v60, v54, v22
	v_dot2c_f32_bf16_e32 v52, v56, v20
	s_nop 0
	v_dot2c_f32_bf16_e32 v60, v58, v26
	v_dot2c_f32_bf16_e32 v52, v62, v24
	v_cvt_scalef32_pk_bf16_fp4 v54, v83, 1.0
	v_cvt_scalef32_pk_bf16_fp4 v56, v83, 1.0 op_sel:[1,0,0]
	v_cvt_scalef32_pk_bf16_fp4 v58, v83, 1.0 op_sel:[0,1,0]
	v_cvt_scalef32_pk_bf16_fp4 v62, v83, 1.0 op_sel:[1,1,0]
	s_nop 0
	v_dot2c_f32_bf16_e32 v60, v54, v30
	v_dot2c_f32_bf16_e32 v52, v56, v28
	s_nop 0
	v_dot2c_f32_bf16_e32 v60, v58, v36
	v_dot2c_f32_bf16_e32 v52, v62, v34
	s_nop 0
	s_nop 2
	v_add_f32_e32 v51, v60, v52
	s_add_u32 s12, s12, s100
	s_addc_u32 s13, s13, s101
	global_load_dwordx4 v[80:83], v207, s[12:13]
	s_waitcnt vmcnt(15)
	v_cvt_scalef32_pk_bf16_fp4 v52, v84, 1.0
	v_mov_b32_e32 v60, 0
	v_cvt_scalef32_pk_bf16_fp4 v54, v84, 1.0 op_sel:[1,0,0]
	v_cvt_scalef32_pk_bf16_fp4 v56, v84, 1.0 op_sel:[0,1,0]
	v_cvt_scalef32_pk_bf16_fp4 v58, v84, 1.0 op_sel:[1,1,0]
	v_dot2c_f32_bf16_e32 v60, v52, v6
	v_mov_b32_e32 v52, 0
	v_dot2c_f32_bf16_e32 v52, v54, v4
	v_dot2c_f32_bf16_e32 v60, v56, v10
	s_add_i32 s12, s28, -10
	v_dot2c_f32_bf16_e32 v52, v58, v8
	v_cvt_scalef32_pk_bf16_fp4 v54, v85, 1.0
	v_cvt_scalef32_pk_bf16_fp4 v56, v85, 1.0 op_sel:[1,0,0]
	v_cvt_scalef32_pk_bf16_fp4 v58, v85, 1.0 op_sel:[0,1,0]
	v_cvt_scalef32_pk_bf16_fp4 v62, v85, 1.0 op_sel:[1,1,0]
	v_readlane_b32 s12, v46, s12
	v_dot2c_f32_bf16_e32 v60, v54, v14
	v_dot2c_f32_bf16_e32 v52, v56, v12
	s_lshr_b32 s12, s12, 7
	v_dot2c_f32_bf16_e32 v60, v58, v18
	v_dot2c_f32_bf16_e32 v52, v62, v16
	v_cvt_scalef32_pk_bf16_fp4 v54, v86, 1.0
	v_cvt_scalef32_pk_bf16_fp4 v56, v86, 1.0 op_sel:[1,0,0]
	v_cvt_scalef32_pk_bf16_fp4 v58, v86, 1.0 op_sel:[0,1,0]
	v_cvt_scalef32_pk_bf16_fp4 v62, v86, 1.0 op_sel:[1,1,0]
	s_mov_b32 s13, s86
	v_dot2c_f32_bf16_e32 v60, v54, v22
	v_dot2c_f32_bf16_e32 v52, v56, v20
	s_lshl_b64 s[12:13], s[12:13], 10
	v_dot2c_f32_bf16_e32 v60, v58, v26
	v_dot2c_f32_bf16_e32 v52, v62, v24
	v_cvt_scalef32_pk_bf16_fp4 v54, v87, 1.0
	v_cvt_scalef32_pk_bf16_fp4 v56, v87, 1.0 op_sel:[1,0,0]
	v_cvt_scalef32_pk_bf16_fp4 v58, v87, 1.0 op_sel:[0,1,0]
	v_cvt_scalef32_pk_bf16_fp4 v62, v87, 1.0 op_sel:[1,1,0]
	s_nop 0
	v_dot2c_f32_bf16_e32 v60, v54, v30
	v_dot2c_f32_bf16_e32 v52, v56, v28
	s_nop 0
	v_dot2c_f32_bf16_e32 v60, v58, v36
	v_dot2c_f32_bf16_e32 v52, v62, v34
	v_mov_b32_e32 v62, 0
	s_nop 2
	v_add_f32_e32 v52, v60, v52
	s_add_u32 s12, s12, s100
	s_addc_u32 s13, s13, s101
	global_load_dwordx4 v[84:87], v207, s[12:13]
	s_waitcnt vmcnt(15)
; #define P4_FOR16(M) M(0) M(1) M(2) M(3) M(4) M(5) M(6) M(7) M(8) M(9) M(10) M(11) M(12) M(13) M(14) M(15)
; #define P4_U(i) { P4_DOT(b##i, part[i]); const int nk_ = __builtin_amdgcn_readlane(ksel, nb + i); P4_LOAD(b##i, Ug, nk_); }
; #define P4_U(i) { P4_DOT(b##i, part[i]); const int nk_ = __builtin_amdgcn_readlane(kn, i); P4_LOAD(b##i, nbase, nk_); }
; __device__ __forceinline__ void peer_gather_f4p(const float* X, const int* __restrict__ IDX, const float* __restrict__ G, ...
;     ...
; #pragma unroll 1
;         for (int bt = 0; bt < 7; ++bt) {
;             const int ksel = (bt + 1 < 4) ? k0 : k1;
;             const int nb = (16 * (bt + 1)) & 63;
;     ...
;             P4_FOR16(P4_U)
;     ...
;             P4_RED(bt);
;         }
	v_cvt_scalef32_pk_bf16_fp4 v54, v88, 1.0
	v_cvt_scalef32_pk_bf16_fp4 v56, v88, 1.0 op_sel:[1,0,0]
	v_cvt_scalef32_pk_bf16_fp4 v58, v88, 1.0 op_sel:[0,1,0]
	v_cvt_scalef32_pk_bf16_fp4 v60, v88, 1.0 op_sel:[1,1,0]
	s_add_i32 s12, s28, -9
	v_dot2c_f32_bf16_e32 v62, v54, v6
	v_mov_b32_e32 v54, 0
	v_dot2c_f32_bf16_e32 v54, v56, v4
	v_dot2c_f32_bf16_e32 v62, v58, v10
	v_readlane_b32 s12, v46, s12
	v_dot2c_f32_bf16_e32 v54, v60, v8
	v_cvt_scalef32_pk_bf16_fp4 v56, v89, 1.0
	v_cvt_scalef32_pk_bf16_fp4 v58, v89, 1.0 op_sel:[1,0,0]
	v_cvt_scalef32_pk_bf16_fp4 v60, v89, 1.0 op_sel:[0,1,0]
	v_cvt_scalef32_pk_bf16_fp4 v88, v89, 1.0 op_sel:[1,1,0]
	s_lshr_b32 s12, s12, 7
	v_dot2c_f32_bf16_e32 v62, v56, v14
	v_dot2c_f32_bf16_e32 v54, v58, v12
	s_mov_b32 s13, s86
	v_dot2c_f32_bf16_e32 v62, v60, v18
	v_dot2c_f32_bf16_e32 v54, v88, v16
	v_cvt_scalef32_pk_bf16_fp4 v56, v90, 1.0
	v_cvt_scalef32_pk_bf16_fp4 v58, v90, 1.0 op_sel:[1,0,0]
	v_cvt_scalef32_pk_bf16_fp4 v60, v90, 1.0 op_sel:[0,1,0]
	v_cvt_scalef32_pk_bf16_fp4 v88, v90, 1.0 op_sel:[1,1,0]
	s_lshl_b64 s[12:13], s[12:13], 10
	v_dot2c_f32_bf16_e32 v62, v56, v22
	v_dot2c_f32_bf16_e32 v54, v58, v20
	s_nop 0
	v_dot2c_f32_bf16_e32 v62, v60, v26
	v_dot2c_f32_bf16_e32 v54, v88, v24
	v_cvt_scalef32_pk_bf16_fp4 v56, v91, 1.0
	v_cvt_scalef32_pk_bf16_fp4 v58, v91, 1.0 op_sel:[1,0,0]
	v_cvt_scalef32_pk_bf16_fp4 v60, v91, 1.0 op_sel:[0,1,0]
	v_cvt_scalef32_pk_bf16_fp4 v88, v91, 1.0 op_sel:[1,1,0]
	s_nop 0
	v_dot2c_f32_bf16_e32 v62, v56, v30
	v_dot2c_f32_bf16_e32 v54, v58, v28
	s_nop 0
	v_dot2c_f32_bf16_e32 v62, v60, v36
	v_dot2c_f32_bf16_e32 v54, v88, v34
	s_nop 0
	s_nop 2
	v_add_f32_e32 v53, v62, v54
	s_add_u32 s12, s12, s100
	s_addc_u32 s13, s13, s101
	global_load_dwordx4 v[88:91], v207, s[12:13]
	s_waitcnt vmcnt(15)
	v_cvt_scalef32_pk_bf16_fp4 v54, v92, 1.0
	v_mov_b32_e32 v62, 0
	v_cvt_scalef32_pk_bf16_fp4 v56, v92, 1.0 op_sel:[1,0,0]
	v_cvt_scalef32_pk_bf16_fp4 v58, v92, 1.0 op_sel:[0,1,0]
	v_cvt_scalef32_pk_bf16_fp4 v60, v92, 1.0 op_sel:[1,1,0]
	v_dot2c_f32_bf16_e32 v62, v54, v6
	v_mov_b32_e32 v54, 0
	v_dot2c_f32_bf16_e32 v54, v56, v4
	v_dot2c_f32_bf16_e32 v62, v58, v10
	s_add_i32 s12, s28, -8
	v_dot2c_f32_bf16_e32 v54, v60, v8
	v_cvt_scalef32_pk_bf16_fp4 v56, v93, 1.0
	v_cvt_scalef32_pk_bf16_fp4 v58, v93, 1.0 op_sel:[1,0,0]
	v_cvt_scalef32_pk_bf16_fp4 v60, v93, 1.0 op_sel:[0,1,0]
	v_cvt_scalef32_pk_bf16_fp4 v92, v93, 1.0 op_sel:[1,1,0]
	v_readlane_b32 s12, v46, s12
	v_dot2c_f32_bf16_e32 v62, v56, v14
	v_dot2c_f32_bf16_e32 v54, v58, v12
	s_lshr_b32 s12, s12, 7
	v_dot2c_f32_bf16_e32 v62, v60, v18
	v_dot2c_f32_bf16_e32 v54, v92, v16
	v_cvt_scalef32_pk_bf16_fp4 v56, v94, 1.0
	v_cvt_scalef32_pk_bf16_fp4 v58, v94, 1.0 op_sel:[1,0,0]
	v_cvt_scalef32_pk_bf16_fp4 v60, v94, 1.0 op_sel:[0,1,0]
	v_cvt_scalef32_pk_bf16_fp4 v92, v94, 1.0 op_sel:[1,1,0]
	s_mov_b32 s13, s86
	v_dot2c_f32_bf16_e32 v62, v56, v22
	v_dot2c_f32_bf16_e32 v54, v58, v20
	s_lshl_b64 s[12:13], s[12:13], 10
	v_dot2c_f32_bf16_e32 v62, v60, v26
	v_dot2c_f32_bf16_e32 v54, v92, v24
	v_cvt_scalef32_pk_bf16_fp4 v56, v95, 1.0
	v_cvt_scalef32_pk_bf16_fp4 v58, v95, 1.0 op_sel:[1,0,0]
	v_cvt_scalef32_pk_bf16_fp4 v60, v95, 1.0 op_sel:[0,1,0]
	v_cvt_scalef32_pk_bf16_fp4 v92, v95, 1.0 op_sel:[1,1,0]
	s_nop 0
	v_dot2c_f32_bf16_e32 v62, v56, v30
	v_dot2c_f32_bf16_e32 v54, v58, v28
	s_nop 0
	v_dot2c_f32_bf16_e32 v62, v60, v36
	v_dot2c_f32_bf16_e32 v54, v92, v34
	s_nop 0
	s_nop 2
	v_add_f32_e32 v54, v62, v54
	s_add_u32 s12, s12, s100
	s_addc_u32 s13, s13, s101
	global_load_dwordx4 v[92:95], v207, s[12:13]
	s_waitcnt vmcnt(15)
	v_cvt_scalef32_pk_bf16_fp4 v56, v96, 1.0
	v_cvt_scalef32_pk_bf16_fp4 v58, v96, 1.0 op_sel:[1,0,0]
	v_cvt_scalef32_pk_bf16_fp4 v60, v96, 1.0 op_sel:[0,1,0]
	v_cvt_scalef32_pk_bf16_fp4 v62, v96, 1.0 op_sel:[1,1,0]
	s_add_i32 s12, s28, -7
	v_dot2c_f32_bf16_e32 v100, v56, v6
	v_mov_b32_e32 v56, 0
	v_dot2c_f32_bf16_e32 v56, v58, v4
	v_dot2c_f32_bf16_e32 v100, v60, v10
	v_readlane_b32 s12, v46, s12
	v_dot2c_f32_bf16_e32 v56, v62, v8
	v_cvt_scalef32_pk_bf16_fp4 v58, v97, 1.0
	v_cvt_scalef32_pk_bf16_fp4 v60, v97, 1.0 op_sel:[1,0,0]
	v_cvt_scalef32_pk_bf16_fp4 v62, v97, 1.0 op_sel:[0,1,0]
	v_cvt_scalef32_pk_bf16_fp4 v96, v97, 1.0 op_sel:[1,1,0]
	s_lshr_b32 s12, s12, 7
	v_dot2c_f32_bf16_e32 v100, v58, v14
	v_dot2c_f32_bf16_e32 v56, v60, v12
	s_mov_b32 s13, s86
	v_dot2c_f32_bf16_e32 v100, v62, v18
	v_dot2c_f32_bf16_e32 v56, v96, v16
	v_cvt_scalef32_pk_bf16_fp4 v58, v98, 1.0
	v_cvt_scalef32_pk_bf16_fp4 v60, v98, 1.0 op_sel:[1,0,0]
	v_cvt_scalef32_pk_bf16_fp4 v62, v98, 1.0 op_sel:[0,1,0]
	v_cvt_scalef32_pk_bf16_fp4 v96, v98, 1.0 op_sel:[1,1,0]
	s_lshl_b64 s[12:13], s[12:13], 10
	v_dot2c_f32_bf16_e32 v100, v58, v22
	v_dot2c_f32_bf16_e32 v56, v60, v20
	s_nop 0
	v_dot2c_f32_bf16_e32 v100, v62, v26
	v_dot2c_f32_bf16_e32 v56, v96, v24
	v_cvt_scalef32_pk_bf16_fp4 v58, v99, 1.0
	v_cvt_scalef32_pk_bf16_fp4 v60, v99, 1.0 op_sel:[1,0,0]
	v_cvt_scalef32_pk_bf16_fp4 v62, v99, 1.0 op_sel:[0,1,0]
	v_cvt_scalef32_pk_bf16_fp4 v96, v99, 1.0 op_sel:[1,1,0]
	s_nop 0
	v_dot2c_f32_bf16_e32 v100, v58, v30
	v_dot2c_f32_bf16_e32 v56, v60, v28
	s_nop 0
	v_dot2c_f32_bf16_e32 v100, v62, v36
	v_dot2c_f32_bf16_e32 v56, v96, v34
	s_nop 0
	s_nop 2
	v_add_f32_e32 v55, v100, v56
	s_add_u32 s12, s12, s100
	s_addc_u32 s13, s13, s101
	global_load_dwordx4 v[96:99], v207, s[12:13]
	s_waitcnt vmcnt(15)
; #define P4_FOR16(M) M(0) M(1) M(2) M(3) M(4) M(5) M(6) M(7) M(8) M(9) M(10) M(11) M(12) M(13) M(14) M(15)
; #define P4_U(i) { P4_DOT(b##i, part[i]); const int nk_ = __builtin_amdgcn_readlane(ksel, nb + i); P4_LOAD(b##i, Ug, nk_); }
; #define P4_U(i) { P4_DOT(b##i, part[i]); const int nk_ = __builtin_amdgcn_readlane(kn, i); P4_LOAD(b##i, nbase, nk_); }
; __device__ __forceinline__ void peer_gather_f4p(const float* X, const int* __restrict__ IDX, const float* __restrict__ G, ...
;     ...
; #pragma unroll 1
;         for (int bt = 0; bt < 7; ++bt) {
;             const int ksel = (bt + 1 < 4) ? k0 : k1;
;             const int nb = (16 * (bt + 1)) & 63;
;     ...
;             P4_FOR16(P4_U)
;     ...
;             P4_RED(bt);
;         }
	v_cvt_scalef32_pk_bf16_fp4 v56, v104, 1.0
	v_mov_b32_e32 v100, 0
	v_cvt_scalef32_pk_bf16_fp4 v58, v104, 1.0 op_sel:[1,0,0]
	v_cvt_scalef32_pk_bf16_fp4 v60, v104, 1.0 op_sel:[0,1,0]
	v_cvt_scalef32_pk_bf16_fp4 v62, v104, 1.0 op_sel:[1,1,0]
	v_dot2c_f32_bf16_e32 v100, v56, v6
	v_mov_b32_e32 v56, 0
	v_dot2c_f32_bf16_e32 v56, v58, v4
	v_dot2c_f32_bf16_e32 v100, v60, v10
	s_add_i32 s12, s28, -6
	v_dot2c_f32_bf16_e32 v56, v62, v8
	v_cvt_scalef32_pk_bf16_fp4 v58, v105, 1.0
	v_cvt_scalef32_pk_bf16_fp4 v60, v105, 1.0 op_sel:[1,0,0]
	v_cvt_scalef32_pk_bf16_fp4 v62, v105, 1.0 op_sel:[0,1,0]
	v_cvt_scalef32_pk_bf16_fp4 v102, v105, 1.0 op_sel:[1,1,0]
	v_readlane_b32 s12, v46, s12
	v_dot2c_f32_bf16_e32 v100, v58, v14
	v_dot2c_f32_bf16_e32 v56, v60, v12
	s_lshr_b32 s12, s12, 7
	v_dot2c_f32_bf16_e32 v100, v62, v18
	v_dot2c_f32_bf16_e32 v56, v102, v16
	v_cvt_scalef32_pk_bf16_fp4 v58, v106, 1.0
	v_cvt_scalef32_pk_bf16_fp4 v60, v106, 1.0 op_sel:[1,0,0]
	v_cvt_scalef32_pk_bf16_fp4 v62, v106, 1.0 op_sel:[0,1,0]
	v_cvt_scalef32_pk_bf16_fp4 v102, v106, 1.0 op_sel:[1,1,0]
	s_mov_b32 s13, s86
	v_dot2c_f32_bf16_e32 v100, v58, v22
	v_dot2c_f32_bf16_e32 v56, v60, v20
	s_lshl_b64 s[12:13], s[12:13], 10
	v_dot2c_f32_bf16_e32 v100, v62, v26
	v_dot2c_f32_bf16_e32 v56, v102, v24
	v_cvt_scalef32_pk_bf16_fp4 v58, v107, 1.0
	v_cvt_scalef32_pk_bf16_fp4 v60, v107, 1.0 op_sel:[1,0,0]
	v_cvt_scalef32_pk_bf16_fp4 v62, v107, 1.0 op_sel:[0,1,0]
	v_cvt_scalef32_pk_bf16_fp4 v102, v107, 1.0 op_sel:[1,1,0]
	s_nop 0
	v_dot2c_f32_bf16_e32 v100, v58, v30
	v_dot2c_f32_bf16_e32 v56, v60, v28
	s_nop 0
	v_dot2c_f32_bf16_e32 v100, v62, v36
	v_dot2c_f32_bf16_e32 v56, v102, v34
	v_mov_b32_e32 v102, 0
	s_nop 2
	v_add_f32_e32 v56, v100, v56
	s_add_u32 s12, s12, s100
	s_addc_u32 s13, s13, s101
	global_load_dwordx4 v[104:107], v207, s[12:13]
	s_waitcnt vmcnt(15)
	v_cvt_scalef32_pk_bf16_fp4 v58, v108, 1.0
	v_cvt_scalef32_pk_bf16_fp4 v60, v108, 1.0 op_sel:[1,0,0]
	v_cvt_scalef32_pk_bf16_fp4 v62, v108, 1.0 op_sel:[0,1,0]
	v_cvt_scalef32_pk_bf16_fp4 v100, v108, 1.0 op_sel:[1,1,0]
	s_add_i32 s12, s28, -5
	v_dot2c_f32_bf16_e32 v102, v58, v6
	v_mov_b32_e32 v58, 0
	v_dot2c_f32_bf16_e32 v58, v60, v4
	v_dot2c_f32_bf16_e32 v102, v62, v10
	v_readlane_b32 s12, v46, s12
	v_dot2c_f32_bf16_e32 v58, v100, v8
	v_cvt_scalef32_pk_bf16_fp4 v60, v109, 1.0
	v_cvt_scalef32_pk_bf16_fp4 v62, v109, 1.0 op_sel:[1,0,0]
	v_cvt_scalef32_pk_bf16_fp4 v100, v109, 1.0 op_sel:[0,1,0]
	v_cvt_scalef32_pk_bf16_fp4 v108, v109, 1.0 op_sel:[1,1,0]
	s_lshr_b32 s12, s12, 7
	v_dot2c_f32_bf16_e32 v102, v60, v14
	v_dot2c_f32_bf16_e32 v58, v62, v12
	s_mov_b32 s13, s86
	v_dot2c_f32_bf16_e32 v102, v100, v18
	v_dot2c_f32_bf16_e32 v58, v108, v16
	v_cvt_scalef32_pk_bf16_fp4 v60, v110, 1.0
	v_cvt_scalef32_pk_bf16_fp4 v62, v110, 1.0 op_sel:[1,0,0]
	v_cvt_scalef32_pk_bf16_fp4 v100, v110, 1.0 op_sel:[0,1,0]
	v_cvt_scalef32_pk_bf16_fp4 v108, v110, 1.0 op_sel:[1,1,0]
	s_lshl_b64 s[12:13], s[12:13], 10
	v_dot2c_f32_bf16_e32 v102, v60, v22
	v_dot2c_f32_bf16_e32 v58, v62, v20
	s_nop 0
	v_dot2c_f32_bf16_e32 v102, v100, v26
	v_dot2c_f32_bf16_e32 v58, v108, v24
	v_cvt_scalef32_pk_bf16_fp4 v60, v111, 1.0
	v_cvt_scalef32_pk_bf16_fp4 v62, v111, 1.0 op_sel:[1,0,0]
	v_cvt_scalef32_pk_bf16_fp4 v100, v111, 1.0 op_sel:[0,1,0]
	v_cvt_scalef32_pk_bf16_fp4 v108, v111, 1.0 op_sel:[1,1,0]
	s_nop 0
	v_dot2c_f32_bf16_e32 v102, v60, v30
	v_dot2c_f32_bf16_e32 v58, v62, v28
	s_nop 0
	v_dot2c_f32_bf16_e32 v102, v100, v36
	v_dot2c_f32_bf16_e32 v58, v108, v34
	s_nop 0
	s_nop 2
	v_add_f32_e32 v57, v102, v58
	s_add_u32 s12, s12, s100
	s_addc_u32 s13, s13, s101
	global_load_dwordx4 v[108:111], v207, s[12:13]
	s_waitcnt vmcnt(15)
	v_cvt_scalef32_pk_bf16_fp4 v58, v112, 1.0
	v_mov_b32_e32 v102, 0
	v_cvt_scalef32_pk_bf16_fp4 v60, v112, 1.0 op_sel:[1,0,0]
	v_cvt_scalef32_pk_bf16_fp4 v62, v112, 1.0 op_sel:[0,1,0]
	v_cvt_scalef32_pk_bf16_fp4 v100, v112, 1.0 op_sel:[1,1,0]
	v_dot2c_f32_bf16_e32 v102, v58, v6
	v_mov_b32_e32 v58, 0
	v_dot2c_f32_bf16_e32 v58, v60, v4
	v_dot2c_f32_bf16_e32 v102, v62, v10
	s_add_i32 s12, s28, -4
	v_dot2c_f32_bf16_e32 v58, v100, v8
	v_cvt_scalef32_pk_bf16_fp4 v60, v113, 1.0
	v_cvt_scalef32_pk_bf16_fp4 v62, v113, 1.0 op_sel:[1,0,0]
	v_cvt_scalef32_pk_bf16_fp4 v100, v113, 1.0 op_sel:[0,1,0]
	v_cvt_scalef32_pk_bf16_fp4 v112, v113, 1.0 op_sel:[1,1,0]
	v_readlane_b32 s12, v46, s12
	v_dot2c_f32_bf16_e32 v102, v60, v14
	v_dot2c_f32_bf16_e32 v58, v62, v12
	s_lshr_b32 s12, s12, 7
	v_dot2c_f32_bf16_e32 v102, v100, v18
	v_dot2c_f32_bf16_e32 v58, v112, v16
	v_cvt_scalef32_pk_bf16_fp4 v60, v114, 1.0
	v_cvt_scalef32_pk_bf16_fp4 v62, v114, 1.0 op_sel:[1,0,0]
	v_cvt_scalef32_pk_bf16_fp4 v100, v114, 1.0 op_sel:[0,1,0]
	v_cvt_scalef32_pk_bf16_fp4 v112, v114, 1.0 op_sel:[1,1,0]
	s_mov_b32 s13, s86
	v_dot2c_f32_bf16_e32 v102, v60, v22
	v_dot2c_f32_bf16_e32 v58, v62, v20
	s_lshl_b64 s[12:13], s[12:13], 10
	v_dot2c_f32_bf16_e32 v102, v100, v26
	v_dot2c_f32_bf16_e32 v58, v112, v24
	v_cvt_scalef32_pk_bf16_fp4 v60, v115, 1.0
	v_cvt_scalef32_pk_bf16_fp4 v62, v115, 1.0 op_sel:[1,0,0]
	v_cvt_scalef32_pk_bf16_fp4 v100, v115, 1.0 op_sel:[0,1,0]
	v_cvt_scalef32_pk_bf16_fp4 v112, v115, 1.0 op_sel:[1,1,0]
	s_nop 0
	v_dot2c_f32_bf16_e32 v102, v60, v30
	v_dot2c_f32_bf16_e32 v58, v62, v28
	s_nop 0
	v_dot2c_f32_bf16_e32 v102, v100, v36
	v_dot2c_f32_bf16_e32 v58, v112, v34
	s_nop 0
	s_nop 2
	v_add_f32_e32 v132, v102, v58
	s_add_u32 s12, s12, s100
	s_addc_u32 s13, s13, s101
	global_load_dwordx4 v[112:115], v207, s[12:13]
	s_waitcnt vmcnt(15)
; #define P4_FOR16(M) M(0) M(1) M(2) M(3) M(4) M(5) M(6) M(7) M(8) M(9) M(10) M(11) M(12) M(13) M(14) M(15)
; #define P4_U(i) { P4_DOT(b##i, part[i]); const int nk_ = __builtin_amdgcn_readlane(ksel, nb + i); P4_LOAD(b##i, Ug, nk_); }
; #define P4_U(i) { P4_DOT(b##i, part[i]); const int nk_ = __builtin_amdgcn_readlane(kn, i); P4_LOAD(b##i, nbase, nk_); }
; __device__ __forceinline__ void peer_gather_f4p(const float* X, const int* __restrict__ IDX, const float* __restrict__ G, ...
;     ...
; #pragma unroll 1
;         for (int bt = 0; bt < 7; ++bt) {
;             const int ksel = (bt + 1 < 4) ? k0 : k1;
;             const int nb = (16 * (bt + 1)) & 63;
;     ...
;             P4_FOR16(P4_U)
;     ...
;             P4_RED(bt);
;         }
	v_cvt_scalef32_pk_bf16_fp4 v58, v116, 1.0
	v_mov_b32_e32 v102, 0
	v_cvt_scalef32_pk_bf16_fp4 v60, v116, 1.0 op_sel:[1,0,0]
	v_cvt_scalef32_pk_bf16_fp4 v62, v116, 1.0 op_sel:[0,1,0]
	v_cvt_scalef32_pk_bf16_fp4 v100, v116, 1.0 op_sel:[1,1,0]
	v_dot2c_f32_bf16_e32 v102, v58, v6
	v_mov_b32_e32 v58, 0
	v_dot2c_f32_bf16_e32 v58, v60, v4
	v_dot2c_f32_bf16_e32 v102, v62, v10
	s_add_i32 s12, s28, -3
	v_dot2c_f32_bf16_e32 v58, v100, v8
	v_cvt_scalef32_pk_bf16_fp4 v60, v117, 1.0
	v_cvt_scalef32_pk_bf16_fp4 v62, v117, 1.0 op_sel:[1,0,0]
	v_cvt_scalef32_pk_bf16_fp4 v100, v117, 1.0 op_sel:[0,1,0]
	v_cvt_scalef32_pk_bf16_fp4 v116, v117, 1.0 op_sel:[1,1,0]
	v_readlane_b32 s12, v46, s12
	v_dot2c_f32_bf16_e32 v102, v60, v14
	v_dot2c_f32_bf16_e32 v58, v62, v12
	s_lshr_b32 s12, s12, 7
	v_dot2c_f32_bf16_e32 v102, v100, v18
	v_dot2c_f32_bf16_e32 v58, v116, v16
	v_cvt_scalef32_pk_bf16_fp4 v60, v118, 1.0
	v_cvt_scalef32_pk_bf16_fp4 v62, v118, 1.0 op_sel:[1,0,0]
	v_cvt_scalef32_pk_bf16_fp4 v100, v118, 1.0 op_sel:[0,1,0]
	v_cvt_scalef32_pk_bf16_fp4 v116, v118, 1.0 op_sel:[1,1,0]
	s_mov_b32 s13, s86
	v_dot2c_f32_bf16_e32 v102, v60, v22
	v_dot2c_f32_bf16_e32 v58, v62, v20
	s_lshl_b64 s[12:13], s[12:13], 10
	v_dot2c_f32_bf16_e32 v102, v100, v26
	v_dot2c_f32_bf16_e32 v58, v116, v24
	v_cvt_scalef32_pk_bf16_fp4 v60, v119, 1.0
	v_cvt_scalef32_pk_bf16_fp4 v62, v119, 1.0 op_sel:[1,0,0]
	v_cvt_scalef32_pk_bf16_fp4 v100, v119, 1.0 op_sel:[0,1,0]
	v_cvt_scalef32_pk_bf16_fp4 v116, v119, 1.0 op_sel:[1,1,0]
	s_nop 0
	v_dot2c_f32_bf16_e32 v102, v60, v30
	v_dot2c_f32_bf16_e32 v58, v62, v28
	s_nop 0
	v_dot2c_f32_bf16_e32 v102, v100, v36
	v_dot2c_f32_bf16_e32 v58, v116, v34
	s_nop 0
	s_nop 2
	v_add_f32_e32 v133, v102, v58
	s_add_u32 s12, s12, s100
	s_addc_u32 s13, s13, s101
	global_load_dwordx4 v[116:119], v207, s[12:13]
	s_waitcnt vmcnt(15)
	v_cvt_scalef32_pk_bf16_fp4 v58, v120, 1.0
	v_mov_b32_e32 v102, 0
	v_cvt_scalef32_pk_bf16_fp4 v60, v120, 1.0 op_sel:[1,0,0]
	v_cvt_scalef32_pk_bf16_fp4 v62, v120, 1.0 op_sel:[0,1,0]
	v_cvt_scalef32_pk_bf16_fp4 v100, v120, 1.0 op_sel:[1,1,0]
	v_dot2c_f32_bf16_e32 v102, v58, v6
	v_mov_b32_e32 v58, 0
	v_dot2c_f32_bf16_e32 v58, v60, v4
	v_dot2c_f32_bf16_e32 v102, v62, v10
	s_add_i32 s12, s28, -2
	v_dot2c_f32_bf16_e32 v58, v100, v8
	v_cvt_scalef32_pk_bf16_fp4 v60, v121, 1.0
	v_cvt_scalef32_pk_bf16_fp4 v62, v121, 1.0 op_sel:[1,0,0]
	v_cvt_scalef32_pk_bf16_fp4 v100, v121, 1.0 op_sel:[0,1,0]
	v_cvt_scalef32_pk_bf16_fp4 v120, v121, 1.0 op_sel:[1,1,0]
	v_readlane_b32 s12, v46, s12
	v_dot2c_f32_bf16_e32 v102, v60, v14
	v_dot2c_f32_bf16_e32 v58, v62, v12
	s_lshr_b32 s12, s12, 7
	v_dot2c_f32_bf16_e32 v102, v100, v18
	v_dot2c_f32_bf16_e32 v58, v120, v16
	v_cvt_scalef32_pk_bf16_fp4 v60, v122, 1.0
	v_cvt_scalef32_pk_bf16_fp4 v62, v122, 1.0 op_sel:[1,0,0]
	v_cvt_scalef32_pk_bf16_fp4 v100, v122, 1.0 op_sel:[0,1,0]
	v_cvt_scalef32_pk_bf16_fp4 v120, v122, 1.0 op_sel:[1,1,0]
	s_mov_b32 s13, s86
	v_dot2c_f32_bf16_e32 v102, v60, v22
	v_dot2c_f32_bf16_e32 v58, v62, v20
	s_lshl_b64 s[12:13], s[12:13], 10
	v_dot2c_f32_bf16_e32 v102, v100, v26
	v_dot2c_f32_bf16_e32 v58, v120, v24
	v_cvt_scalef32_pk_bf16_fp4 v60, v123, 1.0
	v_cvt_scalef32_pk_bf16_fp4 v62, v123, 1.0 op_sel:[1,0,0]
	v_cvt_scalef32_pk_bf16_fp4 v100, v123, 1.0 op_sel:[0,1,0]
	v_cvt_scalef32_pk_bf16_fp4 v120, v123, 1.0 op_sel:[1,1,0]
	s_nop 0
	v_dot2c_f32_bf16_e32 v102, v60, v30
	v_dot2c_f32_bf16_e32 v58, v62, v28
	s_nop 0
	v_dot2c_f32_bf16_e32 v102, v100, v36
	v_dot2c_f32_bf16_e32 v58, v120, v34
	s_nop 0
	s_nop 2
	v_add_f32_e32 v134, v102, v58
	s_add_u32 s12, s12, s100
	s_addc_u32 s13, s13, s101
	global_load_dwordx4 v[120:123], v207, s[12:13]
	s_waitcnt vmcnt(15)
	v_cvt_scalef32_pk_bf16_fp4 v58, v124, 1.0
	v_mov_b32_e32 v102, 0
	v_cvt_scalef32_pk_bf16_fp4 v60, v124, 1.0 op_sel:[1,0,0]
	v_cvt_scalef32_pk_bf16_fp4 v62, v124, 1.0 op_sel:[0,1,0]
	v_cvt_scalef32_pk_bf16_fp4 v100, v124, 1.0 op_sel:[1,1,0]
	v_dot2c_f32_bf16_e32 v102, v58, v6
	v_mov_b32_e32 v58, 0
	v_dot2c_f32_bf16_e32 v58, v60, v4
	v_dot2c_f32_bf16_e32 v102, v62, v10
	s_add_i32 s12, s28, -1
	v_dot2c_f32_bf16_e32 v58, v100, v8
	v_cvt_scalef32_pk_bf16_fp4 v60, v125, 1.0
	v_cvt_scalef32_pk_bf16_fp4 v62, v125, 1.0 op_sel:[1,0,0]
	v_cvt_scalef32_pk_bf16_fp4 v100, v125, 1.0 op_sel:[0,1,0]
	v_cvt_scalef32_pk_bf16_fp4 v124, v125, 1.0 op_sel:[1,1,0]
	v_readlane_b32 s12, v46, s12
	v_dot2c_f32_bf16_e32 v102, v60, v14
	v_dot2c_f32_bf16_e32 v58, v62, v12
	s_lshr_b32 s12, s12, 7
	v_dot2c_f32_bf16_e32 v102, v100, v18
	v_dot2c_f32_bf16_e32 v58, v124, v16
	v_cvt_scalef32_pk_bf16_fp4 v60, v126, 1.0
	v_cvt_scalef32_pk_bf16_fp4 v62, v126, 1.0 op_sel:[1,0,0]
	v_cvt_scalef32_pk_bf16_fp4 v100, v126, 1.0 op_sel:[0,1,0]
	v_cvt_scalef32_pk_bf16_fp4 v124, v126, 1.0 op_sel:[1,1,0]
	s_mov_b32 s13, s86
	v_dot2c_f32_bf16_e32 v102, v60, v22
	v_dot2c_f32_bf16_e32 v58, v62, v20
	s_lshl_b64 s[12:13], s[12:13], 10
	v_dot2c_f32_bf16_e32 v102, v100, v26
	v_dot2c_f32_bf16_e32 v58, v124, v24
	v_cvt_scalef32_pk_bf16_fp4 v60, v127, 1.0
	v_cvt_scalef32_pk_bf16_fp4 v62, v127, 1.0 op_sel:[1,0,0]
	v_cvt_scalef32_pk_bf16_fp4 v100, v127, 1.0 op_sel:[0,1,0]
	v_cvt_scalef32_pk_bf16_fp4 v124, v127, 1.0 op_sel:[1,1,0]
	s_nop 0
	v_dot2c_f32_bf16_e32 v102, v60, v30
	v_dot2c_f32_bf16_e32 v58, v62, v28
	s_nop 0
	v_dot2c_f32_bf16_e32 v102, v100, v36
	v_dot2c_f32_bf16_e32 v58, v124, v34
	s_nop 0
	s_nop 2
	v_add_f32_e32 v135, v102, v58
	v_lshl_add_u64 v[58:59], v[40:41], 0, s[12:13]
	v_mov_b32_e32 v102, 0
	global_load_dwordx4 v[124:127], v[58:59], off
	s_waitcnt vmcnt(15)
	v_cvt_scalef32_pk_bf16_fp4 v58, v128, 1.0
	v_cvt_scalef32_pk_bf16_fp4 v60, v128, 1.0 op_sel:[1,0,0]
	v_cvt_scalef32_pk_bf16_fp4 v62, v128, 1.0 op_sel:[0,1,0]
	v_cvt_scalef32_pk_bf16_fp4 v100, v128, 1.0 op_sel:[1,1,0]
	v_readlane_b32 s12, v46, s28
	v_dot2c_f32_bf16_e32 v102, v58, v6
	v_dot2c_f32_bf16_e32 v42, v60, v4
	s_lshr_b32 s12, s12, 7
	v_dot2c_f32_bf16_e32 v102, v62, v10
	v_dot2c_f32_bf16_e32 v42, v100, v8
	v_cvt_scalef32_pk_bf16_fp4 v58, v129, 1.0
	v_cvt_scalef32_pk_bf16_fp4 v60, v129, 1.0 op_sel:[1,0,0]
	v_cvt_scalef32_pk_bf16_fp4 v62, v129, 1.0 op_sel:[0,1,0]
	v_cvt_scalef32_pk_bf16_fp4 v100, v129, 1.0 op_sel:[1,1,0]
	s_mov_b32 s13, s86
	v_dot2c_f32_bf16_e32 v102, v58, v14
	v_dot2c_f32_bf16_e32 v42, v60, v12
	s_lshl_b64 s[12:13], s[12:13], 10
	v_dot2c_f32_bf16_e32 v102, v62, v18
	v_dot2c_f32_bf16_e32 v42, v100, v16
	v_cvt_scalef32_pk_bf16_fp4 v58, v130, 1.0
	v_cvt_scalef32_pk_bf16_fp4 v60, v130, 1.0 op_sel:[1,0,0]
	v_cvt_scalef32_pk_bf16_fp4 v62, v130, 1.0 op_sel:[0,1,0]
	v_cvt_scalef32_pk_bf16_fp4 v100, v130, 1.0 op_sel:[1,1,0]
	v_cndmask_b32_e64 v46, v48, v56, s[48:49]
	v_dot2c_f32_bf16_e32 v102, v58, v22
	v_dot2c_f32_bf16_e32 v42, v60, v20
	ds_swizzle_b32 v46, v46 offset:swizzle(SWAP,8)
	v_dot2c_f32_bf16_e32 v102, v62, v26
	v_dot2c_f32_bf16_e32 v42, v100, v24
	v_cvt_scalef32_pk_bf16_fp4 v58, v131, 1.0
	v_cvt_scalef32_pk_bf16_fp4 v60, v131, 1.0 op_sel:[1,0,0]
	v_cvt_scalef32_pk_bf16_fp4 v62, v131, 1.0 op_sel:[0,1,0]
	v_cvt_scalef32_pk_bf16_fp4 v100, v131, 1.0 op_sel:[1,1,0]
	s_nop 0
	v_dot2c_f32_bf16_e32 v102, v58, v30
	v_dot2c_f32_bf16_e32 v42, v60, v28
	s_nop 0
	v_dot2c_f32_bf16_e32 v102, v62, v36
	v_dot2c_f32_bf16_e32 v42, v100, v34
	s_nop 0
	s_nop 2
	v_add_f32_e32 v58, v102, v42
	v_lshl_add_u64 v[42:43], v[40:41], 0, s[12:13]
	global_load_dwordx4 v[128:131], v[42:43], off
	v_cndmask_b32_e64 v43, v47, v55, s[48:49]
	ds_swizzle_b32 v43, v43 offset:swizzle(SWAP,8)
	v_cndmask_b32_e64 v42, v55, v47, s[48:49]
	v_cndmask_b32_e64 v47, v49, v57, s[48:49]
	ds_swizzle_b32 v47, v47 offset:swizzle(SWAP,8)
	s_waitcnt lgkmcnt(1)
	v_add_f32_e32 v42, v42, v43
	v_cndmask_b32_e64 v43, v56, v48, s[48:49]
	v_cndmask_b32_e64 v48, v50, v132, s[48:49]
	v_add_f32_e32 v43, v43, v46
	v_cndmask_b32_e64 v46, v57, v49, s[48:49]
	ds_swizzle_b32 v48, v48 offset:swizzle(SWAP,8)
	v_cndmask_b32_e64 v49, v51, v133, s[48:49]
	ds_swizzle_b32 v49, v49 offset:swizzle(SWAP,8)
	s_waitcnt lgkmcnt(2)
	v_add_f32_e32 v46, v46, v47
	v_cndmask_b32_e64 v47, v132, v50, s[48:49]
	v_cndmask_b32_e64 v50, v52, v134, s[48:49]
	ds_swizzle_b32 v50, v50 offset:swizzle(SWAP,8)
	s_waitcnt lgkmcnt(2)
	v_add_f32_e32 v47, v47, v48
	v_cndmask_b32_e64 v48, v133, v51, s[48:49]
	v_cndmask_b32_e64 v51, v53, v135, s[48:49]
	s_waitcnt lgkmcnt(1)
	v_add_f32_e32 v48, v48, v49
	v_cndmask_b32_e64 v49, v134, v52, s[48:49]
	ds_swizzle_b32 v51, v51 offset:swizzle(SWAP,8)
	v_cndmask_b32_e64 v52, v54, v58, s[48:49]
	ds_swizzle_b32 v52, v52 offset:swizzle(SWAP,8)
	s_waitcnt lgkmcnt(2)
	v_add_f32_e32 v49, v49, v50
	v_cndmask_b32_e64 v50, v135, v53, s[48:49]
	s_waitcnt lgkmcnt(1)
	v_add_f32_e32 v50, v50, v51
	v_cndmask_b32_e64 v51, v58, v54, s[48:49]
	s_waitcnt lgkmcnt(0)
	v_add_f32_e32 v51, v51, v52
	v_cndmask_b32_e64 v53, v42, v48, s[46:47]
	v_cndmask_b32_e64 v42, v48, v42, s[46:47]
	v_cndmask_b32_e64 v48, v49, v43, s[46:47]
	v_cndmask_b32_e64 v43, v43, v49, s[46:47]
	v_cndmask_b32_e64 v49, v46, v50, s[46:47]
	v_cndmask_b32_e64 v52, v47, v51, s[46:47]
	ds_swizzle_b32 v53, v53 offset:swizzle(SWAP,4)
	ds_swizzle_b32 v43, v43 offset:swizzle(SWAP,4)
	ds_swizzle_b32 v49, v49 offset:swizzle(SWAP,4)
	ds_swizzle_b32 v52, v52 offset:swizzle(SWAP,4)
	v_cndmask_b32_e64 v46, v50, v46, s[46:47]
	v_cndmask_b32_e64 v47, v51, v47, s[46:47]
	s_waitcnt lgkmcnt(3)
	v_add_f32_e32 v42, v42, v53
	s_waitcnt lgkmcnt(2)
	v_add_f32_e32 v43, v48, v43
	s_waitcnt lgkmcnt(1)
	v_add_f32_e32 v46, v46, v49
	s_waitcnt lgkmcnt(0)
	v_add_f32_e32 v47, v47, v52
	v_cndmask_b32_e64 v48, v42, v46, s[44:45]
	v_cndmask_b32_e64 v49, v43, v47, s[44:45]
	ds_swizzle_b32 v48, v48 offset:swizzle(SWAP,2)
	ds_swizzle_b32 v49, v49 offset:swizzle(SWAP,2)
	v_cndmask_b32_e64 v42, v46, v42, s[44:45]
	v_cndmask_b32_e64 v43, v47, v43, s[44:45]
	s_waitcnt lgkmcnt(1)
	v_add_f32_e32 v42, v42, v48
	s_waitcnt lgkmcnt(0)
	v_add_f32_e32 v43, v43, v49
	v_cndmask_b32_e64 v46, v42, v43, s[42:43]
	ds_swizzle_b32 v46, v46 offset:swizzle(SWAP,1)
	v_cndmask_b32_e64 v42, v43, v42, s[42:43]
	s_waitcnt lgkmcnt(0)
	v_add_f32_e32 v42, v42, v46
	ds_swizzle_b32 v43, v42 offset:swizzle(SWAP,16)
	s_waitcnt lgkmcnt(0)
	v_add_f32_e32 v46, v42, v43
	ds_read2st64_b32 v[42:43], v45 offset1:8
	v_mov_b32_e32 v47, v46
	s_nop 1
	v_permlane32_swap_b32_e32 v46, v47
	v_add_f32_e32 v46, v46, v47
	s_waitcnt lgkmcnt(0)
	v_mul_f32_e32 v42, v42, v46
	v_mul_f32_e32 v46, 0x3d372713, v42
	v_mul_f32_e32 v46, v42, v46
	v_fma_f32 v46, v42, v46, v42
	v_mul_f32_e32 v46, 0x3f4c422a, v46
	v_cmp_nlt_f32_e64 s[12:13], |v46|, s25
	s_and_saveexec_b64 s[40:41], s[12:13]
	s_xor_b64 s[12:13], exec, s[40:41]
	s_cbranch_execz .LBB0_536
	v_add_f32_e64 v47, |v46|, |v46|
	v_mul_f32_e32 v48, 0x3fb8aa3b, v47
	v_rndne_f32_e32 v49, v48
	v_sub_f32_e32 v50, v48, v49
	v_fma_f32 v48, v47, s70, -v48
	v_fmac_f32_e32 v48, 0x32a5705f, v47
	v_add_f32_e32 v48, v50, v48
	v_cvt_i32_f32_e32 v49, v49
	v_exp_f32_e32 v48, v48
	v_cmp_ngt_f32_e64 s[50:51], s67, v47
	v_ldexp_f32 v48, v48, v49
	s_nop 0
	v_cndmask_b32_e64 v48, 0, v48, s[50:51]
	v_cmp_nlt_f32_e64 s[50:51], s68, v47
	s_nop 1
	v_cndmask_b32_e64 v47, v205, v48, s[50:51]
	v_add_f32_e32 v47, 1.0, v47
	v_rcp_f32_e32 v47, v47
	s_nop 0
	v_fma_f32 v47, v47, -2.0, 1.0
	s_andn2_saveexec_b64 s[12:13], s[12:13]
	s_cbranch_execnz .LBB0_537

; #define P4_FOR16(M) M(0) M(1) M(2) M(3) M(4) M(5) M(6) M(7) M(8) M(9) M(10) M(11) M(12) M(13) M(14) M(15)
; #define P4_U(i) { P4_DOT(b##i, part[i]); const int nk_ = __builtin_amdgcn_readlane(ksel, nb + i); P4_LOAD(b##i, Ug, nk_); }
; #define P4_U(i) { P4_DOT(b##i, part[i]); const int nk_ = __builtin_amdgcn_readlane(kn, i); P4_LOAD(b##i, nbase, nk_); }
; __device__ __forceinline__ void peer_gather_f4p(const float* X, const int* __restrict__ IDX, const float* __restrict__ G, ...
;     ...
;         {
;     ...
;             P4_FOR16(P4_U)
.LBB0_539:
	s_mov_b32 s87, s86
	s_waitcnt vmcnt(15)
	v_cvt_scalef32_pk_bf16_fp4 v42, v64, 1.0
	v_mov_b32_e32 v50, 0
	v_or_b32_e32 v40, s27, v44
	v_cvt_scalef32_pk_bf16_fp4 v44, v64, 1.0 op_sel:[1,0,0]
	v_cvt_scalef32_pk_bf16_fp4 v46, v64, 1.0 op_sel:[0,1,0]
	v_cvt_scalef32_pk_bf16_fp4 v48, v64, 1.0 op_sel:[1,1,0]
	v_dot2c_f32_bf16_e32 v50, v42, v6
	v_mov_b32_e32 v42, 0
	v_dot2c_f32_bf16_e32 v42, v44, v4
	v_dot2c_f32_bf16_e32 v50, v46, v10
	s_cmp_eq_u32 s26, 3
	v_dot2c_f32_bf16_e32 v42, v48, v8
	v_cvt_scalef32_pk_bf16_fp4 v44, v65, 1.0
	v_cvt_scalef32_pk_bf16_fp4 v46, v65, 1.0 op_sel:[1,0,0]
	v_cvt_scalef32_pk_bf16_fp4 v48, v65, 1.0 op_sel:[0,1,0]
	v_cvt_scalef32_pk_bf16_fp4 v52, v65, 1.0 op_sel:[1,1,0]
	v_readlane_b32 s26, v2, 0
	v_dot2c_f32_bf16_e32 v50, v44, v14
	v_dot2c_f32_bf16_e32 v42, v46, v12
	s_cselect_b32 s12, s53, s55
	v_dot2c_f32_bf16_e32 v50, v48, v18
	v_dot2c_f32_bf16_e32 v42, v52, v16
	v_cvt_scalef32_pk_bf16_fp4 v44, v66, 1.0
	v_cvt_scalef32_pk_bf16_fp4 v46, v66, 1.0 op_sel:[1,0,0]
	v_cvt_scalef32_pk_bf16_fp4 v48, v66, 1.0 op_sel:[0,1,0]
	v_cvt_scalef32_pk_bf16_fp4 v52, v66, 1.0 op_sel:[1,1,0]
	s_cselect_b32 s13, s52, s54
	v_dot2c_f32_bf16_e32 v50, v44, v22
	v_dot2c_f32_bf16_e32 v42, v46, v20
	s_lshr_b32 s26, s26, 7
	v_dot2c_f32_bf16_e32 v50, v48, v26
	v_dot2c_f32_bf16_e32 v42, v52, v24
	s_mov_b32 s27, s86
	v_cvt_scalef32_pk_bf16_fp4 v44, v67, 1.0
	v_cvt_scalef32_pk_bf16_fp4 v46, v67, 1.0 op_sel:[1,0,0]
	v_cvt_scalef32_pk_bf16_fp4 v48, v67, 1.0 op_sel:[0,1,0]
	v_cvt_scalef32_pk_bf16_fp4 v52, v67, 1.0 op_sel:[1,1,0]
	s_lshl_b64 s[26:27], s[26:27], 10
	v_dot2c_f32_bf16_e32 v50, v44, v30
	v_dot2c_f32_bf16_e32 v42, v46, v28
	s_add_u32 s26, s13, s26
	v_dot2c_f32_bf16_e32 v50, v48, v36
	v_dot2c_f32_bf16_e32 v42, v52, v34
	s_addc_u32 s27, s12, s27
	s_nop 2
	v_add_f32_e32 v41, v50, v42
	global_load_dwordx4 v[64:67], v32, s[26:27]
	s_waitcnt vmcnt(15)
	v_cvt_scalef32_pk_bf16_fp4 v42, v68, 1.0
	v_mov_b32_e32 v50, 0
	v_cvt_scalef32_pk_bf16_fp4 v44, v68, 1.0 op_sel:[1,0,0]
	v_cvt_scalef32_pk_bf16_fp4 v46, v68, 1.0 op_sel:[0,1,0]
	v_cvt_scalef32_pk_bf16_fp4 v48, v68, 1.0 op_sel:[1,1,0]
	v_dot2c_f32_bf16_e32 v50, v42, v6
	v_mov_b32_e32 v42, 0
	v_dot2c_f32_bf16_e32 v42, v44, v4
	v_dot2c_f32_bf16_e32 v50, v46, v10
	v_readlane_b32 s26, v2, 1
	v_dot2c_f32_bf16_e32 v42, v48, v8
	v_cvt_scalef32_pk_bf16_fp4 v44, v69, 1.0
	v_cvt_scalef32_pk_bf16_fp4 v46, v69, 1.0 op_sel:[1,0,0]
	v_cvt_scalef32_pk_bf16_fp4 v48, v69, 1.0 op_sel:[0,1,0]
	v_cvt_scalef32_pk_bf16_fp4 v52, v69, 1.0 op_sel:[1,1,0]
	s_lshr_b32 s26, s26, 7
	v_dot2c_f32_bf16_e32 v50, v44, v14
	v_dot2c_f32_bf16_e32 v42, v46, v12
	s_mov_b32 s27, s86
	v_dot2c_f32_bf16_e32 v50, v48, v18
	v_dot2c_f32_bf16_e32 v42, v52, v16
	v_cvt_scalef32_pk_bf16_fp4 v44, v70, 1.0
	v_cvt_scalef32_pk_bf16_fp4 v46, v70, 1.0 op_sel:[1,0,0]
	v_cvt_scalef32_pk_bf16_fp4 v48, v70, 1.0 op_sel:[0,1,0]
	v_cvt_scalef32_pk_bf16_fp4 v52, v70, 1.0 op_sel:[1,1,0]
	s_lshl_b64 s[26:27], s[26:27], 10
	v_dot2c_f32_bf16_e32 v50, v44, v22
	v_dot2c_f32_bf16_e32 v42, v46, v20
	s_add_u32 s26, s13, s26
	v_dot2c_f32_bf16_e32 v50, v48, v26
	v_dot2c_f32_bf16_e32 v42, v52, v24
	v_cvt_scalef32_pk_bf16_fp4 v44, v71, 1.0
	v_cvt_scalef32_pk_bf16_fp4 v46, v71, 1.0 op_sel:[1,0,0]
	v_cvt_scalef32_pk_bf16_fp4 v48, v71, 1.0 op_sel:[0,1,0]
	v_cvt_scalef32_pk_bf16_fp4 v52, v71, 1.0 op_sel:[1,1,0]
	s_addc_u32 s27, s12, s27
	v_dot2c_f32_bf16_e32 v50, v44, v30
	v_dot2c_f32_bf16_e32 v42, v46, v28
	v_mov_b32_e32 v38, 0
	v_dot2c_f32_bf16_e32 v50, v48, v36
	v_dot2c_f32_bf16_e32 v42, v52, v34
	v_mov_b32_e32 v52, 0
	s_nop 2
	v_add_f32_e32 v42, v50, v42
	global_load_dwordx4 v[68:71], v32, s[26:27]
	s_waitcnt vmcnt(15)
	v_cvt_scalef32_pk_bf16_fp4 v44, v72, 1.0
	v_cvt_scalef32_pk_bf16_fp4 v46, v72, 1.0 op_sel:[1,0,0]
	v_cvt_scalef32_pk_bf16_fp4 v48, v72, 1.0 op_sel:[0,1,0]
	v_cvt_scalef32_pk_bf16_fp4 v50, v72, 1.0 op_sel:[1,1,0]
	v_readlane_b32 s26, v2, 2
	v_dot2c_f32_bf16_e32 v52, v44, v6
	v_mov_b32_e32 v44, 0
	v_dot2c_f32_bf16_e32 v44, v46, v4
	v_dot2c_f32_bf16_e32 v52, v48, v10
	s_lshr_b32 s26, s26, 7
	v_dot2c_f32_bf16_e32 v44, v50, v8
	v_cvt_scalef32_pk_bf16_fp4 v46, v73, 1.0
	v_cvt_scalef32_pk_bf16_fp4 v48, v73, 1.0 op_sel:[1,0,0]
	v_cvt_scalef32_pk_bf16_fp4 v50, v73, 1.0 op_sel:[0,1,0]
	v_cvt_scalef32_pk_bf16_fp4 v54, v73, 1.0 op_sel:[1,1,0]
	s_mov_b32 s27, s86
	v_dot2c_f32_bf16_e32 v52, v46, v14
	v_dot2c_f32_bf16_e32 v44, v48, v12
	s_lshl_b64 s[26:27], s[26:27], 10
	v_dot2c_f32_bf16_e32 v52, v50, v18
	v_dot2c_f32_bf16_e32 v44, v54, v16
	v_cvt_scalef32_pk_bf16_fp4 v46, v74, 1.0
	v_cvt_scalef32_pk_bf16_fp4 v48, v74, 1.0 op_sel:[1,0,0]
	v_cvt_scalef32_pk_bf16_fp4 v50, v74, 1.0 op_sel:[0,1,0]
	v_cvt_scalef32_pk_bf16_fp4 v54, v74, 1.0 op_sel:[1,1,0]
	s_add_u32 s26, s13, s26
	v_dot2c_f32_bf16_e32 v52, v46, v22
	v_dot2c_f32_bf16_e32 v44, v48, v20
	s_addc_u32 s27, s12, s27
	v_dot2c_f32_bf16_e32 v52, v50, v26
	v_dot2c_f32_bf16_e32 v44, v54, v24
	v_cvt_scalef32_pk_bf16_fp4 v46, v75, 1.0
	v_cvt_scalef32_pk_bf16_fp4 v48, v75, 1.0 op_sel:[1,0,0]
	v_cvt_scalef32_pk_bf16_fp4 v50, v75, 1.0 op_sel:[0,1,0]
	v_cvt_scalef32_pk_bf16_fp4 v54, v75, 1.0 op_sel:[1,1,0]
	s_nop 0
	v_dot2c_f32_bf16_e32 v52, v46, v30
	v_dot2c_f32_bf16_e32 v44, v48, v28
	s_nop 0
	v_dot2c_f32_bf16_e32 v52, v50, v36
	v_dot2c_f32_bf16_e32 v44, v54, v34
	s_nop 0
	s_nop 2
	v_add_f32_e32 v43, v52, v44
	global_load_dwordx4 v[72:75], v32, s[26:27]
	s_waitcnt vmcnt(15)
; #define P4_FOR16(M) M(0) M(1) M(2) M(3) M(4) M(5) M(6) M(7) M(8) M(9) M(10) M(11) M(12) M(13) M(14) M(15)
; #define P4_U(i) { P4_DOT(b##i, part[i]); const int nk_ = __builtin_amdgcn_readlane(ksel, nb + i); P4_LOAD(b##i, Ug, nk_); }
; #define P4_U(i) { P4_DOT(b##i, part[i]); const int nk_ = __builtin_amdgcn_readlane(kn, i); P4_LOAD(b##i, nbase, nk_); }
; __device__ __forceinline__ void peer_gather_f4p(const float* X, const int* __restrict__ IDX, const float* __restrict__ G, ...
;     ...
;         {
;     ...
;             P4_FOR16(P4_U)
	v_cvt_scalef32_pk_bf16_fp4 v44, v76, 1.0
	v_mov_b32_e32 v52, 0
	v_cvt_scalef32_pk_bf16_fp4 v46, v76, 1.0 op_sel:[1,0,0]
	v_cvt_scalef32_pk_bf16_fp4 v48, v76, 1.0 op_sel:[0,1,0]
	v_cvt_scalef32_pk_bf16_fp4 v50, v76, 1.0 op_sel:[1,1,0]
	v_dot2c_f32_bf16_e32 v52, v44, v6
	v_mov_b32_e32 v44, 0
	v_dot2c_f32_bf16_e32 v44, v46, v4
	v_dot2c_f32_bf16_e32 v52, v48, v10
	v_readlane_b32 s26, v2, 3
	v_dot2c_f32_bf16_e32 v44, v50, v8
	v_cvt_scalef32_pk_bf16_fp4 v46, v77, 1.0
	v_cvt_scalef32_pk_bf16_fp4 v48, v77, 1.0 op_sel:[1,0,0]
	v_cvt_scalef32_pk_bf16_fp4 v50, v77, 1.0 op_sel:[0,1,0]
	v_cvt_scalef32_pk_bf16_fp4 v54, v77, 1.0 op_sel:[1,1,0]
	s_lshr_b32 s26, s26, 7
	v_dot2c_f32_bf16_e32 v52, v46, v14
	v_dot2c_f32_bf16_e32 v44, v48, v12
	s_mov_b32 s27, s86
	v_dot2c_f32_bf16_e32 v52, v50, v18
	v_dot2c_f32_bf16_e32 v44, v54, v16
	v_cvt_scalef32_pk_bf16_fp4 v46, v78, 1.0
	v_cvt_scalef32_pk_bf16_fp4 v48, v78, 1.0 op_sel:[1,0,0]
	v_cvt_scalef32_pk_bf16_fp4 v50, v78, 1.0 op_sel:[0,1,0]
	v_cvt_scalef32_pk_bf16_fp4 v54, v78, 1.0 op_sel:[1,1,0]
	s_lshl_b64 s[26:27], s[26:27], 10
	v_dot2c_f32_bf16_e32 v52, v46, v22
	v_dot2c_f32_bf16_e32 v44, v48, v20
	s_add_u32 s26, s13, s26
	v_dot2c_f32_bf16_e32 v52, v50, v26
	v_dot2c_f32_bf16_e32 v44, v54, v24
	v_cvt_scalef32_pk_bf16_fp4 v46, v79, 1.0
	v_cvt_scalef32_pk_bf16_fp4 v48, v79, 1.0 op_sel:[1,0,0]
	v_cvt_scalef32_pk_bf16_fp4 v50, v79, 1.0 op_sel:[0,1,0]
	v_cvt_scalef32_pk_bf16_fp4 v54, v79, 1.0 op_sel:[1,1,0]
	s_addc_u32 s27, s12, s27
	v_dot2c_f32_bf16_e32 v52, v46, v30
	v_dot2c_f32_bf16_e32 v44, v48, v28
	s_nop 0
	v_dot2c_f32_bf16_e32 v52, v50, v36
	v_dot2c_f32_bf16_e32 v44, v54, v34
	v_mov_b32_e32 v54, 0
	s_nop 2
	v_add_f32_e32 v44, v52, v44
	global_load_dwordx4 v[76:79], v32, s[26:27]
	s_waitcnt vmcnt(15)
	v_cvt_scalef32_pk_bf16_fp4 v46, v80, 1.0
	v_cvt_scalef32_pk_bf16_fp4 v48, v80, 1.0 op_sel:[1,0,0]
	v_cvt_scalef32_pk_bf16_fp4 v50, v80, 1.0 op_sel:[0,1,0]
	v_cvt_scalef32_pk_bf16_fp4 v52, v80, 1.0 op_sel:[1,1,0]
	v_readlane_b32 s26, v2, 4
	v_dot2c_f32_bf16_e32 v54, v46, v6
	v_mov_b32_e32 v46, 0
	v_dot2c_f32_bf16_e32 v46, v48, v4
	v_dot2c_f32_bf16_e32 v54, v50, v10
	s_lshr_b32 s26, s26, 7
	v_dot2c_f32_bf16_e32 v46, v52, v8
	v_cvt_scalef32_pk_bf16_fp4 v48, v81, 1.0
	v_cvt_scalef32_pk_bf16_fp4 v50, v81, 1.0 op_sel:[1,0,0]
	v_cvt_scalef32_pk_bf16_fp4 v52, v81, 1.0 op_sel:[0,1,0]
	v_cvt_scalef32_pk_bf16_fp4 v56, v81, 1.0 op_sel:[1,1,0]
	s_mov_b32 s27, s86
	v_dot2c_f32_bf16_e32 v54, v48, v14
	v_dot2c_f32_bf16_e32 v46, v50, v12
	s_lshl_b64 s[26:27], s[26:27], 10
	v_dot2c_f32_bf16_e32 v54, v52, v18
	v_dot2c_f32_bf16_e32 v46, v56, v16
	v_cvt_scalef32_pk_bf16_fp4 v48, v82, 1.0
	v_cvt_scalef32_pk_bf16_fp4 v50, v82, 1.0 op_sel:[1,0,0]
	v_cvt_scalef32_pk_bf16_fp4 v52, v82, 1.0 op_sel:[0,1,0]
	v_cvt_scalef32_pk_bf16_fp4 v56, v82, 1.0 op_sel:[1,1,0]
	s_add_u32 s26, s13, s26
	v_dot2c_f32_bf16_e32 v54, v48, v22
	v_dot2c_f32_bf16_e32 v46, v50, v20
	s_addc_u32 s27, s12, s27
	v_dot2c_f32_bf16_e32 v54, v52, v26
	v_dot2c_f32_bf16_e32 v46, v56, v24
	v_cvt_scalef32_pk_bf16_fp4 v48, v83, 1.0
	v_cvt_scalef32_pk_bf16_fp4 v50, v83, 1.0 op_sel:[1,0,0]
	v_cvt_scalef32_pk_bf16_fp4 v52, v83, 1.0 op_sel:[0,1,0]
	v_cvt_scalef32_pk_bf16_fp4 v56, v83, 1.0 op_sel:[1,1,0]
	s_nop 0
	v_dot2c_f32_bf16_e32 v54, v48, v30
	v_dot2c_f32_bf16_e32 v46, v50, v28
	s_nop 0
	v_dot2c_f32_bf16_e32 v54, v52, v36
	v_dot2c_f32_bf16_e32 v46, v56, v34
	s_nop 0
	s_nop 2
	v_add_f32_e32 v45, v54, v46
	global_load_dwordx4 v[80:83], v32, s[26:27]
	s_waitcnt vmcnt(15)
	v_cvt_scalef32_pk_bf16_fp4 v46, v84, 1.0
	v_mov_b32_e32 v54, 0
	v_cvt_scalef32_pk_bf16_fp4 v48, v84, 1.0 op_sel:[1,0,0]
	v_cvt_scalef32_pk_bf16_fp4 v50, v84, 1.0 op_sel:[0,1,0]
	v_cvt_scalef32_pk_bf16_fp4 v52, v84, 1.0 op_sel:[1,1,0]
	v_dot2c_f32_bf16_e32 v54, v46, v6
	v_mov_b32_e32 v46, 0
	v_dot2c_f32_bf16_e32 v46, v48, v4
	v_dot2c_f32_bf16_e32 v54, v50, v10
	v_readlane_b32 s26, v2, 5
	v_dot2c_f32_bf16_e32 v46, v52, v8
	v_cvt_scalef32_pk_bf16_fp4 v48, v85, 1.0
	v_cvt_scalef32_pk_bf16_fp4 v50, v85, 1.0 op_sel:[1,0,0]
	v_cvt_scalef32_pk_bf16_fp4 v52, v85, 1.0 op_sel:[0,1,0]
	v_cvt_scalef32_pk_bf16_fp4 v56, v85, 1.0 op_sel:[1,1,0]
	s_lshr_b32 s26, s26, 7
	v_dot2c_f32_bf16_e32 v54, v48, v14
	v_dot2c_f32_bf16_e32 v46, v50, v12
	s_mov_b32 s27, s86
	v_dot2c_f32_bf16_e32 v54, v52, v18
	v_dot2c_f32_bf16_e32 v46, v56, v16
	v_cvt_scalef32_pk_bf16_fp4 v48, v86, 1.0
	v_cvt_scalef32_pk_bf16_fp4 v50, v86, 1.0 op_sel:[1,0,0]
	v_cvt_scalef32_pk_bf16_fp4 v52, v86, 1.0 op_sel:[0,1,0]
	v_cvt_scalef32_pk_bf16_fp4 v56, v86, 1.0 op_sel:[1,1,0]
	s_lshl_b64 s[26:27], s[26:27], 10
	v_dot2c_f32_bf16_e32 v54, v48, v22
	v_dot2c_f32_bf16_e32 v46, v50, v20
	s_add_u32 s26, s13, s26
	v_dot2c_f32_bf16_e32 v54, v52, v26
	v_dot2c_f32_bf16_e32 v46, v56, v24
	v_cvt_scalef32_pk_bf16_fp4 v48, v87, 1.0
	v_cvt_scalef32_pk_bf16_fp4 v50, v87, 1.0 op_sel:[1,0,0]
	v_cvt_scalef32_pk_bf16_fp4 v52, v87, 1.0 op_sel:[0,1,0]
	v_cvt_scalef32_pk_bf16_fp4 v56, v87, 1.0 op_sel:[1,1,0]
	s_addc_u32 s27, s12, s27
	v_dot2c_f32_bf16_e32 v54, v48, v30
	v_dot2c_f32_bf16_e32 v46, v50, v28
	s_nop 0
	v_dot2c_f32_bf16_e32 v54, v52, v36
	v_dot2c_f32_bf16_e32 v46, v56, v34
	v_mov_b32_e32 v56, 0
	s_nop 2
	v_add_f32_e32 v46, v54, v46
	global_load_dwordx4 v[84:87], v32, s[26:27]
	s_waitcnt vmcnt(15)
; #define P4_FOR16(M) M(0) M(1) M(2) M(3) M(4) M(5) M(6) M(7) M(8) M(9) M(10) M(11) M(12) M(13) M(14) M(15)
; #define P4_U(i) { P4_DOT(b##i, part[i]); const int nk_ = __builtin_amdgcn_readlane(ksel, nb + i); P4_LOAD(b##i, Ug, nk_); }
; #define P4_U(i) { P4_DOT(b##i, part[i]); const int nk_ = __builtin_amdgcn_readlane(kn, i); P4_LOAD(b##i, nbase, nk_); }
; __device__ __forceinline__ void peer_gather_f4p(const float* X, const int* __restrict__ IDX, const float* __restrict__ G, ...
;     ...
;         {
;     ...
;             P4_FOR16(P4_U)
	v_cvt_scalef32_pk_bf16_fp4 v48, v88, 1.0
	v_cvt_scalef32_pk_bf16_fp4 v50, v88, 1.0 op_sel:[1,0,0]
	v_cvt_scalef32_pk_bf16_fp4 v52, v88, 1.0 op_sel:[0,1,0]
	v_cvt_scalef32_pk_bf16_fp4 v54, v88, 1.0 op_sel:[1,1,0]
	v_readlane_b32 s26, v2, 6
	v_dot2c_f32_bf16_e32 v56, v48, v6
	v_mov_b32_e32 v48, 0
	v_dot2c_f32_bf16_e32 v48, v50, v4
	v_dot2c_f32_bf16_e32 v56, v52, v10
	s_lshr_b32 s26, s26, 7
	v_dot2c_f32_bf16_e32 v48, v54, v8
	v_cvt_scalef32_pk_bf16_fp4 v50, v89, 1.0
	v_cvt_scalef32_pk_bf16_fp4 v52, v89, 1.0 op_sel:[1,0,0]
	v_cvt_scalef32_pk_bf16_fp4 v54, v89, 1.0 op_sel:[0,1,0]
	v_cvt_scalef32_pk_bf16_fp4 v58, v89, 1.0 op_sel:[1,1,0]
	s_mov_b32 s27, s86
	v_dot2c_f32_bf16_e32 v56, v50, v14
	v_dot2c_f32_bf16_e32 v48, v52, v12
	s_lshl_b64 s[26:27], s[26:27], 10
	v_dot2c_f32_bf16_e32 v56, v54, v18
	v_dot2c_f32_bf16_e32 v48, v58, v16
	v_cvt_scalef32_pk_bf16_fp4 v50, v90, 1.0
	v_cvt_scalef32_pk_bf16_fp4 v52, v90, 1.0 op_sel:[1,0,0]
	v_cvt_scalef32_pk_bf16_fp4 v54, v90, 1.0 op_sel:[0,1,0]
	v_cvt_scalef32_pk_bf16_fp4 v58, v90, 1.0 op_sel:[1,1,0]
	s_add_u32 s26, s13, s26
	v_dot2c_f32_bf16_e32 v56, v50, v22
	v_dot2c_f32_bf16_e32 v48, v52, v20
	s_addc_u32 s27, s12, s27
	v_dot2c_f32_bf16_e32 v56, v54, v26
	v_dot2c_f32_bf16_e32 v48, v58, v24
	v_cvt_scalef32_pk_bf16_fp4 v50, v91, 1.0
	v_cvt_scalef32_pk_bf16_fp4 v52, v91, 1.0 op_sel:[1,0,0]
	v_cvt_scalef32_pk_bf16_fp4 v54, v91, 1.0 op_sel:[0,1,0]
	v_cvt_scalef32_pk_bf16_fp4 v58, v91, 1.0 op_sel:[1,1,0]
	s_nop 0
	v_dot2c_f32_bf16_e32 v56, v50, v30
	v_dot2c_f32_bf16_e32 v48, v52, v28
	s_nop 0
	v_dot2c_f32_bf16_e32 v56, v54, v36
	v_dot2c_f32_bf16_e32 v48, v58, v34
	s_nop 0
	s_nop 2
	v_add_f32_e32 v47, v56, v48
	global_load_dwordx4 v[88:91], v32, s[26:27]
	s_waitcnt vmcnt(15)
	v_cvt_scalef32_pk_bf16_fp4 v48, v92, 1.0
	v_mov_b32_e32 v56, 0
	v_cvt_scalef32_pk_bf16_fp4 v50, v92, 1.0 op_sel:[1,0,0]
	v_cvt_scalef32_pk_bf16_fp4 v52, v92, 1.0 op_sel:[0,1,0]
	v_cvt_scalef32_pk_bf16_fp4 v54, v92, 1.0 op_sel:[1,1,0]
	v_dot2c_f32_bf16_e32 v56, v48, v6
	v_mov_b32_e32 v48, 0
	v_dot2c_f32_bf16_e32 v48, v50, v4
	v_dot2c_f32_bf16_e32 v56, v52, v10
	v_readlane_b32 s26, v2, 7
	v_dot2c_f32_bf16_e32 v48, v54, v8
	v_cvt_scalef32_pk_bf16_fp4 v50, v93, 1.0
	v_cvt_scalef32_pk_bf16_fp4 v52, v93, 1.0 op_sel:[1,0,0]
	v_cvt_scalef32_pk_bf16_fp4 v54, v93, 1.0 op_sel:[0,1,0]
	v_cvt_scalef32_pk_bf16_fp4 v58, v93, 1.0 op_sel:[1,1,0]
	s_lshr_b32 s26, s26, 7
	v_dot2c_f32_bf16_e32 v56, v50, v14
	v_dot2c_f32_bf16_e32 v48, v52, v12
	s_mov_b32 s27, s86
	v_dot2c_f32_bf16_e32 v56, v54, v18
	v_dot2c_f32_bf16_e32 v48, v58, v16
	v_cvt_scalef32_pk_bf16_fp4 v50, v94, 1.0
	v_cvt_scalef32_pk_bf16_fp4 v52, v94, 1.0 op_sel:[1,0,0]
	v_cvt_scalef32_pk_bf16_fp4 v54, v94, 1.0 op_sel:[0,1,0]
	v_cvt_scalef32_pk_bf16_fp4 v58, v94, 1.0 op_sel:[1,1,0]
	s_lshl_b64 s[26:27], s[26:27], 10
	v_dot2c_f32_bf16_e32 v56, v50, v22
	v_dot2c_f32_bf16_e32 v48, v52, v20
	s_add_u32 s26, s13, s26
	v_dot2c_f32_bf16_e32 v56, v54, v26
	v_dot2c_f32_bf16_e32 v48, v58, v24
	v_cvt_scalef32_pk_bf16_fp4 v50, v95, 1.0
	v_cvt_scalef32_pk_bf16_fp4 v52, v95, 1.0 op_sel:[1,0,0]
	v_cvt_scalef32_pk_bf16_fp4 v54, v95, 1.0 op_sel:[0,1,0]
	v_cvt_scalef32_pk_bf16_fp4 v58, v95, 1.0 op_sel:[1,1,0]
	s_addc_u32 s27, s12, s27
	v_dot2c_f32_bf16_e32 v56, v50, v30
	v_dot2c_f32_bf16_e32 v48, v52, v28
	s_nop 0
	v_dot2c_f32_bf16_e32 v56, v54, v36
	v_dot2c_f32_bf16_e32 v48, v58, v34
	v_mov_b32_e32 v58, 0
	s_nop 2
	v_add_f32_e32 v48, v56, v48
	global_load_dwordx4 v[92:95], v32, s[26:27]
	s_waitcnt vmcnt(15)
	v_cvt_scalef32_pk_bf16_fp4 v50, v96, 1.0
	v_cvt_scalef32_pk_bf16_fp4 v52, v96, 1.0 op_sel:[1,0,0]
	v_cvt_scalef32_pk_bf16_fp4 v54, v96, 1.0 op_sel:[0,1,0]
	v_cvt_scalef32_pk_bf16_fp4 v56, v96, 1.0 op_sel:[1,1,0]
	v_readlane_b32 s26, v2, 8
	v_dot2c_f32_bf16_e32 v58, v50, v6
	v_mov_b32_e32 v50, 0
	v_dot2c_f32_bf16_e32 v50, v52, v4
	v_dot2c_f32_bf16_e32 v58, v54, v10
	s_lshr_b32 s26, s26, 7
	v_dot2c_f32_bf16_e32 v50, v56, v8
	v_cvt_scalef32_pk_bf16_fp4 v52, v97, 1.0
	v_cvt_scalef32_pk_bf16_fp4 v54, v97, 1.0 op_sel:[1,0,0]
	v_cvt_scalef32_pk_bf16_fp4 v56, v97, 1.0 op_sel:[0,1,0]
	v_cvt_scalef32_pk_bf16_fp4 v60, v97, 1.0 op_sel:[1,1,0]
	s_mov_b32 s27, s86
	v_dot2c_f32_bf16_e32 v58, v52, v14
	v_dot2c_f32_bf16_e32 v50, v54, v12
	s_lshl_b64 s[26:27], s[26:27], 10
	v_dot2c_f32_bf16_e32 v58, v56, v18
	v_dot2c_f32_bf16_e32 v50, v60, v16
	v_cvt_scalef32_pk_bf16_fp4 v52, v98, 1.0
	v_cvt_scalef32_pk_bf16_fp4 v54, v98, 1.0 op_sel:[1,0,0]
	v_cvt_scalef32_pk_bf16_fp4 v56, v98, 1.0 op_sel:[0,1,0]
	v_cvt_scalef32_pk_bf16_fp4 v60, v98, 1.0 op_sel:[1,1,0]
	s_add_u32 s26, s13, s26
	v_dot2c_f32_bf16_e32 v58, v52, v22
	v_dot2c_f32_bf16_e32 v50, v54, v20
	s_addc_u32 s27, s12, s27
	v_dot2c_f32_bf16_e32 v58, v56, v26
	v_dot2c_f32_bf16_e32 v50, v60, v24
	v_cvt_scalef32_pk_bf16_fp4 v52, v99, 1.0
	v_cvt_scalef32_pk_bf16_fp4 v54, v99, 1.0 op_sel:[1,0,0]
	v_cvt_scalef32_pk_bf16_fp4 v56, v99, 1.0 op_sel:[0,1,0]
	v_cvt_scalef32_pk_bf16_fp4 v60, v99, 1.0 op_sel:[1,1,0]
	s_nop 0
	v_dot2c_f32_bf16_e32 v58, v52, v30
	v_dot2c_f32_bf16_e32 v50, v54, v28
	s_nop 0
	v_dot2c_f32_bf16_e32 v58, v56, v36
	v_dot2c_f32_bf16_e32 v50, v60, v34
	s_nop 0
	s_nop 2
	v_add_f32_e32 v49, v58, v50
	global_load_dwordx4 v[96:99], v32, s[26:27]
	s_waitcnt vmcnt(15)
; #define P4_FOR16(M) M(0) M(1) M(2) M(3) M(4) M(5) M(6) M(7) M(8) M(9) M(10) M(11) M(12) M(13) M(14) M(15)
; #define P4_U(i) { P4_DOT(b##i, part[i]); const int nk_ = __builtin_amdgcn_readlane(ksel, nb + i); P4_LOAD(b##i, Ug, nk_); }
; #define P4_U(i) { P4_DOT(b##i, part[i]); const int nk_ = __builtin_amdgcn_readlane(kn, i); P4_LOAD(b##i, nbase, nk_); }
; __device__ __forceinline__ void peer_gather_f4p(const float* X, const int* __restrict__ IDX, const float* __restrict__ G, ...
;     ...
;         {
;     ...
;             P4_FOR16(P4_U)
	v_cvt_scalef32_pk_bf16_fp4 v50, v104, 1.0
	v_mov_b32_e32 v58, 0
	v_cvt_scalef32_pk_bf16_fp4 v52, v104, 1.0 op_sel:[1,0,0]
	v_cvt_scalef32_pk_bf16_fp4 v54, v104, 1.0 op_sel:[0,1,0]
	v_cvt_scalef32_pk_bf16_fp4 v56, v104, 1.0 op_sel:[1,1,0]
	v_dot2c_f32_bf16_e32 v58, v50, v6
	v_mov_b32_e32 v50, 0
	v_dot2c_f32_bf16_e32 v50, v52, v4
	v_dot2c_f32_bf16_e32 v58, v54, v10
	v_readlane_b32 s26, v2, 9
	v_dot2c_f32_bf16_e32 v50, v56, v8
	v_cvt_scalef32_pk_bf16_fp4 v52, v105, 1.0
	v_cvt_scalef32_pk_bf16_fp4 v54, v105, 1.0 op_sel:[1,0,0]
	v_cvt_scalef32_pk_bf16_fp4 v56, v105, 1.0 op_sel:[0,1,0]
	v_cvt_scalef32_pk_bf16_fp4 v60, v105, 1.0 op_sel:[1,1,0]
	s_lshr_b32 s26, s26, 7
	v_dot2c_f32_bf16_e32 v58, v52, v14
	v_dot2c_f32_bf16_e32 v50, v54, v12
	s_mov_b32 s27, s86
	v_dot2c_f32_bf16_e32 v58, v56, v18
	v_dot2c_f32_bf16_e32 v50, v60, v16
	v_cvt_scalef32_pk_bf16_fp4 v52, v106, 1.0
	v_cvt_scalef32_pk_bf16_fp4 v54, v106, 1.0 op_sel:[1,0,0]
	v_cvt_scalef32_pk_bf16_fp4 v56, v106, 1.0 op_sel:[0,1,0]
	v_cvt_scalef32_pk_bf16_fp4 v60, v106, 1.0 op_sel:[1,1,0]
	s_lshl_b64 s[26:27], s[26:27], 10
	v_dot2c_f32_bf16_e32 v58, v52, v22
	v_dot2c_f32_bf16_e32 v50, v54, v20
	s_add_u32 s26, s13, s26
	v_dot2c_f32_bf16_e32 v58, v56, v26
	v_dot2c_f32_bf16_e32 v50, v60, v24
	v_cvt_scalef32_pk_bf16_fp4 v52, v107, 1.0
	v_cvt_scalef32_pk_bf16_fp4 v54, v107, 1.0 op_sel:[1,0,0]
	v_cvt_scalef32_pk_bf16_fp4 v56, v107, 1.0 op_sel:[0,1,0]
	v_cvt_scalef32_pk_bf16_fp4 v60, v107, 1.0 op_sel:[1,1,0]
	s_addc_u32 s27, s12, s27
	v_dot2c_f32_bf16_e32 v58, v52, v30
	v_dot2c_f32_bf16_e32 v50, v54, v28
	s_nop 0
	v_dot2c_f32_bf16_e32 v58, v56, v36
	v_dot2c_f32_bf16_e32 v50, v60, v34
	v_mov_b32_e32 v60, 0
	s_nop 2
	v_add_f32_e32 v50, v58, v50
	global_load_dwordx4 v[104:107], v32, s[26:27]
	s_waitcnt vmcnt(15)
	v_cvt_scalef32_pk_bf16_fp4 v52, v108, 1.0
	v_cvt_scalef32_pk_bf16_fp4 v54, v108, 1.0 op_sel:[1,0,0]
	v_cvt_scalef32_pk_bf16_fp4 v56, v108, 1.0 op_sel:[0,1,0]
	v_cvt_scalef32_pk_bf16_fp4 v58, v108, 1.0 op_sel:[1,1,0]
	v_readlane_b32 s26, v2, 10
	v_dot2c_f32_bf16_e32 v60, v52, v6
	v_mov_b32_e32 v52, 0
	v_dot2c_f32_bf16_e32 v52, v54, v4
	v_dot2c_f32_bf16_e32 v60, v56, v10
	s_lshr_b32 s26, s26, 7
	v_dot2c_f32_bf16_e32 v52, v58, v8
	v_cvt_scalef32_pk_bf16_fp4 v54, v109, 1.0
	v_cvt_scalef32_pk_bf16_fp4 v56, v109, 1.0 op_sel:[1,0,0]
	v_cvt_scalef32_pk_bf16_fp4 v58, v109, 1.0 op_sel:[0,1,0]
	v_cvt_scalef32_pk_bf16_fp4 v62, v109, 1.0 op_sel:[1,1,0]
	s_mov_b32 s27, s86
	v_dot2c_f32_bf16_e32 v60, v54, v14
	v_dot2c_f32_bf16_e32 v52, v56, v12
	s_lshl_b64 s[26:27], s[26:27], 10
	v_dot2c_f32_bf16_e32 v60, v58, v18
	v_dot2c_f32_bf16_e32 v52, v62, v16
	v_cvt_scalef32_pk_bf16_fp4 v54, v110, 1.0
	v_cvt_scalef32_pk_bf16_fp4 v56, v110, 1.0 op_sel:[1,0,0]
	v_cvt_scalef32_pk_bf16_fp4 v58, v110, 1.0 op_sel:[0,1,0]
	v_cvt_scalef32_pk_bf16_fp4 v62, v110, 1.0 op_sel:[1,1,0]
	s_add_u32 s26, s13, s26
	v_dot2c_f32_bf16_e32 v60, v54, v22
	v_dot2c_f32_bf16_e32 v52, v56, v20
	s_addc_u32 s27, s12, s27
	v_dot2c_f32_bf16_e32 v60, v58, v26
	v_dot2c_f32_bf16_e32 v52, v62, v24
	v_cvt_scalef32_pk_bf16_fp4 v54, v111, 1.0
	v_cvt_scalef32_pk_bf16_fp4 v56, v111, 1.0 op_sel:[1,0,0]
	v_cvt_scalef32_pk_bf16_fp4 v58, v111, 1.0 op_sel:[0,1,0]
	v_cvt_scalef32_pk_bf16_fp4 v62, v111, 1.0 op_sel:[1,1,0]
	s_nop 0
	v_dot2c_f32_bf16_e32 v60, v54, v30
	v_dot2c_f32_bf16_e32 v52, v56, v28
	s_nop 0
	v_dot2c_f32_bf16_e32 v60, v58, v36
	v_dot2c_f32_bf16_e32 v52, v62, v34
	s_nop 0
	s_nop 2
	v_add_f32_e32 v51, v60, v52
	global_load_dwordx4 v[108:111], v32, s[26:27]
	s_waitcnt vmcnt(15)
	v_cvt_scalef32_pk_bf16_fp4 v52, v112, 1.0
	v_mov_b32_e32 v60, 0
	v_cvt_scalef32_pk_bf16_fp4 v54, v112, 1.0 op_sel:[1,0,0]
	v_cvt_scalef32_pk_bf16_fp4 v56, v112, 1.0 op_sel:[0,1,0]
	v_cvt_scalef32_pk_bf16_fp4 v58, v112, 1.0 op_sel:[1,1,0]
	v_dot2c_f32_bf16_e32 v60, v52, v6
	v_mov_b32_e32 v52, 0
	v_dot2c_f32_bf16_e32 v52, v54, v4
	v_dot2c_f32_bf16_e32 v60, v56, v10
	v_readlane_b32 s26, v2, 11
	v_dot2c_f32_bf16_e32 v52, v58, v8
	v_cvt_scalef32_pk_bf16_fp4 v54, v113, 1.0
	v_cvt_scalef32_pk_bf16_fp4 v56, v113, 1.0 op_sel:[1,0,0]
	v_cvt_scalef32_pk_bf16_fp4 v58, v113, 1.0 op_sel:[0,1,0]
	v_cvt_scalef32_pk_bf16_fp4 v62, v113, 1.0 op_sel:[1,1,0]
	s_lshr_b32 s26, s26, 7
	v_dot2c_f32_bf16_e32 v60, v54, v14
	v_dot2c_f32_bf16_e32 v52, v56, v12
	s_mov_b32 s27, s86
	v_dot2c_f32_bf16_e32 v60, v58, v18
	v_dot2c_f32_bf16_e32 v52, v62, v16
	v_cvt_scalef32_pk_bf16_fp4 v54, v114, 1.0
	v_cvt_scalef32_pk_bf16_fp4 v56, v114, 1.0 op_sel:[1,0,0]
	v_cvt_scalef32_pk_bf16_fp4 v58, v114, 1.0 op_sel:[0,1,0]
	v_cvt_scalef32_pk_bf16_fp4 v62, v114, 1.0 op_sel:[1,1,0]
	s_lshl_b64 s[26:27], s[26:27], 10
	v_dot2c_f32_bf16_e32 v60, v54, v22
	v_dot2c_f32_bf16_e32 v52, v56, v20
	s_add_u32 s26, s13, s26
	v_dot2c_f32_bf16_e32 v60, v58, v26
	v_dot2c_f32_bf16_e32 v52, v62, v24
	v_cvt_scalef32_pk_bf16_fp4 v54, v115, 1.0
	v_cvt_scalef32_pk_bf16_fp4 v56, v115, 1.0 op_sel:[1,0,0]
	v_cvt_scalef32_pk_bf16_fp4 v58, v115, 1.0 op_sel:[0,1,0]
	v_cvt_scalef32_pk_bf16_fp4 v62, v115, 1.0 op_sel:[1,1,0]
	s_addc_u32 s27, s12, s27
	v_dot2c_f32_bf16_e32 v60, v54, v30
	v_dot2c_f32_bf16_e32 v52, v56, v28
	s_nop 0
	v_dot2c_f32_bf16_e32 v60, v58, v36
	v_dot2c_f32_bf16_e32 v52, v62, v34
	s_nop 0
	s_nop 2
	v_add_f32_e32 v100, v60, v52
	global_load_dwordx4 v[112:115], v32, s[26:27]
	s_waitcnt vmcnt(15)
; #define P4_FOR16(M) M(0) M(1) M(2) M(3) M(4) M(5) M(6) M(7) M(8) M(9) M(10) M(11) M(12) M(13) M(14) M(15)
; #define P4_U(i) { P4_DOT(b##i, part[i]); const int nk_ = __builtin_amdgcn_readlane(ksel, nb + i); P4_LOAD(b##i, Ug, nk_); }
; #define P4_U(i) { P4_DOT(b##i, part[i]); const int nk_ = __builtin_amdgcn_readlane(kn, i); P4_LOAD(b##i, nbase, nk_); }
; __device__ __forceinline__ void peer_gather_f4p(const float* X, const int* __restrict__ IDX, const float* __restrict__ G, ...
;     ...
;         {
;     ...
;             P4_FOR16(P4_U)
	v_cvt_scalef32_pk_bf16_fp4 v52, v116, 1.0
	v_mov_b32_e32 v60, 0
	v_cvt_scalef32_pk_bf16_fp4 v54, v116, 1.0 op_sel:[1,0,0]
	v_cvt_scalef32_pk_bf16_fp4 v56, v116, 1.0 op_sel:[0,1,0]
	v_cvt_scalef32_pk_bf16_fp4 v58, v116, 1.0 op_sel:[1,1,0]
	v_dot2c_f32_bf16_e32 v60, v52, v6
	v_mov_b32_e32 v52, 0
	v_dot2c_f32_bf16_e32 v52, v54, v4
	v_dot2c_f32_bf16_e32 v60, v56, v10
	v_readlane_b32 s26, v2, 12
	v_dot2c_f32_bf16_e32 v52, v58, v8
	v_cvt_scalef32_pk_bf16_fp4 v54, v117, 1.0
	v_cvt_scalef32_pk_bf16_fp4 v56, v117, 1.0 op_sel:[1,0,0]
	v_cvt_scalef32_pk_bf16_fp4 v58, v117, 1.0 op_sel:[0,1,0]
	v_cvt_scalef32_pk_bf16_fp4 v62, v117, 1.0 op_sel:[1,1,0]
	s_lshr_b32 s26, s26, 7
	v_dot2c_f32_bf16_e32 v60, v54, v14
	v_dot2c_f32_bf16_e32 v52, v56, v12
	s_mov_b32 s27, s86
	v_dot2c_f32_bf16_e32 v60, v58, v18
	v_dot2c_f32_bf16_e32 v52, v62, v16
	v_cvt_scalef32_pk_bf16_fp4 v54, v118, 1.0
	v_cvt_scalef32_pk_bf16_fp4 v56, v118, 1.0 op_sel:[1,0,0]
	v_cvt_scalef32_pk_bf16_fp4 v58, v118, 1.0 op_sel:[0,1,0]
	v_cvt_scalef32_pk_bf16_fp4 v62, v118, 1.0 op_sel:[1,1,0]
	s_lshl_b64 s[26:27], s[26:27], 10
	v_dot2c_f32_bf16_e32 v60, v54, v22
	v_dot2c_f32_bf16_e32 v52, v56, v20
	s_add_u32 s26, s13, s26
	v_dot2c_f32_bf16_e32 v60, v58, v26
	v_dot2c_f32_bf16_e32 v52, v62, v24
	v_cvt_scalef32_pk_bf16_fp4 v54, v119, 1.0
	v_cvt_scalef32_pk_bf16_fp4 v56, v119, 1.0 op_sel:[1,0,0]
	v_cvt_scalef32_pk_bf16_fp4 v58, v119, 1.0 op_sel:[0,1,0]
	v_cvt_scalef32_pk_bf16_fp4 v62, v119, 1.0 op_sel:[1,1,0]
	s_addc_u32 s27, s12, s27
	v_dot2c_f32_bf16_e32 v60, v54, v30
	v_dot2c_f32_bf16_e32 v52, v56, v28
	s_nop 0
	v_dot2c_f32_bf16_e32 v60, v58, v36
	v_dot2c_f32_bf16_e32 v52, v62, v34
	s_nop 0
	s_nop 2
	v_add_f32_e32 v101, v60, v52
	global_load_dwordx4 v[116:119], v32, s[26:27]
	s_waitcnt vmcnt(15)
	v_cvt_scalef32_pk_bf16_fp4 v52, v120, 1.0
	v_mov_b32_e32 v60, 0
	v_cvt_scalef32_pk_bf16_fp4 v54, v120, 1.0 op_sel:[1,0,0]
	v_cvt_scalef32_pk_bf16_fp4 v56, v120, 1.0 op_sel:[0,1,0]
	v_cvt_scalef32_pk_bf16_fp4 v58, v120, 1.0 op_sel:[1,1,0]
	v_dot2c_f32_bf16_e32 v60, v52, v6
	v_mov_b32_e32 v52, 0
	v_dot2c_f32_bf16_e32 v52, v54, v4
	v_dot2c_f32_bf16_e32 v60, v56, v10
	v_readlane_b32 s26, v2, 13
	v_dot2c_f32_bf16_e32 v52, v58, v8
	v_cvt_scalef32_pk_bf16_fp4 v54, v121, 1.0
	v_cvt_scalef32_pk_bf16_fp4 v56, v121, 1.0 op_sel:[1,0,0]
	v_cvt_scalef32_pk_bf16_fp4 v58, v121, 1.0 op_sel:[0,1,0]
	v_cvt_scalef32_pk_bf16_fp4 v62, v121, 1.0 op_sel:[1,1,0]
	s_lshr_b32 s26, s26, 7
	v_dot2c_f32_bf16_e32 v60, v54, v14
	v_dot2c_f32_bf16_e32 v52, v56, v12
	s_mov_b32 s27, s86
	v_dot2c_f32_bf16_e32 v60, v58, v18
	v_dot2c_f32_bf16_e32 v52, v62, v16
	v_cvt_scalef32_pk_bf16_fp4 v54, v122, 1.0
	v_cvt_scalef32_pk_bf16_fp4 v56, v122, 1.0 op_sel:[1,0,0]
	v_cvt_scalef32_pk_bf16_fp4 v58, v122, 1.0 op_sel:[0,1,0]
	v_cvt_scalef32_pk_bf16_fp4 v62, v122, 1.0 op_sel:[1,1,0]
	s_lshl_b64 s[26:27], s[26:27], 10
	v_dot2c_f32_bf16_e32 v60, v54, v22
	v_dot2c_f32_bf16_e32 v52, v56, v20
	s_add_u32 s26, s13, s26
	v_dot2c_f32_bf16_e32 v60, v58, v26
	v_dot2c_f32_bf16_e32 v52, v62, v24
	v_cvt_scalef32_pk_bf16_fp4 v54, v123, 1.0
	v_cvt_scalef32_pk_bf16_fp4 v56, v123, 1.0 op_sel:[1,0,0]
	v_cvt_scalef32_pk_bf16_fp4 v58, v123, 1.0 op_sel:[0,1,0]
	v_cvt_scalef32_pk_bf16_fp4 v62, v123, 1.0 op_sel:[1,1,0]
	s_addc_u32 s27, s12, s27
	v_dot2c_f32_bf16_e32 v60, v54, v30
	v_dot2c_f32_bf16_e32 v52, v56, v28
	s_nop 0
	v_dot2c_f32_bf16_e32 v60, v58, v36
	v_dot2c_f32_bf16_e32 v52, v62, v34
	s_nop 0
	s_nop 2
	v_add_f32_e32 v102, v60, v52
	global_load_dwordx4 v[120:123], v32, s[26:27]
	s_waitcnt vmcnt(15)
	v_cvt_scalef32_pk_bf16_fp4 v52, v124, 1.0
	v_mov_b32_e32 v60, 0
	v_cvt_scalef32_pk_bf16_fp4 v54, v124, 1.0 op_sel:[1,0,0]
	v_cvt_scalef32_pk_bf16_fp4 v56, v124, 1.0 op_sel:[0,1,0]
	v_cvt_scalef32_pk_bf16_fp4 v58, v124, 1.0 op_sel:[1,1,0]
	v_dot2c_f32_bf16_e32 v60, v52, v6
	v_mov_b32_e32 v52, 0
	v_dot2c_f32_bf16_e32 v52, v54, v4
	v_dot2c_f32_bf16_e32 v60, v56, v10
	v_readlane_b32 s26, v2, 14
	v_dot2c_f32_bf16_e32 v52, v58, v8
	v_cvt_scalef32_pk_bf16_fp4 v54, v125, 1.0
	v_cvt_scalef32_pk_bf16_fp4 v56, v125, 1.0 op_sel:[1,0,0]
	v_cvt_scalef32_pk_bf16_fp4 v58, v125, 1.0 op_sel:[0,1,0]
	v_cvt_scalef32_pk_bf16_fp4 v62, v125, 1.0 op_sel:[1,1,0]
	s_lshr_b32 s26, s26, 7
	v_dot2c_f32_bf16_e32 v60, v54, v14
	v_dot2c_f32_bf16_e32 v52, v56, v12
	s_mov_b32 s27, s86
	v_dot2c_f32_bf16_e32 v60, v58, v18
	v_dot2c_f32_bf16_e32 v52, v62, v16
	v_cvt_scalef32_pk_bf16_fp4 v54, v126, 1.0
	v_cvt_scalef32_pk_bf16_fp4 v56, v126, 1.0 op_sel:[1,0,0]
	v_cvt_scalef32_pk_bf16_fp4 v58, v126, 1.0 op_sel:[0,1,0]
	v_cvt_scalef32_pk_bf16_fp4 v62, v126, 1.0 op_sel:[1,1,0]
	s_lshl_b64 s[26:27], s[26:27], 10
	v_dot2c_f32_bf16_e32 v60, v54, v22
	v_dot2c_f32_bf16_e32 v52, v56, v20
	s_add_u32 s26, s13, s26
	v_dot2c_f32_bf16_e32 v60, v58, v26
	v_dot2c_f32_bf16_e32 v52, v62, v24
	v_cvt_scalef32_pk_bf16_fp4 v54, v127, 1.0
	v_cvt_scalef32_pk_bf16_fp4 v56, v127, 1.0 op_sel:[1,0,0]
	v_cvt_scalef32_pk_bf16_fp4 v58, v127, 1.0 op_sel:[0,1,0]
	v_cvt_scalef32_pk_bf16_fp4 v62, v127, 1.0 op_sel:[1,1,0]
	s_addc_u32 s27, s12, s27
	v_dot2c_f32_bf16_e32 v60, v54, v30
	v_dot2c_f32_bf16_e32 v52, v56, v28
	s_nop 0
	v_dot2c_f32_bf16_e32 v60, v58, v36
	v_dot2c_f32_bf16_e32 v52, v62, v34
	s_nop 0
	s_nop 2
	v_add_f32_e32 v62, v60, v52
	v_lshl_add_u64 v[52:53], s[26:27], 0, v[32:33]
	v_mov_b32_e32 v60, 0
	global_load_dwordx4 v[124:127], v[52:53], off
	s_waitcnt vmcnt(15)
; __device__ __forceinline__ float gelu_tanh(float h) {
;     return 0.5f * h * (1.f + tanhf(0.7978845608028654f * (h + 0.044715f * h * h * h)));
; }
	v_cvt_scalef32_pk_bf16_fp4 v52, v128, 1.0
	v_cvt_scalef32_pk_bf16_fp4 v54, v128, 1.0 op_sel:[1,0,0]
	v_cvt_scalef32_pk_bf16_fp4 v56, v128, 1.0 op_sel:[0,1,0]
	v_cvt_scalef32_pk_bf16_fp4 v58, v128, 1.0 op_sel:[1,1,0]
	v_readlane_b32 s26, v2, 15
	v_dot2c_f32_bf16_e32 v60, v52, v6
	v_dot2c_f32_bf16_e32 v38, v54, v4
	s_lshr_b32 s26, s26, 7
	v_dot2c_f32_bf16_e32 v60, v56, v10
	v_dot2c_f32_bf16_e32 v38, v58, v8
	v_cvt_scalef32_pk_bf16_fp4 v4, v129, 1.0
	v_cvt_scalef32_pk_bf16_fp4 v6, v129, 1.0 op_sel:[1,0,0]
	v_cvt_scalef32_pk_bf16_fp4 v8, v129, 1.0 op_sel:[0,1,0]
	v_cvt_scalef32_pk_bf16_fp4 v10, v129, 1.0 op_sel:[1,1,0]
	s_mov_b32 s27, s86
	v_dot2c_f32_bf16_e32 v60, v4, v14
	v_dot2c_f32_bf16_e32 v38, v6, v12
	s_lshl_b64 s[26:27], s[26:27], 10
	v_dot2c_f32_bf16_e32 v60, v8, v18
	v_dot2c_f32_bf16_e32 v38, v10, v16
	v_cvt_scalef32_pk_bf16_fp4 v4, v130, 1.0
	v_cvt_scalef32_pk_bf16_fp4 v6, v130, 1.0 op_sel:[1,0,0]
	v_cvt_scalef32_pk_bf16_fp4 v8, v130, 1.0 op_sel:[0,1,0]
	v_cvt_scalef32_pk_bf16_fp4 v10, v130, 1.0 op_sel:[1,1,0]
	s_add_u32 s26, s13, s26
	v_dot2c_f32_bf16_e32 v60, v4, v22
	v_dot2c_f32_bf16_e32 v38, v6, v20
	s_addc_u32 s27, s12, s27
	v_dot2c_f32_bf16_e32 v60, v8, v26
	v_dot2c_f32_bf16_e32 v38, v10, v24
	v_cvt_scalef32_pk_bf16_fp4 v4, v131, 1.0
	v_cvt_scalef32_pk_bf16_fp4 v6, v131, 1.0 op_sel:[1,0,0]
	v_cvt_scalef32_pk_bf16_fp4 v8, v131, 1.0 op_sel:[0,1,0]
	v_cvt_scalef32_pk_bf16_fp4 v10, v131, 1.0 op_sel:[1,1,0]
	v_cndmask_b32_e64 v2, v49, v41, s[48:49]
	v_dot2c_f32_bf16_e32 v60, v4, v30
	v_dot2c_f32_bf16_e32 v38, v6, v28
	v_cndmask_b32_e64 v7, v43, v51, s[48:49]
	v_dot2c_f32_bf16_e32 v60, v8, v36
	v_dot2c_f32_bf16_e32 v38, v10, v34
	ds_swizzle_b32 v7, v7 offset:swizzle(SWAP,8)
	s_nop 2
	v_add_f32_e32 v6, v60, v38
	global_load_dwordx4 v[128:131], v32, s[26:27]
	v_cndmask_b32_e64 v4, v41, v49, s[48:49]
	ds_swizzle_b32 v4, v4 offset:swizzle(SWAP,8)
	v_cndmask_b32_e64 v5, v42, v50, s[48:49]
	ds_swizzle_b32 v5, v5 offset:swizzle(SWAP,8)
	v_cndmask_b32_e64 v8, v44, v100, s[48:49]
	ds_swizzle_b32 v8, v8 offset:swizzle(SWAP,8)
	v_cndmask_b32_e64 v9, v45, v101, s[48:49]
	ds_swizzle_b32 v9, v9 offset:swizzle(SWAP,8)
	v_cndmask_b32_e64 v10, v46, v102, s[48:49]
	s_waitcnt lgkmcnt(3)
	v_add_f32_e32 v2, v2, v4
	v_cndmask_b32_e64 v4, v50, v42, s[48:49]
	ds_swizzle_b32 v10, v10 offset:swizzle(SWAP,8)
	v_cndmask_b32_e64 v11, v47, v62, s[48:49]
	s_waitcnt lgkmcnt(3)
	v_add_f32_e32 v4, v4, v5
	v_cndmask_b32_e64 v5, v51, v43, s[48:49]
	ds_swizzle_b32 v11, v11 offset:swizzle(SWAP,8)
	v_add_f32_e32 v5, v5, v7
	v_cndmask_b32_e64 v7, v100, v44, s[48:49]
	s_waitcnt lgkmcnt(3)
	v_add_f32_e32 v7, v7, v8
	v_cndmask_b32_e64 v8, v101, v45, s[48:49]
	s_waitcnt lgkmcnt(2)
	v_add_f32_e32 v8, v8, v9
	v_cndmask_b32_e64 v9, v102, v46, s[48:49]
	s_waitcnt lgkmcnt(1)
	v_add_f32_e32 v9, v9, v10
	v_cndmask_b32_e64 v10, v62, v47, s[48:49]
	s_waitcnt lgkmcnt(0)
	v_add_f32_e32 v10, v10, v11
	v_cndmask_b32_e64 v11, v6, v48, s[48:49]
	v_cndmask_b32_e64 v6, v48, v6, s[48:49]
	ds_swizzle_b32 v6, v6 offset:swizzle(SWAP,8)
	s_waitcnt lgkmcnt(0)
	v_add_f32_e32 v6, v11, v6
	v_cndmask_b32_e64 v11, v8, v2, s[46:47]
	v_cndmask_b32_e64 v2, v2, v8, s[46:47]
	v_cndmask_b32_e64 v8, v9, v4, s[46:47]
	v_cndmask_b32_e64 v4, v4, v9, s[46:47]
	ds_swizzle_b32 v4, v4 offset:swizzle(SWAP,4)
	ds_swizzle_b32 v2, v2 offset:swizzle(SWAP,4)
	s_waitcnt lgkmcnt(1)
	v_add_f32_e32 v4, v8, v4
	v_cndmask_b32_e64 v8, v10, v5, s[46:47]
	v_cndmask_b32_e64 v5, v5, v10, s[46:47]
	ds_swizzle_b32 v5, v5 offset:swizzle(SWAP,4)
	s_waitcnt lgkmcnt(1)
	v_add_f32_e32 v2, v11, v2
	s_waitcnt lgkmcnt(0)
	v_add_f32_e32 v5, v8, v5
	v_cndmask_b32_e64 v8, v6, v7, s[46:47]
	v_cndmask_b32_e64 v6, v7, v6, s[46:47]
	ds_swizzle_b32 v6, v6 offset:swizzle(SWAP,4)
	v_cndmask_b32_e64 v7, v5, v2, s[44:45]
	v_cndmask_b32_e64 v2, v2, v5, s[44:45]
	ds_swizzle_b32 v2, v2 offset:swizzle(SWAP,2)
	s_waitcnt lgkmcnt(1)
	v_add_f32_e32 v6, v8, v6
	v_cndmask_b32_e64 v5, v6, v4, s[44:45]
	v_cndmask_b32_e64 v4, v4, v6, s[44:45]
	ds_swizzle_b32 v4, v4 offset:swizzle(SWAP,2)
	s_waitcnt lgkmcnt(1)
	v_add_f32_e32 v2, v7, v2
	s_waitcnt lgkmcnt(0)
	v_add_f32_e32 v4, v5, v4
	v_cndmask_b32_e64 v5, v4, v2, s[42:43]
	v_cndmask_b32_e64 v2, v2, v4, s[42:43]
	ds_swizzle_b32 v2, v2 offset:swizzle(SWAP,1)
	s_waitcnt lgkmcnt(0)
	v_add_f32_e32 v2, v5, v2
	ds_swizzle_b32 v4, v2 offset:swizzle(SWAP,16)
	s_waitcnt lgkmcnt(0)
	v_add_f32_e32 v2, v2, v4
	v_mov_b32_e32 v4, v2
	s_nop 1
	v_permlane32_swap_b32_e32 v2, v4
	v_add_f32_e32 v6, v2, v4
	v_lshl_add_u32 v2, v40, 2, s14
	v_add_u32_e32 v4, 0xc0, v2
	ds_read2st64_b32 v[4:5], v4 offset0:9 offset1:17
	s_waitcnt lgkmcnt(0)
	v_mul_f32_e32 v4, v4, v6
	v_mul_f32_e32 v6, 0x3d372713, v4
	v_mul_f32_e32 v6, v4, v6
	v_fma_f32 v6, v4, v6, v4
	v_mul_f32_e32 v6, 0x3f4c422a, v6
	v_cmp_nlt_f32_e64 s[12:13], |v6|, s25
	s_and_saveexec_b64 s[26:27], s[12:13]
	s_xor_b64 s[12:13], exec, s[26:27]
	s_cbranch_execz .LBB0_543
	v_add_f32_e64 v7, |v6|, |v6|
	v_mul_f32_e32 v8, 0x3fb8aa3b, v7
	v_rndne_f32_e32 v9, v8
	v_sub_f32_e32 v10, v8, v9
	v_fma_f32 v8, v7, s70, -v8
	v_fmac_f32_e32 v8, 0x32a5705f, v7
	v_add_f32_e32 v8, v10, v8
	v_cvt_i32_f32_e32 v9, v9
	v_exp_f32_e32 v8, v8
	v_cmp_ngt_f32_e64 s[42:43], s67, v7
	v_ldexp_f32 v8, v8, v9
	s_nop 0
	v_cndmask_b32_e64 v8, 0, v8, s[42:43]
	v_cmp_nlt_f32_e64 s[42:43], s68, v7
	s_nop 1
	v_cndmask_b32_e64 v7, v205, v8, s[42:43]
	v_add_f32_e32 v7, 1.0, v7
	v_rcp_f32_e32 v7, v7
	s_nop 0
	v_fma_f32 v7, v7, -2.0, 1.0
	s_andn2_saveexec_b64 s[12:13], s[12:13]
	s_cbranch_execnz .LBB0_544

; #define P4_FOR16(M) M(0) M(1) M(2) M(3) M(4) M(5) M(6) M(7) M(8) M(9) M(10) M(11) M(12) M(13) M(14) M(15)
; #define P4_U(i) { P4_DOT(b##i, part[i]); const int nk_ = __builtin_amdgcn_readlane(ksel, nb + i); P4_LOAD(b##i, Ug, nk_); }
; #define P4_U(i) { P4_DOT(b##i, part[i]); const int nk_ = __builtin_amdgcn_readlane(kn, i); P4_LOAD(b##i, nbase, nk_); }
; __device__ __forceinline__ void peer_gather_f4p(const float* X, const int* __restrict__ IDX, const float* __restrict__ G, ...
;     ...
; #pragma unroll 1
;         for (int bt = 0; bt < 7; ++bt) {
;             const int ksel = (bt + 1 < 4) ? k0 : k1;
;             const int nb = (16 * (bt + 1)) & 63;
;     ...
;             P4_FOR16(P4_U)
.LBB0_1230:
	s_mov_b32 s87, s86
	s_waitcnt vmcnt(15)
	v_cvt_scalef32_pk_bf16_fp4 v48, v64, 1.0
	v_mov_b32_e32 v56, 0
	v_cvt_scalef32_pk_bf16_fp4 v50, v64, 1.0 op_sel:[1,0,0]
	v_cvt_scalef32_pk_bf16_fp4 v52, v64, 1.0 op_sel:[0,1,0]
	v_cvt_scalef32_pk_bf16_fp4 v54, v64, 1.0 op_sel:[1,1,0]
	v_dot2c_f32_bf16_e32 v56, v48, v6
	v_mov_b32_e32 v48, 0
	v_dot2c_f32_bf16_e32 v48, v50, v4
	v_dot2c_f32_bf16_e32 v56, v52, v10
	s_cmp_lt_u32 s29, 3
	v_dot2c_f32_bf16_e32 v48, v54, v8
	v_cvt_scalef32_pk_bf16_fp4 v50, v65, 1.0
	v_cvt_scalef32_pk_bf16_fp4 v52, v65, 1.0 op_sel:[1,0,0]
	v_cvt_scalef32_pk_bf16_fp4 v54, v65, 1.0 op_sel:[0,1,0]
	v_cvt_scalef32_pk_bf16_fp4 v58, v65, 1.0 op_sel:[1,1,0]
	s_cselect_b64 s[48:49], -1, 0
	v_dot2c_f32_bf16_e32 v56, v50, v14
	v_dot2c_f32_bf16_e32 v48, v52, v12
	s_waitcnt lgkmcnt(1)
	v_cndmask_b32_e64 v46, v39, v38, s[48:49]
	v_dot2c_f32_bf16_e32 v56, v54, v18
	v_dot2c_f32_bf16_e32 v48, v58, v16
	v_cvt_scalef32_pk_bf16_fp4 v50, v66, 1.0
	v_cvt_scalef32_pk_bf16_fp4 v52, v66, 1.0 op_sel:[1,0,0]
	v_cvt_scalef32_pk_bf16_fp4 v54, v66, 1.0 op_sel:[0,1,0]
	v_cvt_scalef32_pk_bf16_fp4 v58, v66, 1.0 op_sel:[1,1,0]
	s_add_i32 s12, s28, -15
	v_dot2c_f32_bf16_e32 v56, v50, v22
	v_dot2c_f32_bf16_e32 v48, v52, v20
	v_readlane_b32 s12, v46, s12
	v_dot2c_f32_bf16_e32 v56, v54, v26
	v_dot2c_f32_bf16_e32 v48, v58, v24
	v_cvt_scalef32_pk_bf16_fp4 v50, v67, 1.0
	v_cvt_scalef32_pk_bf16_fp4 v52, v67, 1.0 op_sel:[1,0,0]
	v_cvt_scalef32_pk_bf16_fp4 v54, v67, 1.0 op_sel:[0,1,0]
	v_cvt_scalef32_pk_bf16_fp4 v58, v67, 1.0 op_sel:[1,1,0]
	s_lshr_b32 s12, s12, 7
	v_dot2c_f32_bf16_e32 v56, v50, v30
	v_dot2c_f32_bf16_e32 v48, v52, v28
	s_mov_b32 s13, s86
	v_dot2c_f32_bf16_e32 v56, v54, v36
	v_dot2c_f32_bf16_e32 v48, v58, v34
	s_lshl_b64 s[12:13], s[12:13], 10
	s_nop 2
	v_readfirstlane_b32 s100, v40
	v_readfirstlane_b32 s101, v41
	v_subrev_u32_e32 v207, s100, v40
	v_add_f32_e32 v47, v56, v48
	s_add_u32 s12, s12, s100
	s_addc_u32 s13, s13, s101
	global_load_dwordx4 v[64:67], v207, s[12:13]
	s_waitcnt vmcnt(15)
	v_cvt_scalef32_pk_bf16_fp4 v48, v68, 1.0
	v_mov_b32_e32 v56, 0
	v_cvt_scalef32_pk_bf16_fp4 v50, v68, 1.0 op_sel:[1,0,0]
	v_cvt_scalef32_pk_bf16_fp4 v52, v68, 1.0 op_sel:[0,1,0]
	v_cvt_scalef32_pk_bf16_fp4 v54, v68, 1.0 op_sel:[1,1,0]
	v_dot2c_f32_bf16_e32 v56, v48, v6
	v_mov_b32_e32 v48, 0
	v_dot2c_f32_bf16_e32 v48, v50, v4
	v_dot2c_f32_bf16_e32 v56, v52, v10
	s_add_i32 s12, s28, -14
	v_dot2c_f32_bf16_e32 v48, v54, v8
	v_cvt_scalef32_pk_bf16_fp4 v50, v69, 1.0
	v_cvt_scalef32_pk_bf16_fp4 v52, v69, 1.0 op_sel:[1,0,0]
	v_cvt_scalef32_pk_bf16_fp4 v54, v69, 1.0 op_sel:[0,1,0]
	v_cvt_scalef32_pk_bf16_fp4 v58, v69, 1.0 op_sel:[1,1,0]
	v_readlane_b32 s12, v46, s12
	v_dot2c_f32_bf16_e32 v56, v50, v14
	v_dot2c_f32_bf16_e32 v48, v52, v12
	s_lshr_b32 s12, s12, 7
	v_dot2c_f32_bf16_e32 v56, v54, v18
	v_dot2c_f32_bf16_e32 v48, v58, v16
	v_cvt_scalef32_pk_bf16_fp4 v50, v70, 1.0
	v_cvt_scalef32_pk_bf16_fp4 v52, v70, 1.0 op_sel:[1,0,0]
	v_cvt_scalef32_pk_bf16_fp4 v54, v70, 1.0 op_sel:[0,1,0]
	v_cvt_scalef32_pk_bf16_fp4 v58, v70, 1.0 op_sel:[1,1,0]
	s_mov_b32 s13, s86
	v_dot2c_f32_bf16_e32 v56, v50, v22
	v_dot2c_f32_bf16_e32 v48, v52, v20
	s_lshl_b64 s[12:13], s[12:13], 10
	v_dot2c_f32_bf16_e32 v56, v54, v26
	v_dot2c_f32_bf16_e32 v48, v58, v24
	v_cvt_scalef32_pk_bf16_fp4 v50, v71, 1.0
	v_cvt_scalef32_pk_bf16_fp4 v52, v71, 1.0 op_sel:[1,0,0]
	v_cvt_scalef32_pk_bf16_fp4 v54, v71, 1.0 op_sel:[0,1,0]
	v_cvt_scalef32_pk_bf16_fp4 v58, v71, 1.0 op_sel:[1,1,0]
	v_mov_b32_e32 v42, 0
	v_dot2c_f32_bf16_e32 v56, v50, v30
	v_dot2c_f32_bf16_e32 v48, v52, v28
	s_nop 0
	v_dot2c_f32_bf16_e32 v56, v54, v36
	v_dot2c_f32_bf16_e32 v48, v58, v34
	v_mov_b32_e32 v58, 0
	s_nop 2
	v_add_f32_e32 v48, v56, v48
	s_add_u32 s12, s12, s100
	s_addc_u32 s13, s13, s101
	global_load_dwordx4 v[68:71], v207, s[12:13]
	s_waitcnt vmcnt(15)
	v_cvt_scalef32_pk_bf16_fp4 v50, v72, 1.0
	v_cvt_scalef32_pk_bf16_fp4 v52, v72, 1.0 op_sel:[1,0,0]
	v_cvt_scalef32_pk_bf16_fp4 v54, v72, 1.0 op_sel:[0,1,0]
	v_cvt_scalef32_pk_bf16_fp4 v56, v72, 1.0 op_sel:[1,1,0]
	s_add_i32 s12, s28, -13
	v_dot2c_f32_bf16_e32 v58, v50, v6
	v_mov_b32_e32 v50, 0
	v_dot2c_f32_bf16_e32 v50, v52, v4
	v_dot2c_f32_bf16_e32 v58, v54, v10
	v_readlane_b32 s12, v46, s12
	v_dot2c_f32_bf16_e32 v50, v56, v8
	v_cvt_scalef32_pk_bf16_fp4 v52, v73, 1.0
	v_cvt_scalef32_pk_bf16_fp4 v54, v73, 1.0 op_sel:[1,0,0]
	v_cvt_scalef32_pk_bf16_fp4 v56, v73, 1.0 op_sel:[0,1,0]
	v_cvt_scalef32_pk_bf16_fp4 v60, v73, 1.0 op_sel:[1,1,0]
	s_lshr_b32 s12, s12, 7
	v_dot2c_f32_bf16_e32 v58, v52, v14
	v_dot2c_f32_bf16_e32 v50, v54, v12
	s_mov_b32 s13, s86
	v_dot2c_f32_bf16_e32 v58, v56, v18
	v_dot2c_f32_bf16_e32 v50, v60, v16
	v_cvt_scalef32_pk_bf16_fp4 v52, v74, 1.0
	v_cvt_scalef32_pk_bf16_fp4 v54, v74, 1.0 op_sel:[1,0,0]
	v_cvt_scalef32_pk_bf16_fp4 v56, v74, 1.0 op_sel:[0,1,0]
	v_cvt_scalef32_pk_bf16_fp4 v60, v74, 1.0 op_sel:[1,1,0]
	s_lshl_b64 s[12:13], s[12:13], 10
	v_dot2c_f32_bf16_e32 v58, v52, v22
	v_dot2c_f32_bf16_e32 v50, v54, v20
	s_nop 0
	v_dot2c_f32_bf16_e32 v58, v56, v26
	v_dot2c_f32_bf16_e32 v50, v60, v24
	v_cvt_scalef32_pk_bf16_fp4 v52, v75, 1.0
	v_cvt_scalef32_pk_bf16_fp4 v54, v75, 1.0 op_sel:[1,0,0]
	v_cvt_scalef32_pk_bf16_fp4 v56, v75, 1.0 op_sel:[0,1,0]
	v_cvt_scalef32_pk_bf16_fp4 v60, v75, 1.0 op_sel:[1,1,0]
	s_nop 0
	v_dot2c_f32_bf16_e32 v58, v52, v30
	v_dot2c_f32_bf16_e32 v50, v54, v28
	s_nop 0
	v_dot2c_f32_bf16_e32 v58, v56, v36
	v_dot2c_f32_bf16_e32 v50, v60, v34
	s_nop 0
	s_nop 2
	v_add_f32_e32 v49, v58, v50
	s_add_u32 s12, s12, s100
	s_addc_u32 s13, s13, s101
	global_load_dwordx4 v[72:75], v207, s[12:13]
	s_waitcnt vmcnt(15)
; #define P4_FOR16(M) M(0) M(1) M(2) M(3) M(4) M(5) M(6) M(7) M(8) M(9) M(10) M(11) M(12) M(13) M(14) M(15)
; #define P4_U(i) { P4_DOT(b##i, part[i]); const int nk_ = __builtin_amdgcn_readlane(ksel, nb + i); P4_LOAD(b##i, Ug, nk_); }
; #define P4_U(i) { P4_DOT(b##i, part[i]); const int nk_ = __builtin_amdgcn_readlane(kn, i); P4_LOAD(b##i, nbase, nk_); }
; __device__ __forceinline__ void peer_gather_f4p(const float* X, const int* __restrict__ IDX, const float* __restrict__ G, ...
;     ...
; #pragma unroll 1
;         for (int bt = 0; bt < 7; ++bt) {
;             const int ksel = (bt + 1 < 4) ? k0 : k1;
;             const int nb = (16 * (bt + 1)) & 63;
;     ...
;             P4_FOR16(P4_U)
	v_cvt_scalef32_pk_bf16_fp4 v50, v76, 1.0
	v_mov_b32_e32 v58, 0
	v_cvt_scalef32_pk_bf16_fp4 v52, v76, 1.0 op_sel:[1,0,0]
	v_cvt_scalef32_pk_bf16_fp4 v54, v76, 1.0 op_sel:[0,1,0]
	v_cvt_scalef32_pk_bf16_fp4 v56, v76, 1.0 op_sel:[1,1,0]
	v_dot2c_f32_bf16_e32 v58, v50, v6
	v_mov_b32_e32 v50, 0
	v_dot2c_f32_bf16_e32 v50, v52, v4
	v_dot2c_f32_bf16_e32 v58, v54, v10
	s_add_i32 s12, s28, -12
	v_dot2c_f32_bf16_e32 v50, v56, v8
	v_cvt_scalef32_pk_bf16_fp4 v52, v77, 1.0
	v_cvt_scalef32_pk_bf16_fp4 v54, v77, 1.0 op_sel:[1,0,0]
	v_cvt_scalef32_pk_bf16_fp4 v56, v77, 1.0 op_sel:[0,1,0]
	v_cvt_scalef32_pk_bf16_fp4 v60, v77, 1.0 op_sel:[1,1,0]
	v_readlane_b32 s12, v46, s12
	v_dot2c_f32_bf16_e32 v58, v52, v14
	v_dot2c_f32_bf16_e32 v50, v54, v12
	s_lshr_b32 s12, s12, 7
	v_dot2c_f32_bf16_e32 v58, v56, v18
	v_dot2c_f32_bf16_e32 v50, v60, v16
	v_cvt_scalef32_pk_bf16_fp4 v52, v78, 1.0
	v_cvt_scalef32_pk_bf16_fp4 v54, v78, 1.0 op_sel:[1,0,0]
	v_cvt_scalef32_pk_bf16_fp4 v56, v78, 1.0 op_sel:[0,1,0]
	v_cvt_scalef32_pk_bf16_fp4 v60, v78, 1.0 op_sel:[1,1,0]
	s_mov_b32 s13, s86
	v_dot2c_f32_bf16_e32 v58, v52, v22
	v_dot2c_f32_bf16_e32 v50, v54, v20
	s_lshl_b64 s[12:13], s[12:13], 10
	v_dot2c_f32_bf16_e32 v58, v56, v26
	v_dot2c_f32_bf16_e32 v50, v60, v24
	v_cvt_scalef32_pk_bf16_fp4 v52, v79, 1.0
	v_cvt_scalef32_pk_bf16_fp4 v54, v79, 1.0 op_sel:[1,0,0]
	v_cvt_scalef32_pk_bf16_fp4 v56, v79, 1.0 op_sel:[0,1,0]
	v_cvt_scalef32_pk_bf16_fp4 v60, v79, 1.0 op_sel:[1,1,0]
	s_nop 0
	v_dot2c_f32_bf16_e32 v58, v52, v30
	v_dot2c_f32_bf16_e32 v50, v54, v28
	s_nop 0
	v_dot2c_f32_bf16_e32 v58, v56, v36
	v_dot2c_f32_bf16_e32 v50, v60, v34
	v_mov_b32_e32 v60, 0
	s_nop 2
	v_add_f32_e32 v50, v58, v50
	s_add_u32 s12, s12, s100
	s_addc_u32 s13, s13, s101
	global_load_dwordx4 v[76:79], v207, s[12:13]
	s_waitcnt vmcnt(15)
	v_cvt_scalef32_pk_bf16_fp4 v52, v84, 1.0
	v_cvt_scalef32_pk_bf16_fp4 v54, v84, 1.0 op_sel:[1,0,0]
	v_cvt_scalef32_pk_bf16_fp4 v56, v84, 1.0 op_sel:[0,1,0]
	v_cvt_scalef32_pk_bf16_fp4 v58, v84, 1.0 op_sel:[1,1,0]
	s_add_i32 s12, s28, -11
	v_dot2c_f32_bf16_e32 v60, v52, v6
	v_mov_b32_e32 v52, 0
	v_dot2c_f32_bf16_e32 v52, v54, v4
	v_dot2c_f32_bf16_e32 v60, v56, v10
	v_readlane_b32 s12, v46, s12
	v_dot2c_f32_bf16_e32 v52, v58, v8
	v_cvt_scalef32_pk_bf16_fp4 v54, v85, 1.0
	v_cvt_scalef32_pk_bf16_fp4 v56, v85, 1.0 op_sel:[1,0,0]
	v_cvt_scalef32_pk_bf16_fp4 v58, v85, 1.0 op_sel:[0,1,0]
	v_cvt_scalef32_pk_bf16_fp4 v62, v85, 1.0 op_sel:[1,1,0]
	s_lshr_b32 s12, s12, 7
	v_dot2c_f32_bf16_e32 v60, v54, v14
	v_dot2c_f32_bf16_e32 v52, v56, v12
	s_mov_b32 s13, s86
	v_dot2c_f32_bf16_e32 v60, v58, v18
	v_dot2c_f32_bf16_e32 v52, v62, v16
	v_cvt_scalef32_pk_bf16_fp4 v54, v86, 1.0
	v_cvt_scalef32_pk_bf16_fp4 v56, v86, 1.0 op_sel:[1,0,0]
	v_cvt_scalef32_pk_bf16_fp4 v58, v86, 1.0 op_sel:[0,1,0]
	v_cvt_scalef32_pk_bf16_fp4 v62, v86, 1.0 op_sel:[1,1,0]
	s_lshl_b64 s[12:13], s[12:13], 10
	v_dot2c_f32_bf16_e32 v60, v54, v22
	v_dot2c_f32_bf16_e32 v52, v56, v20
	s_nop 0
	v_dot2c_f32_bf16_e32 v60, v58, v26
	v_dot2c_f32_bf16_e32 v52, v62, v24
	v_cvt_scalef32_pk_bf16_fp4 v54, v87, 1.0
	v_cvt_scalef32_pk_bf16_fp4 v56, v87, 1.0 op_sel:[1,0,0]
	v_cvt_scalef32_pk_bf16_fp4 v58, v87, 1.0 op_sel:[0,1,0]
	v_cvt_scalef32_pk_bf16_fp4 v62, v87, 1.0 op_sel:[1,1,0]
	s_nop 0
	v_dot2c_f32_bf16_e32 v60, v54, v30
	v_dot2c_f32_bf16_e32 v52, v56, v28
	s_nop 0
	v_dot2c_f32_bf16_e32 v60, v58, v36
	v_dot2c_f32_bf16_e32 v52, v62, v34
	s_nop 0
	s_nop 2
	v_add_f32_e32 v51, v60, v52
	s_add_u32 s12, s12, s100
	s_addc_u32 s13, s13, s101
	global_load_dwordx4 v[84:87], v207, s[12:13]
	s_waitcnt vmcnt(15)
	v_cvt_scalef32_pk_bf16_fp4 v52, v88, 1.0
	v_mov_b32_e32 v60, 0
	v_cvt_scalef32_pk_bf16_fp4 v54, v88, 1.0 op_sel:[1,0,0]
	v_cvt_scalef32_pk_bf16_fp4 v56, v88, 1.0 op_sel:[0,1,0]
	v_cvt_scalef32_pk_bf16_fp4 v58, v88, 1.0 op_sel:[1,1,0]
	v_dot2c_f32_bf16_e32 v60, v52, v6
	v_mov_b32_e32 v52, 0
	v_dot2c_f32_bf16_e32 v52, v54, v4
	v_dot2c_f32_bf16_e32 v60, v56, v10
	s_add_i32 s12, s28, -10
	v_dot2c_f32_bf16_e32 v52, v58, v8
	v_cvt_scalef32_pk_bf16_fp4 v54, v89, 1.0
	v_cvt_scalef32_pk_bf16_fp4 v56, v89, 1.0 op_sel:[1,0,0]
	v_cvt_scalef32_pk_bf16_fp4 v58, v89, 1.0 op_sel:[0,1,0]
	v_cvt_scalef32_pk_bf16_fp4 v62, v89, 1.0 op_sel:[1,1,0]
	v_readlane_b32 s12, v46, s12
	v_dot2c_f32_bf16_e32 v60, v54, v14
	v_dot2c_f32_bf16_e32 v52, v56, v12
	s_lshr_b32 s12, s12, 7
	v_dot2c_f32_bf16_e32 v60, v58, v18
	v_dot2c_f32_bf16_e32 v52, v62, v16
	v_cvt_scalef32_pk_bf16_fp4 v54, v90, 1.0
	v_cvt_scalef32_pk_bf16_fp4 v56, v90, 1.0 op_sel:[1,0,0]
	v_cvt_scalef32_pk_bf16_fp4 v58, v90, 1.0 op_sel:[0,1,0]
	v_cvt_scalef32_pk_bf16_fp4 v62, v90, 1.0 op_sel:[1,1,0]
	s_mov_b32 s13, s86
	v_dot2c_f32_bf16_e32 v60, v54, v22
	v_dot2c_f32_bf16_e32 v52, v56, v20
	s_lshl_b64 s[12:13], s[12:13], 10
	v_dot2c_f32_bf16_e32 v60, v58, v26
	v_dot2c_f32_bf16_e32 v52, v62, v24
	v_cvt_scalef32_pk_bf16_fp4 v54, v91, 1.0
	v_cvt_scalef32_pk_bf16_fp4 v56, v91, 1.0 op_sel:[1,0,0]
	v_cvt_scalef32_pk_bf16_fp4 v58, v91, 1.0 op_sel:[0,1,0]
	v_cvt_scalef32_pk_bf16_fp4 v62, v91, 1.0 op_sel:[1,1,0]
	s_nop 0
	v_dot2c_f32_bf16_e32 v60, v54, v30
	v_dot2c_f32_bf16_e32 v52, v56, v28
	s_nop 0
	v_dot2c_f32_bf16_e32 v60, v58, v36
	v_dot2c_f32_bf16_e32 v52, v62, v34
	v_mov_b32_e32 v62, 0
	s_nop 2
	v_add_f32_e32 v52, v60, v52
	s_add_u32 s12, s12, s100
	s_addc_u32 s13, s13, s101
	global_load_dwordx4 v[88:91], v207, s[12:13]
	s_waitcnt vmcnt(15)
; #define P4_FOR16(M) M(0) M(1) M(2) M(3) M(4) M(5) M(6) M(7) M(8) M(9) M(10) M(11) M(12) M(13) M(14) M(15)
; #define P4_U(i) { P4_DOT(b##i, part[i]); const int nk_ = __builtin_amdgcn_readlane(ksel, nb + i); P4_LOAD(b##i, Ug, nk_); }
; #define P4_U(i) { P4_DOT(b##i, part[i]); const int nk_ = __builtin_amdgcn_readlane(kn, i); P4_LOAD(b##i, nbase, nk_); }
; __device__ __forceinline__ void peer_gather_f4p(const float* X, const int* __restrict__ IDX, const float* __restrict__ G, ...
;     ...
; #pragma unroll 1
;         for (int bt = 0; bt < 7; ++bt) {
;             const int ksel = (bt + 1 < 4) ? k0 : k1;
;             const int nb = (16 * (bt + 1)) & 63;
;     ...
;             P4_FOR16(P4_U)
	v_cvt_scalef32_pk_bf16_fp4 v54, v92, 1.0
	v_cvt_scalef32_pk_bf16_fp4 v56, v92, 1.0 op_sel:[1,0,0]
	v_cvt_scalef32_pk_bf16_fp4 v58, v92, 1.0 op_sel:[0,1,0]
	v_cvt_scalef32_pk_bf16_fp4 v60, v92, 1.0 op_sel:[1,1,0]
	s_add_i32 s12, s28, -9
	v_dot2c_f32_bf16_e32 v62, v54, v6
	v_mov_b32_e32 v54, 0
	v_dot2c_f32_bf16_e32 v54, v56, v4
	v_dot2c_f32_bf16_e32 v62, v58, v10
	v_readlane_b32 s12, v46, s12
	v_dot2c_f32_bf16_e32 v54, v60, v8
	v_cvt_scalef32_pk_bf16_fp4 v56, v93, 1.0
	v_cvt_scalef32_pk_bf16_fp4 v58, v93, 1.0 op_sel:[1,0,0]
	v_cvt_scalef32_pk_bf16_fp4 v60, v93, 1.0 op_sel:[0,1,0]
	v_cvt_scalef32_pk_bf16_fp4 v80, v93, 1.0 op_sel:[1,1,0]
	s_lshr_b32 s12, s12, 7
	v_dot2c_f32_bf16_e32 v62, v56, v14
	v_dot2c_f32_bf16_e32 v54, v58, v12
	s_mov_b32 s13, s86
	v_dot2c_f32_bf16_e32 v62, v60, v18
	v_dot2c_f32_bf16_e32 v54, v80, v16
	v_cvt_scalef32_pk_bf16_fp4 v56, v94, 1.0
	v_cvt_scalef32_pk_bf16_fp4 v58, v94, 1.0 op_sel:[1,0,0]
	v_cvt_scalef32_pk_bf16_fp4 v60, v94, 1.0 op_sel:[0,1,0]
	v_cvt_scalef32_pk_bf16_fp4 v80, v94, 1.0 op_sel:[1,1,0]
	s_lshl_b64 s[12:13], s[12:13], 10
	v_dot2c_f32_bf16_e32 v62, v56, v22
	v_dot2c_f32_bf16_e32 v54, v58, v20
	s_nop 0
	v_dot2c_f32_bf16_e32 v62, v60, v26
	v_dot2c_f32_bf16_e32 v54, v80, v24
	v_cvt_scalef32_pk_bf16_fp4 v56, v95, 1.0
	v_cvt_scalef32_pk_bf16_fp4 v58, v95, 1.0 op_sel:[1,0,0]
	v_cvt_scalef32_pk_bf16_fp4 v60, v95, 1.0 op_sel:[0,1,0]
	v_cvt_scalef32_pk_bf16_fp4 v80, v95, 1.0 op_sel:[1,1,0]
	s_nop 0
	v_dot2c_f32_bf16_e32 v62, v56, v30
	v_dot2c_f32_bf16_e32 v54, v58, v28
	s_nop 0
	v_dot2c_f32_bf16_e32 v62, v60, v36
	v_dot2c_f32_bf16_e32 v54, v80, v34
	s_nop 0
	s_nop 2
	v_add_f32_e32 v53, v62, v54
	s_add_u32 s12, s12, s100
	s_addc_u32 s13, s13, s101
	global_load_dwordx4 v[92:95], v207, s[12:13]
	s_waitcnt vmcnt(15)
	v_cvt_scalef32_pk_bf16_fp4 v54, v96, 1.0
	v_mov_b32_e32 v62, 0
	v_cvt_scalef32_pk_bf16_fp4 v56, v96, 1.0 op_sel:[1,0,0]
	v_cvt_scalef32_pk_bf16_fp4 v58, v96, 1.0 op_sel:[0,1,0]
	v_cvt_scalef32_pk_bf16_fp4 v60, v96, 1.0 op_sel:[1,1,0]
	v_dot2c_f32_bf16_e32 v62, v54, v6
	v_mov_b32_e32 v54, 0
	v_dot2c_f32_bf16_e32 v54, v56, v4
	v_dot2c_f32_bf16_e32 v62, v58, v10
	s_add_i32 s12, s28, -8
	v_dot2c_f32_bf16_e32 v54, v60, v8
	v_cvt_scalef32_pk_bf16_fp4 v56, v97, 1.0
	v_cvt_scalef32_pk_bf16_fp4 v58, v97, 1.0 op_sel:[1,0,0]
	v_cvt_scalef32_pk_bf16_fp4 v60, v97, 1.0 op_sel:[0,1,0]
	v_cvt_scalef32_pk_bf16_fp4 v80, v97, 1.0 op_sel:[1,1,0]
	v_readlane_b32 s12, v46, s12
	v_dot2c_f32_bf16_e32 v62, v56, v14
	v_dot2c_f32_bf16_e32 v54, v58, v12
	s_lshr_b32 s12, s12, 7
	v_dot2c_f32_bf16_e32 v62, v60, v18
	v_dot2c_f32_bf16_e32 v54, v80, v16
	v_cvt_scalef32_pk_bf16_fp4 v56, v98, 1.0
	v_cvt_scalef32_pk_bf16_fp4 v58, v98, 1.0 op_sel:[1,0,0]
	v_cvt_scalef32_pk_bf16_fp4 v60, v98, 1.0 op_sel:[0,1,0]
	v_cvt_scalef32_pk_bf16_fp4 v80, v98, 1.0 op_sel:[1,1,0]
	s_mov_b32 s13, s86
	v_dot2c_f32_bf16_e32 v62, v56, v22
	v_dot2c_f32_bf16_e32 v54, v58, v20
	s_lshl_b64 s[12:13], s[12:13], 10
	v_dot2c_f32_bf16_e32 v62, v60, v26
	v_dot2c_f32_bf16_e32 v54, v80, v24
	v_cvt_scalef32_pk_bf16_fp4 v56, v99, 1.0
	v_cvt_scalef32_pk_bf16_fp4 v58, v99, 1.0 op_sel:[1,0,0]
	v_cvt_scalef32_pk_bf16_fp4 v60, v99, 1.0 op_sel:[0,1,0]
	v_cvt_scalef32_pk_bf16_fp4 v80, v99, 1.0 op_sel:[1,1,0]
	s_nop 0
	v_dot2c_f32_bf16_e32 v62, v56, v30
	v_dot2c_f32_bf16_e32 v54, v58, v28
	s_nop 0
	v_dot2c_f32_bf16_e32 v62, v60, v36
	v_dot2c_f32_bf16_e32 v54, v80, v34
	v_mov_b32_e32 v80, 0
	s_nop 2
	v_add_f32_e32 v54, v62, v54
	s_add_u32 s12, s12, s100
	s_addc_u32 s13, s13, s101
	global_load_dwordx4 v[96:99], v207, s[12:13]
	s_waitcnt vmcnt(15)
	v_cvt_scalef32_pk_bf16_fp4 v56, v100, 1.0
	v_cvt_scalef32_pk_bf16_fp4 v58, v100, 1.0 op_sel:[1,0,0]
	v_cvt_scalef32_pk_bf16_fp4 v60, v100, 1.0 op_sel:[0,1,0]
	v_cvt_scalef32_pk_bf16_fp4 v62, v100, 1.0 op_sel:[1,1,0]
	s_add_i32 s12, s28, -7
	v_dot2c_f32_bf16_e32 v80, v56, v6
	v_mov_b32_e32 v56, 0
	v_dot2c_f32_bf16_e32 v56, v58, v4
	v_dot2c_f32_bf16_e32 v80, v60, v10
	v_readlane_b32 s12, v46, s12
	v_dot2c_f32_bf16_e32 v56, v62, v8
	v_cvt_scalef32_pk_bf16_fp4 v58, v101, 1.0
	v_cvt_scalef32_pk_bf16_fp4 v60, v101, 1.0 op_sel:[1,0,0]
	v_cvt_scalef32_pk_bf16_fp4 v62, v101, 1.0 op_sel:[0,1,0]
	v_cvt_scalef32_pk_bf16_fp4 v82, v101, 1.0 op_sel:[1,1,0]
	s_lshr_b32 s12, s12, 7
	v_dot2c_f32_bf16_e32 v80, v58, v14
	v_dot2c_f32_bf16_e32 v56, v60, v12
	s_mov_b32 s13, s86
	v_dot2c_f32_bf16_e32 v80, v62, v18
	v_dot2c_f32_bf16_e32 v56, v82, v16
	v_cvt_scalef32_pk_bf16_fp4 v58, v102, 1.0
	v_cvt_scalef32_pk_bf16_fp4 v60, v102, 1.0 op_sel:[1,0,0]
	v_cvt_scalef32_pk_bf16_fp4 v62, v102, 1.0 op_sel:[0,1,0]
	v_cvt_scalef32_pk_bf16_fp4 v82, v102, 1.0 op_sel:[1,1,0]
	s_lshl_b64 s[12:13], s[12:13], 10
	v_dot2c_f32_bf16_e32 v80, v58, v22
	v_dot2c_f32_bf16_e32 v56, v60, v20
	s_nop 0
	v_dot2c_f32_bf16_e32 v80, v62, v26
	v_dot2c_f32_bf16_e32 v56, v82, v24
	v_cvt_scalef32_pk_bf16_fp4 v58, v103, 1.0
	v_cvt_scalef32_pk_bf16_fp4 v60, v103, 1.0 op_sel:[1,0,0]
	v_cvt_scalef32_pk_bf16_fp4 v62, v103, 1.0 op_sel:[0,1,0]
	v_cvt_scalef32_pk_bf16_fp4 v82, v103, 1.0 op_sel:[1,1,0]
	s_nop 0
	v_dot2c_f32_bf16_e32 v80, v58, v30
	v_dot2c_f32_bf16_e32 v56, v60, v28
	s_nop 0
	v_dot2c_f32_bf16_e32 v80, v62, v36
	v_dot2c_f32_bf16_e32 v56, v82, v34
	s_nop 0
	s_nop 2
	v_add_f32_e32 v55, v80, v56
	s_add_u32 s12, s12, s100
	s_addc_u32 s13, s13, s101
	global_load_dwordx4 v[100:103], v207, s[12:13]
	s_waitcnt vmcnt(15)
; #define P4_FOR16(M) M(0) M(1) M(2) M(3) M(4) M(5) M(6) M(7) M(8) M(9) M(10) M(11) M(12) M(13) M(14) M(15)
; #define P4_U(i) { P4_DOT(b##i, part[i]); const int nk_ = __builtin_amdgcn_readlane(ksel, nb + i); P4_LOAD(b##i, Ug, nk_); }
; #define P4_U(i) { P4_DOT(b##i, part[i]); const int nk_ = __builtin_amdgcn_readlane(kn, i); P4_LOAD(b##i, nbase, nk_); }
; __device__ __forceinline__ void peer_gather_f4p(const float* X, const int* __restrict__ IDX, const float* __restrict__ G, ...
;     ...
; #pragma unroll 1
;         for (int bt = 0; bt < 7; ++bt) {
;             const int ksel = (bt + 1 < 4) ? k0 : k1;
;             const int nb = (16 * (bt + 1)) & 63;
;     ...
;             P4_FOR16(P4_U)
	v_cvt_scalef32_pk_bf16_fp4 v56, v104, 1.0
	v_mov_b32_e32 v80, 0
	v_cvt_scalef32_pk_bf16_fp4 v58, v104, 1.0 op_sel:[1,0,0]
	v_cvt_scalef32_pk_bf16_fp4 v60, v104, 1.0 op_sel:[0,1,0]
	v_cvt_scalef32_pk_bf16_fp4 v62, v104, 1.0 op_sel:[1,1,0]
	v_dot2c_f32_bf16_e32 v80, v56, v6
	v_mov_b32_e32 v56, 0
	v_dot2c_f32_bf16_e32 v56, v58, v4
	v_dot2c_f32_bf16_e32 v80, v60, v10
	s_add_i32 s12, s28, -6
	v_dot2c_f32_bf16_e32 v56, v62, v8
	v_cvt_scalef32_pk_bf16_fp4 v58, v105, 1.0
	v_cvt_scalef32_pk_bf16_fp4 v60, v105, 1.0 op_sel:[1,0,0]
	v_cvt_scalef32_pk_bf16_fp4 v62, v105, 1.0 op_sel:[0,1,0]
	v_cvt_scalef32_pk_bf16_fp4 v82, v105, 1.0 op_sel:[1,1,0]
	v_readlane_b32 s12, v46, s12
	v_dot2c_f32_bf16_e32 v80, v58, v14
	v_dot2c_f32_bf16_e32 v56, v60, v12
	s_lshr_b32 s12, s12, 7
	v_dot2c_f32_bf16_e32 v80, v62, v18
	v_dot2c_f32_bf16_e32 v56, v82, v16
	v_cvt_scalef32_pk_bf16_fp4 v58, v106, 1.0
	v_cvt_scalef32_pk_bf16_fp4 v60, v106, 1.0 op_sel:[1,0,0]
	v_cvt_scalef32_pk_bf16_fp4 v62, v106, 1.0 op_sel:[0,1,0]
	v_cvt_scalef32_pk_bf16_fp4 v82, v106, 1.0 op_sel:[1,1,0]
	s_mov_b32 s13, s86
	v_dot2c_f32_bf16_e32 v80, v58, v22
	v_dot2c_f32_bf16_e32 v56, v60, v20
	s_lshl_b64 s[12:13], s[12:13], 10
	v_dot2c_f32_bf16_e32 v80, v62, v26
	v_dot2c_f32_bf16_e32 v56, v82, v24
	v_cvt_scalef32_pk_bf16_fp4 v58, v107, 1.0
	v_cvt_scalef32_pk_bf16_fp4 v60, v107, 1.0 op_sel:[1,0,0]
	v_cvt_scalef32_pk_bf16_fp4 v62, v107, 1.0 op_sel:[0,1,0]
	v_cvt_scalef32_pk_bf16_fp4 v82, v107, 1.0 op_sel:[1,1,0]
	s_nop 0
	v_dot2c_f32_bf16_e32 v80, v58, v30
	v_dot2c_f32_bf16_e32 v56, v60, v28
	s_nop 0
	v_dot2c_f32_bf16_e32 v80, v62, v36
	v_dot2c_f32_bf16_e32 v56, v82, v34
	v_mov_b32_e32 v82, 0
	s_nop 2
	v_add_f32_e32 v56, v80, v56
	s_add_u32 s12, s12, s100
	s_addc_u32 s13, s13, s101
	global_load_dwordx4 v[104:107], v207, s[12:13]
	s_waitcnt vmcnt(15)
	v_cvt_scalef32_pk_bf16_fp4 v58, v108, 1.0
	v_cvt_scalef32_pk_bf16_fp4 v60, v108, 1.0 op_sel:[1,0,0]
	v_cvt_scalef32_pk_bf16_fp4 v62, v108, 1.0 op_sel:[0,1,0]
	v_cvt_scalef32_pk_bf16_fp4 v80, v108, 1.0 op_sel:[1,1,0]
	s_add_i32 s12, s28, -5
	v_dot2c_f32_bf16_e32 v82, v58, v6
	v_mov_b32_e32 v58, 0
	v_dot2c_f32_bf16_e32 v58, v60, v4
	v_dot2c_f32_bf16_e32 v82, v62, v10
	v_readlane_b32 s12, v46, s12
	v_dot2c_f32_bf16_e32 v58, v80, v8
	v_cvt_scalef32_pk_bf16_fp4 v60, v109, 1.0
	v_cvt_scalef32_pk_bf16_fp4 v62, v109, 1.0 op_sel:[1,0,0]
	v_cvt_scalef32_pk_bf16_fp4 v80, v109, 1.0 op_sel:[0,1,0]
	v_cvt_scalef32_pk_bf16_fp4 v108, v109, 1.0 op_sel:[1,1,0]
	s_lshr_b32 s12, s12, 7
	v_dot2c_f32_bf16_e32 v82, v60, v14
	v_dot2c_f32_bf16_e32 v58, v62, v12
	s_mov_b32 s13, s86
	v_dot2c_f32_bf16_e32 v82, v80, v18
	v_dot2c_f32_bf16_e32 v58, v108, v16
	v_cvt_scalef32_pk_bf16_fp4 v60, v110, 1.0
	v_cvt_scalef32_pk_bf16_fp4 v62, v110, 1.0 op_sel:[1,0,0]
	v_cvt_scalef32_pk_bf16_fp4 v80, v110, 1.0 op_sel:[0,1,0]
	v_cvt_scalef32_pk_bf16_fp4 v108, v110, 1.0 op_sel:[1,1,0]
	s_lshl_b64 s[12:13], s[12:13], 10
	v_dot2c_f32_bf16_e32 v82, v60, v22
	v_dot2c_f32_bf16_e32 v58, v62, v20
	s_nop 0
	v_dot2c_f32_bf16_e32 v82, v80, v26
	v_dot2c_f32_bf16_e32 v58, v108, v24
	v_cvt_scalef32_pk_bf16_fp4 v60, v111, 1.0
	v_cvt_scalef32_pk_bf16_fp4 v62, v111, 1.0 op_sel:[1,0,0]
	v_cvt_scalef32_pk_bf16_fp4 v80, v111, 1.0 op_sel:[0,1,0]
	v_cvt_scalef32_pk_bf16_fp4 v108, v111, 1.0 op_sel:[1,1,0]
	s_nop 0
	v_dot2c_f32_bf16_e32 v82, v60, v30
	v_dot2c_f32_bf16_e32 v58, v62, v28
	s_nop 0
	v_dot2c_f32_bf16_e32 v82, v80, v36
	v_dot2c_f32_bf16_e32 v58, v108, v34
	s_nop 0
	s_nop 2
	v_add_f32_e32 v57, v82, v58
	s_add_u32 s12, s12, s100
	s_addc_u32 s13, s13, s101
	global_load_dwordx4 v[108:111], v207, s[12:13]
	s_waitcnt vmcnt(15)
	v_cvt_scalef32_pk_bf16_fp4 v58, v112, 1.0
	v_mov_b32_e32 v82, 0
	v_cvt_scalef32_pk_bf16_fp4 v60, v112, 1.0 op_sel:[1,0,0]
	v_cvt_scalef32_pk_bf16_fp4 v62, v112, 1.0 op_sel:[0,1,0]
	v_cvt_scalef32_pk_bf16_fp4 v80, v112, 1.0 op_sel:[1,1,0]
	v_dot2c_f32_bf16_e32 v82, v58, v6
	v_mov_b32_e32 v58, 0
	v_dot2c_f32_bf16_e32 v58, v60, v4
	v_dot2c_f32_bf16_e32 v82, v62, v10
	s_add_i32 s12, s28, -4
	v_dot2c_f32_bf16_e32 v58, v80, v8
	v_cvt_scalef32_pk_bf16_fp4 v60, v113, 1.0
	v_cvt_scalef32_pk_bf16_fp4 v62, v113, 1.0 op_sel:[1,0,0]
	v_cvt_scalef32_pk_bf16_fp4 v80, v113, 1.0 op_sel:[0,1,0]
	v_cvt_scalef32_pk_bf16_fp4 v112, v113, 1.0 op_sel:[1,1,0]
	v_readlane_b32 s12, v46, s12
	v_dot2c_f32_bf16_e32 v82, v60, v14
	v_dot2c_f32_bf16_e32 v58, v62, v12
	s_lshr_b32 s12, s12, 7
	v_dot2c_f32_bf16_e32 v82, v80, v18
	v_dot2c_f32_bf16_e32 v58, v112, v16
	v_cvt_scalef32_pk_bf16_fp4 v60, v114, 1.0
	v_cvt_scalef32_pk_bf16_fp4 v62, v114, 1.0 op_sel:[1,0,0]
	v_cvt_scalef32_pk_bf16_fp4 v80, v114, 1.0 op_sel:[0,1,0]
	v_cvt_scalef32_pk_bf16_fp4 v112, v114, 1.0 op_sel:[1,1,0]
	s_mov_b32 s13, s86
	v_dot2c_f32_bf16_e32 v82, v60, v22
	v_dot2c_f32_bf16_e32 v58, v62, v20
	s_lshl_b64 s[12:13], s[12:13], 10
	v_dot2c_f32_bf16_e32 v82, v80, v26
	v_dot2c_f32_bf16_e32 v58, v112, v24
	v_cvt_scalef32_pk_bf16_fp4 v60, v115, 1.0
	v_cvt_scalef32_pk_bf16_fp4 v62, v115, 1.0 op_sel:[1,0,0]
	v_cvt_scalef32_pk_bf16_fp4 v80, v115, 1.0 op_sel:[0,1,0]
	v_cvt_scalef32_pk_bf16_fp4 v112, v115, 1.0 op_sel:[1,1,0]
	s_nop 0
	v_dot2c_f32_bf16_e32 v82, v60, v30
	v_dot2c_f32_bf16_e32 v58, v62, v28
	s_nop 0
	v_dot2c_f32_bf16_e32 v82, v80, v36
	v_dot2c_f32_bf16_e32 v58, v112, v34
	s_nop 0
	s_nop 2
	v_add_f32_e32 v132, v82, v58
	s_add_u32 s12, s12, s100
	s_addc_u32 s13, s13, s101
	global_load_dwordx4 v[112:115], v207, s[12:13]
	s_waitcnt vmcnt(15)
; #define P4_FOR16(M) M(0) M(1) M(2) M(3) M(4) M(5) M(6) M(7) M(8) M(9) M(10) M(11) M(12) M(13) M(14) M(15)
; #define P4_U(i) { P4_DOT(b##i, part[i]); const int nk_ = __builtin_amdgcn_readlane(ksel, nb + i); P4_LOAD(b##i, Ug, nk_); }
; #define P4_U(i) { P4_DOT(b##i, part[i]); const int nk_ = __builtin_amdgcn_readlane(kn, i); P4_LOAD(b##i, nbase, nk_); }
; __device__ __forceinline__ void peer_gather_f4p(const float* X, const int* __restrict__ IDX, const float* __restrict__ G, ...
;     ...
; #pragma unroll 1
;         for (int bt = 0; bt < 7; ++bt) {
;             const int ksel = (bt + 1 < 4) ? k0 : k1;
;             const int nb = (16 * (bt + 1)) & 63;
;     ...
;             P4_FOR16(P4_U)
	v_cvt_scalef32_pk_bf16_fp4 v58, v116, 1.0
	v_mov_b32_e32 v82, 0
	v_cvt_scalef32_pk_bf16_fp4 v60, v116, 1.0 op_sel:[1,0,0]
	v_cvt_scalef32_pk_bf16_fp4 v62, v116, 1.0 op_sel:[0,1,0]
	v_cvt_scalef32_pk_bf16_fp4 v80, v116, 1.0 op_sel:[1,1,0]
	v_dot2c_f32_bf16_e32 v82, v58, v6
	v_mov_b32_e32 v58, 0
	v_dot2c_f32_bf16_e32 v58, v60, v4
	v_dot2c_f32_bf16_e32 v82, v62, v10
	s_add_i32 s12, s28, -3
	v_dot2c_f32_bf16_e32 v58, v80, v8
	v_cvt_scalef32_pk_bf16_fp4 v60, v117, 1.0
	v_cvt_scalef32_pk_bf16_fp4 v62, v117, 1.0 op_sel:[1,0,0]
	v_cvt_scalef32_pk_bf16_fp4 v80, v117, 1.0 op_sel:[0,1,0]
	v_cvt_scalef32_pk_bf16_fp4 v116, v117, 1.0 op_sel:[1,1,0]
	v_readlane_b32 s12, v46, s12
	v_dot2c_f32_bf16_e32 v82, v60, v14
	v_dot2c_f32_bf16_e32 v58, v62, v12
	s_lshr_b32 s12, s12, 7
	v_dot2c_f32_bf16_e32 v82, v80, v18
	v_dot2c_f32_bf16_e32 v58, v116, v16
	v_cvt_scalef32_pk_bf16_fp4 v60, v118, 1.0
	v_cvt_scalef32_pk_bf16_fp4 v62, v118, 1.0 op_sel:[1,0,0]
	v_cvt_scalef32_pk_bf16_fp4 v80, v118, 1.0 op_sel:[0,1,0]
	v_cvt_scalef32_pk_bf16_fp4 v116, v118, 1.0 op_sel:[1,1,0]
	s_mov_b32 s13, s86
	v_dot2c_f32_bf16_e32 v82, v60, v22
	v_dot2c_f32_bf16_e32 v58, v62, v20
	s_lshl_b64 s[12:13], s[12:13], 10
	v_dot2c_f32_bf16_e32 v82, v80, v26
	v_dot2c_f32_bf16_e32 v58, v116, v24
	v_cvt_scalef32_pk_bf16_fp4 v60, v119, 1.0
	v_cvt_scalef32_pk_bf16_fp4 v62, v119, 1.0 op_sel:[1,0,0]
	v_cvt_scalef32_pk_bf16_fp4 v80, v119, 1.0 op_sel:[0,1,0]
	v_cvt_scalef32_pk_bf16_fp4 v116, v119, 1.0 op_sel:[1,1,0]
	s_nop 0
	v_dot2c_f32_bf16_e32 v82, v60, v30
	v_dot2c_f32_bf16_e32 v58, v62, v28
	s_nop 0
	v_dot2c_f32_bf16_e32 v82, v80, v36
	v_dot2c_f32_bf16_e32 v58, v116, v34
	s_nop 0
	s_nop 2
	v_add_f32_e32 v133, v82, v58
	s_add_u32 s12, s12, s100
	s_addc_u32 s13, s13, s101
	global_load_dwordx4 v[116:119], v207, s[12:13]
	s_waitcnt vmcnt(15)
	v_cvt_scalef32_pk_bf16_fp4 v58, v120, 1.0
	v_mov_b32_e32 v82, 0
	v_cvt_scalef32_pk_bf16_fp4 v60, v120, 1.0 op_sel:[1,0,0]
	v_cvt_scalef32_pk_bf16_fp4 v62, v120, 1.0 op_sel:[0,1,0]
	v_cvt_scalef32_pk_bf16_fp4 v80, v120, 1.0 op_sel:[1,1,0]
	v_dot2c_f32_bf16_e32 v82, v58, v6
	v_mov_b32_e32 v58, 0
	v_dot2c_f32_bf16_e32 v58, v60, v4
	v_dot2c_f32_bf16_e32 v82, v62, v10
	s_add_i32 s12, s28, -2
	v_dot2c_f32_bf16_e32 v58, v80, v8
	v_cvt_scalef32_pk_bf16_fp4 v60, v121, 1.0
	v_cvt_scalef32_pk_bf16_fp4 v62, v121, 1.0 op_sel:[1,0,0]
	v_cvt_scalef32_pk_bf16_fp4 v80, v121, 1.0 op_sel:[0,1,0]
	v_cvt_scalef32_pk_bf16_fp4 v120, v121, 1.0 op_sel:[1,1,0]
	v_readlane_b32 s12, v46, s12
	v_dot2c_f32_bf16_e32 v82, v60, v14
	v_dot2c_f32_bf16_e32 v58, v62, v12
	s_lshr_b32 s12, s12, 7
	v_dot2c_f32_bf16_e32 v82, v80, v18
	v_dot2c_f32_bf16_e32 v58, v120, v16
	v_cvt_scalef32_pk_bf16_fp4 v60, v122, 1.0
	v_cvt_scalef32_pk_bf16_fp4 v62, v122, 1.0 op_sel:[1,0,0]
	v_cvt_scalef32_pk_bf16_fp4 v80, v122, 1.0 op_sel:[0,1,0]
	v_cvt_scalef32_pk_bf16_fp4 v120, v122, 1.0 op_sel:[1,1,0]
	s_mov_b32 s13, s86
	v_dot2c_f32_bf16_e32 v82, v60, v22
	v_dot2c_f32_bf16_e32 v58, v62, v20
	s_lshl_b64 s[12:13], s[12:13], 10
	v_dot2c_f32_bf16_e32 v82, v80, v26
	v_dot2c_f32_bf16_e32 v58, v120, v24
	v_cvt_scalef32_pk_bf16_fp4 v60, v123, 1.0
	v_cvt_scalef32_pk_bf16_fp4 v62, v123, 1.0 op_sel:[1,0,0]
	v_cvt_scalef32_pk_bf16_fp4 v80, v123, 1.0 op_sel:[0,1,0]
	v_cvt_scalef32_pk_bf16_fp4 v120, v123, 1.0 op_sel:[1,1,0]
	s_nop 0
	v_dot2c_f32_bf16_e32 v82, v60, v30
	v_dot2c_f32_bf16_e32 v58, v62, v28
	s_nop 0
	v_dot2c_f32_bf16_e32 v82, v80, v36
	v_dot2c_f32_bf16_e32 v58, v120, v34
	s_nop 0
	s_nop 2
	v_add_f32_e32 v134, v82, v58
	s_add_u32 s12, s12, s100
	s_addc_u32 s13, s13, s101
	global_load_dwordx4 v[120:123], v207, s[12:13]
	s_waitcnt vmcnt(15)
	v_cvt_scalef32_pk_bf16_fp4 v58, v124, 1.0
	v_mov_b32_e32 v82, 0
	v_cvt_scalef32_pk_bf16_fp4 v60, v124, 1.0 op_sel:[1,0,0]
	v_cvt_scalef32_pk_bf16_fp4 v62, v124, 1.0 op_sel:[0,1,0]
	v_cvt_scalef32_pk_bf16_fp4 v80, v124, 1.0 op_sel:[1,1,0]
	v_dot2c_f32_bf16_e32 v82, v58, v6
	v_mov_b32_e32 v58, 0
	v_dot2c_f32_bf16_e32 v58, v60, v4
	v_dot2c_f32_bf16_e32 v82, v62, v10
	s_add_i32 s12, s28, -1
	v_dot2c_f32_bf16_e32 v58, v80, v8
	v_cvt_scalef32_pk_bf16_fp4 v60, v125, 1.0
	v_cvt_scalef32_pk_bf16_fp4 v62, v125, 1.0 op_sel:[1,0,0]
	v_cvt_scalef32_pk_bf16_fp4 v80, v125, 1.0 op_sel:[0,1,0]
	v_cvt_scalef32_pk_bf16_fp4 v124, v125, 1.0 op_sel:[1,1,0]
	v_readlane_b32 s12, v46, s12
	v_dot2c_f32_bf16_e32 v82, v60, v14
	v_dot2c_f32_bf16_e32 v58, v62, v12
	s_lshr_b32 s12, s12, 7
	v_dot2c_f32_bf16_e32 v82, v80, v18
	v_dot2c_f32_bf16_e32 v58, v124, v16
	v_cvt_scalef32_pk_bf16_fp4 v60, v126, 1.0
	v_cvt_scalef32_pk_bf16_fp4 v62, v126, 1.0 op_sel:[1,0,0]
	v_cvt_scalef32_pk_bf16_fp4 v80, v126, 1.0 op_sel:[0,1,0]
	v_cvt_scalef32_pk_bf16_fp4 v124, v126, 1.0 op_sel:[1,1,0]
	s_mov_b32 s13, s86
	v_dot2c_f32_bf16_e32 v82, v60, v22
	v_dot2c_f32_bf16_e32 v58, v62, v20
	s_lshl_b64 s[12:13], s[12:13], 10
	v_dot2c_f32_bf16_e32 v82, v80, v26
	v_dot2c_f32_bf16_e32 v58, v124, v24
	v_cvt_scalef32_pk_bf16_fp4 v60, v127, 1.0
	v_cvt_scalef32_pk_bf16_fp4 v62, v127, 1.0 op_sel:[1,0,0]
	v_cvt_scalef32_pk_bf16_fp4 v80, v127, 1.0 op_sel:[0,1,0]
	v_cvt_scalef32_pk_bf16_fp4 v124, v127, 1.0 op_sel:[1,1,0]
	s_nop 0
	v_dot2c_f32_bf16_e32 v82, v60, v30
	v_dot2c_f32_bf16_e32 v58, v62, v28
	s_nop 0
	v_dot2c_f32_bf16_e32 v82, v80, v36
	v_dot2c_f32_bf16_e32 v58, v124, v34
	s_nop 0
	s_nop 2
	v_add_f32_e32 v135, v82, v58
	v_lshl_add_u64 v[58:59], v[40:41], 0, s[12:13]
	v_mov_b32_e32 v82, 0
	global_load_dwordx4 v[124:127], v[58:59], off
	s_waitcnt vmcnt(15)
; __device__ __forceinline__ float gelu_tanh(float h) {
;     return 0.5f * h * (1.f + tanhf(0.7978845608028654f * (h + 0.044715f * h * h * h)));
; }
	v_cvt_scalef32_pk_bf16_fp4 v58, v128, 1.0
	v_cvt_scalef32_pk_bf16_fp4 v60, v128, 1.0 op_sel:[1,0,0]
	v_cvt_scalef32_pk_bf16_fp4 v62, v128, 1.0 op_sel:[0,1,0]
	v_cvt_scalef32_pk_bf16_fp4 v80, v128, 1.0 op_sel:[1,1,0]
	v_readlane_b32 s12, v46, s28
	v_dot2c_f32_bf16_e32 v82, v58, v6
	v_dot2c_f32_bf16_e32 v42, v60, v4
	s_lshr_b32 s12, s12, 7
	v_dot2c_f32_bf16_e32 v82, v62, v10
	v_dot2c_f32_bf16_e32 v42, v80, v8
	v_cvt_scalef32_pk_bf16_fp4 v58, v129, 1.0
	v_cvt_scalef32_pk_bf16_fp4 v60, v129, 1.0 op_sel:[1,0,0]
	v_cvt_scalef32_pk_bf16_fp4 v62, v129, 1.0 op_sel:[0,1,0]
	v_cvt_scalef32_pk_bf16_fp4 v80, v129, 1.0 op_sel:[1,1,0]
	s_mov_b32 s13, s86
	v_dot2c_f32_bf16_e32 v82, v58, v14
	v_dot2c_f32_bf16_e32 v42, v60, v12
	s_lshl_b64 s[12:13], s[12:13], 10
	v_dot2c_f32_bf16_e32 v82, v62, v18
	v_dot2c_f32_bf16_e32 v42, v80, v16
	v_cvt_scalef32_pk_bf16_fp4 v58, v130, 1.0
	v_cvt_scalef32_pk_bf16_fp4 v60, v130, 1.0 op_sel:[1,0,0]
	v_cvt_scalef32_pk_bf16_fp4 v62, v130, 1.0 op_sel:[0,1,0]
	v_cvt_scalef32_pk_bf16_fp4 v80, v130, 1.0 op_sel:[1,1,0]
	v_cndmask_b32_e64 v46, v48, v56, s[46:47]
	v_dot2c_f32_bf16_e32 v82, v58, v22
	v_dot2c_f32_bf16_e32 v42, v60, v20
	ds_swizzle_b32 v46, v46 offset:swizzle(SWAP,8)
	v_dot2c_f32_bf16_e32 v82, v62, v26
	v_dot2c_f32_bf16_e32 v42, v80, v24
	v_cvt_scalef32_pk_bf16_fp4 v58, v131, 1.0
	v_cvt_scalef32_pk_bf16_fp4 v60, v131, 1.0 op_sel:[1,0,0]
	v_cvt_scalef32_pk_bf16_fp4 v62, v131, 1.0 op_sel:[0,1,0]
	v_cvt_scalef32_pk_bf16_fp4 v80, v131, 1.0 op_sel:[1,1,0]
	s_nop 0
	v_dot2c_f32_bf16_e32 v82, v58, v30
	v_dot2c_f32_bf16_e32 v42, v60, v28
	s_nop 0
	v_dot2c_f32_bf16_e32 v82, v62, v36
	v_dot2c_f32_bf16_e32 v42, v80, v34
	s_nop 0
	s_nop 2
	v_add_f32_e32 v58, v82, v42
	v_lshl_add_u64 v[42:43], v[40:41], 0, s[12:13]
	global_load_dwordx4 v[128:131], v[42:43], off
	v_cndmask_b32_e64 v43, v47, v55, s[46:47]
	ds_swizzle_b32 v43, v43 offset:swizzle(SWAP,8)
	v_cndmask_b32_e64 v42, v55, v47, s[46:47]
	v_cndmask_b32_e64 v47, v49, v57, s[46:47]
	ds_swizzle_b32 v47, v47 offset:swizzle(SWAP,8)
	s_waitcnt lgkmcnt(1)
	v_add_f32_e32 v42, v42, v43
	v_cndmask_b32_e64 v43, v56, v48, s[46:47]
	v_cndmask_b32_e64 v48, v50, v132, s[46:47]
	v_add_f32_e32 v43, v43, v46
	v_cndmask_b32_e64 v46, v57, v49, s[46:47]
	ds_swizzle_b32 v48, v48 offset:swizzle(SWAP,8)
	v_cndmask_b32_e64 v49, v51, v133, s[46:47]
	ds_swizzle_b32 v49, v49 offset:swizzle(SWAP,8)
	s_waitcnt lgkmcnt(2)
	v_add_f32_e32 v46, v46, v47
	v_cndmask_b32_e64 v47, v132, v50, s[46:47]
	v_cndmask_b32_e64 v50, v52, v134, s[46:47]
	ds_swizzle_b32 v50, v50 offset:swizzle(SWAP,8)
	s_waitcnt lgkmcnt(2)
	v_add_f32_e32 v47, v47, v48
	v_cndmask_b32_e64 v48, v133, v51, s[46:47]
	v_cndmask_b32_e64 v51, v53, v135, s[46:47]
	s_waitcnt lgkmcnt(1)
	v_add_f32_e32 v48, v48, v49
	v_cndmask_b32_e64 v49, v134, v52, s[46:47]
	ds_swizzle_b32 v51, v51 offset:swizzle(SWAP,8)
	v_cndmask_b32_e64 v52, v54, v58, s[46:47]
	ds_swizzle_b32 v52, v52 offset:swizzle(SWAP,8)
	s_waitcnt lgkmcnt(2)
	v_add_f32_e32 v49, v49, v50
	v_cndmask_b32_e64 v50, v135, v53, s[46:47]
	s_waitcnt lgkmcnt(1)
	v_add_f32_e32 v50, v50, v51
	v_cndmask_b32_e64 v51, v58, v54, s[46:47]
	s_waitcnt lgkmcnt(0)
	v_add_f32_e32 v51, v51, v52
	v_cndmask_b32_e64 v53, v42, v48, s[44:45]
	v_cndmask_b32_e64 v42, v48, v42, s[44:45]
	v_cndmask_b32_e64 v48, v49, v43, s[44:45]
	v_cndmask_b32_e64 v43, v43, v49, s[44:45]
	v_cndmask_b32_e64 v49, v46, v50, s[44:45]
	v_cndmask_b32_e64 v52, v47, v51, s[44:45]
	ds_swizzle_b32 v53, v53 offset:swizzle(SWAP,4)
	ds_swizzle_b32 v43, v43 offset:swizzle(SWAP,4)
	ds_swizzle_b32 v49, v49 offset:swizzle(SWAP,4)
	ds_swizzle_b32 v52, v52 offset:swizzle(SWAP,4)
	v_cndmask_b32_e64 v46, v50, v46, s[44:45]
	v_cndmask_b32_e64 v47, v51, v47, s[44:45]
	s_waitcnt lgkmcnt(3)
	v_add_f32_e32 v42, v42, v53
	s_waitcnt lgkmcnt(2)
	v_add_f32_e32 v43, v48, v43
	s_waitcnt lgkmcnt(1)
	v_add_f32_e32 v46, v46, v49
	s_waitcnt lgkmcnt(0)
	v_add_f32_e32 v47, v47, v52
	v_cndmask_b32_e64 v48, v42, v46, s[42:43]
	v_cndmask_b32_e64 v49, v43, v47, s[42:43]
	ds_swizzle_b32 v48, v48 offset:swizzle(SWAP,2)
	ds_swizzle_b32 v49, v49 offset:swizzle(SWAP,2)
	v_cndmask_b32_e64 v42, v46, v42, s[42:43]
	v_cndmask_b32_e64 v43, v47, v43, s[42:43]
	s_waitcnt lgkmcnt(1)
	v_add_f32_e32 v42, v42, v48
	s_waitcnt lgkmcnt(0)
	v_add_f32_e32 v43, v43, v49
	v_cndmask_b32_e64 v46, v42, v43, s[40:41]
	ds_swizzle_b32 v46, v46 offset:swizzle(SWAP,1)
	v_cndmask_b32_e64 v42, v43, v42, s[40:41]
	s_waitcnt lgkmcnt(0)
	v_add_f32_e32 v42, v42, v46
	ds_swizzle_b32 v43, v42 offset:swizzle(SWAP,16)
	s_waitcnt lgkmcnt(0)
	v_add_f32_e32 v46, v42, v43
	ds_read2st64_b32 v[42:43], v45 offset1:8
	v_mov_b32_e32 v47, v46
	s_nop 1
	v_permlane32_swap_b32_e32 v46, v47
	v_add_f32_e32 v46, v46, v47
	s_waitcnt lgkmcnt(0)
	v_mul_f32_e32 v42, v42, v46
	v_mul_f32_e32 v46, 0x3d372713, v42
	v_mul_f32_e32 v46, v42, v46
	v_fma_f32 v46, v42, v46, v42
	v_mul_f32_e32 v46, 0x3f4c422a, v46
	v_cmp_nlt_f32_e64 s[12:13], |v46|, s25
	s_and_saveexec_b64 s[48:49], s[12:13]
	s_xor_b64 s[12:13], exec, s[48:49]
	s_cbranch_execz .LBB0_1233
	v_add_f32_e64 v47, |v46|, |v46|
	v_mul_f32_e32 v48, 0x3fb8aa3b, v47
	v_rndne_f32_e32 v49, v48
	v_sub_f32_e32 v50, v48, v49
	v_fma_f32 v48, v47, s70, -v48
	v_fmac_f32_e32 v48, 0x32a5705f, v47
	v_add_f32_e32 v48, v50, v48
	v_cvt_i32_f32_e32 v49, v49
	v_exp_f32_e32 v48, v48
	v_cmp_ngt_f32_e64 s[48:49], s67, v47
	v_ldexp_f32 v48, v48, v49
	s_nop 0
	v_cndmask_b32_e64 v48, 0, v48, s[48:49]
	v_cmp_nlt_f32_e64 s[48:49], s68, v47
	s_nop 1
	v_cndmask_b32_e64 v47, v205, v48, s[48:49]
	v_add_f32_e32 v47, 1.0, v47
	v_rcp_f32_e32 v47, v47
	s_nop 0
	v_fma_f32 v47, v47, -2.0, 1.0
	s_andn2_saveexec_b64 s[12:13], s[12:13]
	s_cbranch_execnz .LBB0_1234

; #define P4_FOR16(M) M(0) M(1) M(2) M(3) M(4) M(5) M(6) M(7) M(8) M(9) M(10) M(11) M(12) M(13) M(14) M(15)
; #define P4_U(i) { P4_DOT(b##i, part[i]); const int nk_ = __builtin_amdgcn_readlane(ksel, nb + i); P4_LOAD(b##i, Ug, nk_); }
; #define P4_U(i) { P4_DOT(b##i, part[i]); const int nk_ = __builtin_amdgcn_readlane(kn, i); P4_LOAD(b##i, nbase, nk_); }
; __device__ __forceinline__ void peer_gather_f4p(const float* X, const int* __restrict__ IDX, const float* __restrict__ G, ...
;     ...
;         {
;     ...
;             P4_FOR16(P4_U)
.LBB0_1236:
	s_mov_b32 s87, s86
	s_waitcnt vmcnt(15)
	v_cvt_scalef32_pk_bf16_fp4 v42, v64, 1.0
	v_mov_b32_e32 v50, 0
	v_or_b32_e32 v40, s27, v44
	v_cvt_scalef32_pk_bf16_fp4 v44, v64, 1.0 op_sel:[1,0,0]
	v_cvt_scalef32_pk_bf16_fp4 v46, v64, 1.0 op_sel:[0,1,0]
	v_cvt_scalef32_pk_bf16_fp4 v48, v64, 1.0 op_sel:[1,1,0]
	v_dot2c_f32_bf16_e32 v50, v42, v6
	v_mov_b32_e32 v42, 0
	v_dot2c_f32_bf16_e32 v42, v44, v4
	v_dot2c_f32_bf16_e32 v50, v46, v10
	s_cmp_eq_u32 s26, 3
	v_dot2c_f32_bf16_e32 v42, v48, v8
	v_cvt_scalef32_pk_bf16_fp4 v44, v65, 1.0
	v_cvt_scalef32_pk_bf16_fp4 v46, v65, 1.0 op_sel:[1,0,0]
	v_cvt_scalef32_pk_bf16_fp4 v48, v65, 1.0 op_sel:[0,1,0]
	v_cvt_scalef32_pk_bf16_fp4 v52, v65, 1.0 op_sel:[1,1,0]
	v_readlane_b32 s26, v2, 0
	v_dot2c_f32_bf16_e32 v50, v44, v14
	v_dot2c_f32_bf16_e32 v42, v46, v12
	s_cselect_b32 s12, s53, s51
	v_dot2c_f32_bf16_e32 v50, v48, v18
	v_dot2c_f32_bf16_e32 v42, v52, v16
	v_cvt_scalef32_pk_bf16_fp4 v44, v66, 1.0
	v_cvt_scalef32_pk_bf16_fp4 v46, v66, 1.0 op_sel:[1,0,0]
	v_cvt_scalef32_pk_bf16_fp4 v48, v66, 1.0 op_sel:[0,1,0]
	v_cvt_scalef32_pk_bf16_fp4 v52, v66, 1.0 op_sel:[1,1,0]
	s_cselect_b32 s13, s52, s50
	v_dot2c_f32_bf16_e32 v50, v44, v22
	v_dot2c_f32_bf16_e32 v42, v46, v20
	s_lshr_b32 s26, s26, 7
	v_dot2c_f32_bf16_e32 v50, v48, v26
	v_dot2c_f32_bf16_e32 v42, v52, v24
	s_mov_b32 s27, s86
	v_cvt_scalef32_pk_bf16_fp4 v44, v67, 1.0
	v_cvt_scalef32_pk_bf16_fp4 v46, v67, 1.0 op_sel:[1,0,0]
	v_cvt_scalef32_pk_bf16_fp4 v48, v67, 1.0 op_sel:[0,1,0]
	v_cvt_scalef32_pk_bf16_fp4 v52, v67, 1.0 op_sel:[1,1,0]
	s_lshl_b64 s[26:27], s[26:27], 10
	v_dot2c_f32_bf16_e32 v50, v44, v30
	v_dot2c_f32_bf16_e32 v42, v46, v28
	s_add_u32 s26, s13, s26
	v_dot2c_f32_bf16_e32 v50, v48, v36
	v_dot2c_f32_bf16_e32 v42, v52, v34
	s_addc_u32 s27, s12, s27
	s_nop 2
	v_add_f32_e32 v41, v50, v42
	global_load_dwordx4 v[64:67], v32, s[26:27]
	s_waitcnt vmcnt(15)
	v_cvt_scalef32_pk_bf16_fp4 v42, v68, 1.0
	v_mov_b32_e32 v50, 0
	v_cvt_scalef32_pk_bf16_fp4 v44, v68, 1.0 op_sel:[1,0,0]
	v_cvt_scalef32_pk_bf16_fp4 v46, v68, 1.0 op_sel:[0,1,0]
	v_cvt_scalef32_pk_bf16_fp4 v48, v68, 1.0 op_sel:[1,1,0]
	v_dot2c_f32_bf16_e32 v50, v42, v6
	v_mov_b32_e32 v42, 0
	v_dot2c_f32_bf16_e32 v42, v44, v4
	v_dot2c_f32_bf16_e32 v50, v46, v10
	v_readlane_b32 s26, v2, 1
	v_dot2c_f32_bf16_e32 v42, v48, v8
	v_cvt_scalef32_pk_bf16_fp4 v44, v69, 1.0
	v_cvt_scalef32_pk_bf16_fp4 v46, v69, 1.0 op_sel:[1,0,0]
	v_cvt_scalef32_pk_bf16_fp4 v48, v69, 1.0 op_sel:[0,1,0]
	v_cvt_scalef32_pk_bf16_fp4 v52, v69, 1.0 op_sel:[1,1,0]
	s_lshr_b32 s26, s26, 7
	v_dot2c_f32_bf16_e32 v50, v44, v14
	v_dot2c_f32_bf16_e32 v42, v46, v12
	s_mov_b32 s27, s86
	v_dot2c_f32_bf16_e32 v50, v48, v18
	v_dot2c_f32_bf16_e32 v42, v52, v16
	v_cvt_scalef32_pk_bf16_fp4 v44, v70, 1.0
	v_cvt_scalef32_pk_bf16_fp4 v46, v70, 1.0 op_sel:[1,0,0]
	v_cvt_scalef32_pk_bf16_fp4 v48, v70, 1.0 op_sel:[0,1,0]
	v_cvt_scalef32_pk_bf16_fp4 v52, v70, 1.0 op_sel:[1,1,0]
	s_lshl_b64 s[26:27], s[26:27], 10
	v_dot2c_f32_bf16_e32 v50, v44, v22
	v_dot2c_f32_bf16_e32 v42, v46, v20
	s_add_u32 s26, s13, s26
	v_dot2c_f32_bf16_e32 v50, v48, v26
	v_dot2c_f32_bf16_e32 v42, v52, v24
	v_cvt_scalef32_pk_bf16_fp4 v44, v71, 1.0
	v_cvt_scalef32_pk_bf16_fp4 v46, v71, 1.0 op_sel:[1,0,0]
	v_cvt_scalef32_pk_bf16_fp4 v48, v71, 1.0 op_sel:[0,1,0]
	v_cvt_scalef32_pk_bf16_fp4 v52, v71, 1.0 op_sel:[1,1,0]
	s_addc_u32 s27, s12, s27
	v_dot2c_f32_bf16_e32 v50, v44, v30
	v_dot2c_f32_bf16_e32 v42, v46, v28
	v_mov_b32_e32 v38, 0
	v_dot2c_f32_bf16_e32 v50, v48, v36
	v_dot2c_f32_bf16_e32 v42, v52, v34
	v_mov_b32_e32 v52, 0
	s_nop 2
	v_add_f32_e32 v42, v50, v42
	global_load_dwordx4 v[68:71], v32, s[26:27]
	s_waitcnt vmcnt(15)
	v_cvt_scalef32_pk_bf16_fp4 v44, v72, 1.0
	v_cvt_scalef32_pk_bf16_fp4 v46, v72, 1.0 op_sel:[1,0,0]
	v_cvt_scalef32_pk_bf16_fp4 v48, v72, 1.0 op_sel:[0,1,0]
	v_cvt_scalef32_pk_bf16_fp4 v50, v72, 1.0 op_sel:[1,1,0]
	v_readlane_b32 s26, v2, 2
	v_dot2c_f32_bf16_e32 v52, v44, v6
	v_mov_b32_e32 v44, 0
	v_dot2c_f32_bf16_e32 v44, v46, v4
	v_dot2c_f32_bf16_e32 v52, v48, v10
	s_lshr_b32 s26, s26, 7
	v_dot2c_f32_bf16_e32 v44, v50, v8
	v_cvt_scalef32_pk_bf16_fp4 v46, v73, 1.0
	v_cvt_scalef32_pk_bf16_fp4 v48, v73, 1.0 op_sel:[1,0,0]
	v_cvt_scalef32_pk_bf16_fp4 v50, v73, 1.0 op_sel:[0,1,0]
	v_cvt_scalef32_pk_bf16_fp4 v54, v73, 1.0 op_sel:[1,1,0]
	s_mov_b32 s27, s86
	v_dot2c_f32_bf16_e32 v52, v46, v14
	v_dot2c_f32_bf16_e32 v44, v48, v12
	s_lshl_b64 s[26:27], s[26:27], 10
	v_dot2c_f32_bf16_e32 v52, v50, v18
	v_dot2c_f32_bf16_e32 v44, v54, v16
	v_cvt_scalef32_pk_bf16_fp4 v46, v74, 1.0
	v_cvt_scalef32_pk_bf16_fp4 v48, v74, 1.0 op_sel:[1,0,0]
	v_cvt_scalef32_pk_bf16_fp4 v50, v74, 1.0 op_sel:[0,1,0]
	v_cvt_scalef32_pk_bf16_fp4 v54, v74, 1.0 op_sel:[1,1,0]
	s_add_u32 s26, s13, s26
	v_dot2c_f32_bf16_e32 v52, v46, v22
	v_dot2c_f32_bf16_e32 v44, v48, v20
	s_addc_u32 s27, s12, s27
	v_dot2c_f32_bf16_e32 v52, v50, v26
	v_dot2c_f32_bf16_e32 v44, v54, v24
	v_cvt_scalef32_pk_bf16_fp4 v46, v75, 1.0
	v_cvt_scalef32_pk_bf16_fp4 v48, v75, 1.0 op_sel:[1,0,0]
	v_cvt_scalef32_pk_bf16_fp4 v50, v75, 1.0 op_sel:[0,1,0]
	v_cvt_scalef32_pk_bf16_fp4 v54, v75, 1.0 op_sel:[1,1,0]
	s_nop 0
	v_dot2c_f32_bf16_e32 v52, v46, v30
	v_dot2c_f32_bf16_e32 v44, v48, v28
	s_nop 0
	v_dot2c_f32_bf16_e32 v52, v50, v36
	v_dot2c_f32_bf16_e32 v44, v54, v34
	s_nop 0
	s_nop 2
	v_add_f32_e32 v43, v52, v44
	global_load_dwordx4 v[72:75], v32, s[26:27]
	s_waitcnt vmcnt(15)
; #define P4_FOR16(M) M(0) M(1) M(2) M(3) M(4) M(5) M(6) M(7) M(8) M(9) M(10) M(11) M(12) M(13) M(14) M(15)
; #define P4_U(i) { P4_DOT(b##i, part[i]); const int nk_ = __builtin_amdgcn_readlane(ksel, nb + i); P4_LOAD(b##i, Ug, nk_); }
; #define P4_U(i) { P4_DOT(b##i, part[i]); const int nk_ = __builtin_amdgcn_readlane(kn, i); P4_LOAD(b##i, nbase, nk_); }
; __device__ __forceinline__ void peer_gather_f4p(const float* X, const int* __restrict__ IDX, const float* __restrict__ G, ...
;     ...
;         {
;     ...
;             P4_FOR16(P4_U)
	v_cvt_scalef32_pk_bf16_fp4 v44, v76, 1.0
	v_mov_b32_e32 v52, 0
	v_cvt_scalef32_pk_bf16_fp4 v46, v76, 1.0 op_sel:[1,0,0]
	v_cvt_scalef32_pk_bf16_fp4 v48, v76, 1.0 op_sel:[0,1,0]
	v_cvt_scalef32_pk_bf16_fp4 v50, v76, 1.0 op_sel:[1,1,0]
	v_dot2c_f32_bf16_e32 v52, v44, v6
	v_mov_b32_e32 v44, 0
	v_dot2c_f32_bf16_e32 v44, v46, v4
	v_dot2c_f32_bf16_e32 v52, v48, v10
	v_readlane_b32 s26, v2, 3
	v_dot2c_f32_bf16_e32 v44, v50, v8
	v_cvt_scalef32_pk_bf16_fp4 v46, v77, 1.0
	v_cvt_scalef32_pk_bf16_fp4 v48, v77, 1.0 op_sel:[1,0,0]
	v_cvt_scalef32_pk_bf16_fp4 v50, v77, 1.0 op_sel:[0,1,0]
	v_cvt_scalef32_pk_bf16_fp4 v54, v77, 1.0 op_sel:[1,1,0]
	s_lshr_b32 s26, s26, 7
	v_dot2c_f32_bf16_e32 v52, v46, v14
	v_dot2c_f32_bf16_e32 v44, v48, v12
	s_mov_b32 s27, s86
	v_dot2c_f32_bf16_e32 v52, v50, v18
	v_dot2c_f32_bf16_e32 v44, v54, v16
	v_cvt_scalef32_pk_bf16_fp4 v46, v78, 1.0
	v_cvt_scalef32_pk_bf16_fp4 v48, v78, 1.0 op_sel:[1,0,0]
	v_cvt_scalef32_pk_bf16_fp4 v50, v78, 1.0 op_sel:[0,1,0]
	v_cvt_scalef32_pk_bf16_fp4 v54, v78, 1.0 op_sel:[1,1,0]
	s_lshl_b64 s[26:27], s[26:27], 10
	v_dot2c_f32_bf16_e32 v52, v46, v22
	v_dot2c_f32_bf16_e32 v44, v48, v20
	s_add_u32 s26, s13, s26
	v_dot2c_f32_bf16_e32 v52, v50, v26
	v_dot2c_f32_bf16_e32 v44, v54, v24
	v_cvt_scalef32_pk_bf16_fp4 v46, v79, 1.0
	v_cvt_scalef32_pk_bf16_fp4 v48, v79, 1.0 op_sel:[1,0,0]
	v_cvt_scalef32_pk_bf16_fp4 v50, v79, 1.0 op_sel:[0,1,0]
	v_cvt_scalef32_pk_bf16_fp4 v54, v79, 1.0 op_sel:[1,1,0]
	s_addc_u32 s27, s12, s27
	v_dot2c_f32_bf16_e32 v52, v46, v30
	v_dot2c_f32_bf16_e32 v44, v48, v28
	s_nop 0
	v_dot2c_f32_bf16_e32 v52, v50, v36
	v_dot2c_f32_bf16_e32 v44, v54, v34
	v_mov_b32_e32 v54, 0
	s_nop 2
	v_add_f32_e32 v44, v52, v44
	global_load_dwordx4 v[76:79], v32, s[26:27]
	s_waitcnt vmcnt(15)
	v_cvt_scalef32_pk_bf16_fp4 v46, v84, 1.0
	v_cvt_scalef32_pk_bf16_fp4 v48, v84, 1.0 op_sel:[1,0,0]
	v_cvt_scalef32_pk_bf16_fp4 v50, v84, 1.0 op_sel:[0,1,0]
	v_cvt_scalef32_pk_bf16_fp4 v52, v84, 1.0 op_sel:[1,1,0]
	v_readlane_b32 s26, v2, 4
	v_dot2c_f32_bf16_e32 v54, v46, v6
	v_mov_b32_e32 v46, 0
	v_dot2c_f32_bf16_e32 v46, v48, v4
	v_dot2c_f32_bf16_e32 v54, v50, v10
	s_lshr_b32 s26, s26, 7
	v_dot2c_f32_bf16_e32 v46, v52, v8
	v_cvt_scalef32_pk_bf16_fp4 v48, v85, 1.0
	v_cvt_scalef32_pk_bf16_fp4 v50, v85, 1.0 op_sel:[1,0,0]
	v_cvt_scalef32_pk_bf16_fp4 v52, v85, 1.0 op_sel:[0,1,0]
	v_cvt_scalef32_pk_bf16_fp4 v56, v85, 1.0 op_sel:[1,1,0]
	s_mov_b32 s27, s86
	v_dot2c_f32_bf16_e32 v54, v48, v14
	v_dot2c_f32_bf16_e32 v46, v50, v12
	s_lshl_b64 s[26:27], s[26:27], 10
	v_dot2c_f32_bf16_e32 v54, v52, v18
	v_dot2c_f32_bf16_e32 v46, v56, v16
	v_cvt_scalef32_pk_bf16_fp4 v48, v86, 1.0
	v_cvt_scalef32_pk_bf16_fp4 v50, v86, 1.0 op_sel:[1,0,0]
	v_cvt_scalef32_pk_bf16_fp4 v52, v86, 1.0 op_sel:[0,1,0]
	v_cvt_scalef32_pk_bf16_fp4 v56, v86, 1.0 op_sel:[1,1,0]
	s_add_u32 s26, s13, s26
	v_dot2c_f32_bf16_e32 v54, v48, v22
	v_dot2c_f32_bf16_e32 v46, v50, v20
	s_addc_u32 s27, s12, s27
	v_dot2c_f32_bf16_e32 v54, v52, v26
	v_dot2c_f32_bf16_e32 v46, v56, v24
	v_cvt_scalef32_pk_bf16_fp4 v48, v87, 1.0
	v_cvt_scalef32_pk_bf16_fp4 v50, v87, 1.0 op_sel:[1,0,0]
	v_cvt_scalef32_pk_bf16_fp4 v52, v87, 1.0 op_sel:[0,1,0]
	v_cvt_scalef32_pk_bf16_fp4 v56, v87, 1.0 op_sel:[1,1,0]
	s_nop 0
	v_dot2c_f32_bf16_e32 v54, v48, v30
	v_dot2c_f32_bf16_e32 v46, v50, v28
	s_nop 0
	v_dot2c_f32_bf16_e32 v54, v52, v36
	v_dot2c_f32_bf16_e32 v46, v56, v34
	s_nop 0
	s_nop 2
	v_add_f32_e32 v45, v54, v46
	global_load_dwordx4 v[84:87], v32, s[26:27]
	s_waitcnt vmcnt(15)
	v_cvt_scalef32_pk_bf16_fp4 v46, v88, 1.0
	v_mov_b32_e32 v54, 0
	v_cvt_scalef32_pk_bf16_fp4 v48, v88, 1.0 op_sel:[1,0,0]
	v_cvt_scalef32_pk_bf16_fp4 v50, v88, 1.0 op_sel:[0,1,0]
	v_cvt_scalef32_pk_bf16_fp4 v52, v88, 1.0 op_sel:[1,1,0]
	v_dot2c_f32_bf16_e32 v54, v46, v6
	v_mov_b32_e32 v46, 0
	v_dot2c_f32_bf16_e32 v46, v48, v4
	v_dot2c_f32_bf16_e32 v54, v50, v10
	v_readlane_b32 s26, v2, 5
	v_dot2c_f32_bf16_e32 v46, v52, v8
	v_cvt_scalef32_pk_bf16_fp4 v48, v89, 1.0
	v_cvt_scalef32_pk_bf16_fp4 v50, v89, 1.0 op_sel:[1,0,0]
	v_cvt_scalef32_pk_bf16_fp4 v52, v89, 1.0 op_sel:[0,1,0]
	v_cvt_scalef32_pk_bf16_fp4 v56, v89, 1.0 op_sel:[1,1,0]
	s_lshr_b32 s26, s26, 7
	v_dot2c_f32_bf16_e32 v54, v48, v14
	v_dot2c_f32_bf16_e32 v46, v50, v12
	s_mov_b32 s27, s86
	v_dot2c_f32_bf16_e32 v54, v52, v18
	v_dot2c_f32_bf16_e32 v46, v56, v16
	v_cvt_scalef32_pk_bf16_fp4 v48, v90, 1.0
	v_cvt_scalef32_pk_bf16_fp4 v50, v90, 1.0 op_sel:[1,0,0]
	v_cvt_scalef32_pk_bf16_fp4 v52, v90, 1.0 op_sel:[0,1,0]
	v_cvt_scalef32_pk_bf16_fp4 v56, v90, 1.0 op_sel:[1,1,0]
	s_lshl_b64 s[26:27], s[26:27], 10
	v_dot2c_f32_bf16_e32 v54, v48, v22
	v_dot2c_f32_bf16_e32 v46, v50, v20
	s_add_u32 s26, s13, s26
	v_dot2c_f32_bf16_e32 v54, v52, v26
	v_dot2c_f32_bf16_e32 v46, v56, v24
	v_cvt_scalef32_pk_bf16_fp4 v48, v91, 1.0
	v_cvt_scalef32_pk_bf16_fp4 v50, v91, 1.0 op_sel:[1,0,0]
	v_cvt_scalef32_pk_bf16_fp4 v52, v91, 1.0 op_sel:[0,1,0]
	v_cvt_scalef32_pk_bf16_fp4 v56, v91, 1.0 op_sel:[1,1,0]
	s_addc_u32 s27, s12, s27
	v_dot2c_f32_bf16_e32 v54, v48, v30
	v_dot2c_f32_bf16_e32 v46, v50, v28
	s_nop 0
	v_dot2c_f32_bf16_e32 v54, v52, v36
	v_dot2c_f32_bf16_e32 v46, v56, v34
	v_mov_b32_e32 v56, 0
	s_nop 2
	v_add_f32_e32 v46, v54, v46
	global_load_dwordx4 v[88:91], v32, s[26:27]
	s_waitcnt vmcnt(15)
; #define P4_FOR16(M) M(0) M(1) M(2) M(3) M(4) M(5) M(6) M(7) M(8) M(9) M(10) M(11) M(12) M(13) M(14) M(15)
; #define P4_U(i) { P4_DOT(b##i, part[i]); const int nk_ = __builtin_amdgcn_readlane(ksel, nb + i); P4_LOAD(b##i, Ug, nk_); }
; #define P4_U(i) { P4_DOT(b##i, part[i]); const int nk_ = __builtin_amdgcn_readlane(kn, i); P4_LOAD(b##i, nbase, nk_); }
; __device__ __forceinline__ void peer_gather_f4p(const float* X, const int* __restrict__ IDX, const float* __restrict__ G, ...
;     ...
;         {
;     ...
;             P4_FOR16(P4_U)
	v_cvt_scalef32_pk_bf16_fp4 v48, v92, 1.0
	v_cvt_scalef32_pk_bf16_fp4 v50, v92, 1.0 op_sel:[1,0,0]
	v_cvt_scalef32_pk_bf16_fp4 v52, v92, 1.0 op_sel:[0,1,0]
	v_cvt_scalef32_pk_bf16_fp4 v54, v92, 1.0 op_sel:[1,1,0]
	v_readlane_b32 s26, v2, 6
	v_dot2c_f32_bf16_e32 v56, v48, v6
	v_mov_b32_e32 v48, 0
	v_dot2c_f32_bf16_e32 v48, v50, v4
	v_dot2c_f32_bf16_e32 v56, v52, v10
	s_lshr_b32 s26, s26, 7
	v_dot2c_f32_bf16_e32 v48, v54, v8
	v_cvt_scalef32_pk_bf16_fp4 v50, v93, 1.0
	v_cvt_scalef32_pk_bf16_fp4 v52, v93, 1.0 op_sel:[1,0,0]
	v_cvt_scalef32_pk_bf16_fp4 v54, v93, 1.0 op_sel:[0,1,0]
	v_cvt_scalef32_pk_bf16_fp4 v58, v93, 1.0 op_sel:[1,1,0]
	s_mov_b32 s27, s86
	v_dot2c_f32_bf16_e32 v56, v50, v14
	v_dot2c_f32_bf16_e32 v48, v52, v12
	s_lshl_b64 s[26:27], s[26:27], 10
	v_dot2c_f32_bf16_e32 v56, v54, v18
	v_dot2c_f32_bf16_e32 v48, v58, v16
	v_cvt_scalef32_pk_bf16_fp4 v50, v94, 1.0
	v_cvt_scalef32_pk_bf16_fp4 v52, v94, 1.0 op_sel:[1,0,0]
	v_cvt_scalef32_pk_bf16_fp4 v54, v94, 1.0 op_sel:[0,1,0]
	v_cvt_scalef32_pk_bf16_fp4 v58, v94, 1.0 op_sel:[1,1,0]
	s_add_u32 s26, s13, s26
	v_dot2c_f32_bf16_e32 v56, v50, v22
	v_dot2c_f32_bf16_e32 v48, v52, v20
	s_addc_u32 s27, s12, s27
	v_dot2c_f32_bf16_e32 v56, v54, v26
	v_dot2c_f32_bf16_e32 v48, v58, v24
	v_cvt_scalef32_pk_bf16_fp4 v50, v95, 1.0
	v_cvt_scalef32_pk_bf16_fp4 v52, v95, 1.0 op_sel:[1,0,0]
	v_cvt_scalef32_pk_bf16_fp4 v54, v95, 1.0 op_sel:[0,1,0]
	v_cvt_scalef32_pk_bf16_fp4 v58, v95, 1.0 op_sel:[1,1,0]
	s_nop 0
	v_dot2c_f32_bf16_e32 v56, v50, v30
	v_dot2c_f32_bf16_e32 v48, v52, v28
	s_nop 0
	v_dot2c_f32_bf16_e32 v56, v54, v36
	v_dot2c_f32_bf16_e32 v48, v58, v34
	s_nop 0
	s_nop 2
	v_add_f32_e32 v47, v56, v48
	global_load_dwordx4 v[92:95], v32, s[26:27]
	s_waitcnt vmcnt(15)
	v_cvt_scalef32_pk_bf16_fp4 v48, v96, 1.0
	v_mov_b32_e32 v56, 0
	v_cvt_scalef32_pk_bf16_fp4 v50, v96, 1.0 op_sel:[1,0,0]
	v_cvt_scalef32_pk_bf16_fp4 v52, v96, 1.0 op_sel:[0,1,0]
	v_cvt_scalef32_pk_bf16_fp4 v54, v96, 1.0 op_sel:[1,1,0]
	v_dot2c_f32_bf16_e32 v56, v48, v6
	v_mov_b32_e32 v48, 0
	v_dot2c_f32_bf16_e32 v48, v50, v4
	v_dot2c_f32_bf16_e32 v56, v52, v10
	v_readlane_b32 s26, v2, 7
	v_dot2c_f32_bf16_e32 v48, v54, v8
	v_cvt_scalef32_pk_bf16_fp4 v50, v97, 1.0
	v_cvt_scalef32_pk_bf16_fp4 v52, v97, 1.0 op_sel:[1,0,0]
	v_cvt_scalef32_pk_bf16_fp4 v54, v97, 1.0 op_sel:[0,1,0]
	v_cvt_scalef32_pk_bf16_fp4 v58, v97, 1.0 op_sel:[1,1,0]
	s_lshr_b32 s26, s26, 7
	v_dot2c_f32_bf16_e32 v56, v50, v14
	v_dot2c_f32_bf16_e32 v48, v52, v12
	s_mov_b32 s27, s86
	v_dot2c_f32_bf16_e32 v56, v54, v18
	v_dot2c_f32_bf16_e32 v48, v58, v16
	v_cvt_scalef32_pk_bf16_fp4 v50, v98, 1.0
	v_cvt_scalef32_pk_bf16_fp4 v52, v98, 1.0 op_sel:[1,0,0]
	v_cvt_scalef32_pk_bf16_fp4 v54, v98, 1.0 op_sel:[0,1,0]
	v_cvt_scalef32_pk_bf16_fp4 v58, v98, 1.0 op_sel:[1,1,0]
	s_lshl_b64 s[26:27], s[26:27], 10
	v_dot2c_f32_bf16_e32 v56, v50, v22
	v_dot2c_f32_bf16_e32 v48, v52, v20
	s_add_u32 s26, s13, s26
	v_dot2c_f32_bf16_e32 v56, v54, v26
	v_dot2c_f32_bf16_e32 v48, v58, v24
	v_cvt_scalef32_pk_bf16_fp4 v50, v99, 1.0
	v_cvt_scalef32_pk_bf16_fp4 v52, v99, 1.0 op_sel:[1,0,0]
	v_cvt_scalef32_pk_bf16_fp4 v54, v99, 1.0 op_sel:[0,1,0]
	v_cvt_scalef32_pk_bf16_fp4 v58, v99, 1.0 op_sel:[1,1,0]
	s_addc_u32 s27, s12, s27
	v_dot2c_f32_bf16_e32 v56, v50, v30
	v_dot2c_f32_bf16_e32 v48, v52, v28
	s_nop 0
	v_dot2c_f32_bf16_e32 v56, v54, v36
	v_dot2c_f32_bf16_e32 v48, v58, v34
	v_mov_b32_e32 v58, 0
	s_nop 2
	v_add_f32_e32 v48, v56, v48
	global_load_dwordx4 v[96:99], v32, s[26:27]
	s_waitcnt vmcnt(15)
	v_cvt_scalef32_pk_bf16_fp4 v50, v100, 1.0
	v_cvt_scalef32_pk_bf16_fp4 v52, v100, 1.0 op_sel:[1,0,0]
	v_cvt_scalef32_pk_bf16_fp4 v54, v100, 1.0 op_sel:[0,1,0]
	v_cvt_scalef32_pk_bf16_fp4 v56, v100, 1.0 op_sel:[1,1,0]
	v_readlane_b32 s26, v2, 8
	v_dot2c_f32_bf16_e32 v58, v50, v6
	v_mov_b32_e32 v50, 0
	v_dot2c_f32_bf16_e32 v50, v52, v4
	v_dot2c_f32_bf16_e32 v58, v54, v10
	s_lshr_b32 s26, s26, 7
	v_dot2c_f32_bf16_e32 v50, v56, v8
	v_cvt_scalef32_pk_bf16_fp4 v52, v101, 1.0
	v_cvt_scalef32_pk_bf16_fp4 v54, v101, 1.0 op_sel:[1,0,0]
	v_cvt_scalef32_pk_bf16_fp4 v56, v101, 1.0 op_sel:[0,1,0]
	v_cvt_scalef32_pk_bf16_fp4 v60, v101, 1.0 op_sel:[1,1,0]
	s_mov_b32 s27, s86
	v_dot2c_f32_bf16_e32 v58, v52, v14
	v_dot2c_f32_bf16_e32 v50, v54, v12
	s_lshl_b64 s[26:27], s[26:27], 10
	v_dot2c_f32_bf16_e32 v58, v56, v18
	v_dot2c_f32_bf16_e32 v50, v60, v16
	v_cvt_scalef32_pk_bf16_fp4 v52, v102, 1.0
	v_cvt_scalef32_pk_bf16_fp4 v54, v102, 1.0 op_sel:[1,0,0]
	v_cvt_scalef32_pk_bf16_fp4 v56, v102, 1.0 op_sel:[0,1,0]
	v_cvt_scalef32_pk_bf16_fp4 v60, v102, 1.0 op_sel:[1,1,0]
	s_add_u32 s26, s13, s26
	v_dot2c_f32_bf16_e32 v58, v52, v22
	v_dot2c_f32_bf16_e32 v50, v54, v20
	s_addc_u32 s27, s12, s27
	v_dot2c_f32_bf16_e32 v58, v56, v26
	v_dot2c_f32_bf16_e32 v50, v60, v24
	v_cvt_scalef32_pk_bf16_fp4 v52, v103, 1.0
	v_cvt_scalef32_pk_bf16_fp4 v54, v103, 1.0 op_sel:[1,0,0]
	v_cvt_scalef32_pk_bf16_fp4 v56, v103, 1.0 op_sel:[0,1,0]
	v_cvt_scalef32_pk_bf16_fp4 v60, v103, 1.0 op_sel:[1,1,0]
	s_nop 0
	v_dot2c_f32_bf16_e32 v58, v52, v30
	v_dot2c_f32_bf16_e32 v50, v54, v28
	s_nop 0
	v_dot2c_f32_bf16_e32 v58, v56, v36
	v_dot2c_f32_bf16_e32 v50, v60, v34
	s_nop 0
	s_nop 2
	v_add_f32_e32 v49, v58, v50
	global_load_dwordx4 v[100:103], v32, s[26:27]
	s_waitcnt vmcnt(15)
; #define P4_FOR16(M) M(0) M(1) M(2) M(3) M(4) M(5) M(6) M(7) M(8) M(9) M(10) M(11) M(12) M(13) M(14) M(15)
; #define P4_U(i) { P4_DOT(b##i, part[i]); const int nk_ = __builtin_amdgcn_readlane(ksel, nb + i); P4_LOAD(b##i, Ug, nk_); }
; #define P4_U(i) { P4_DOT(b##i, part[i]); const int nk_ = __builtin_amdgcn_readlane(kn, i); P4_LOAD(b##i, nbase, nk_); }
; __device__ __forceinline__ void peer_gather_f4p(const float* X, const int* __restrict__ IDX, const float* __restrict__ G, ...
;     ...
;         {
;     ...
;             P4_FOR16(P4_U)
	v_cvt_scalef32_pk_bf16_fp4 v50, v104, 1.0
	v_mov_b32_e32 v58, 0
	v_cvt_scalef32_pk_bf16_fp4 v52, v104, 1.0 op_sel:[1,0,0]
	v_cvt_scalef32_pk_bf16_fp4 v54, v104, 1.0 op_sel:[0,1,0]
	v_cvt_scalef32_pk_bf16_fp4 v56, v104, 1.0 op_sel:[1,1,0]
	v_dot2c_f32_bf16_e32 v58, v50, v6
	v_mov_b32_e32 v50, 0
	v_dot2c_f32_bf16_e32 v50, v52, v4
	v_dot2c_f32_bf16_e32 v58, v54, v10
	v_readlane_b32 s26, v2, 9
	v_dot2c_f32_bf16_e32 v50, v56, v8
	v_cvt_scalef32_pk_bf16_fp4 v52, v105, 1.0
	v_cvt_scalef32_pk_bf16_fp4 v54, v105, 1.0 op_sel:[1,0,0]
	v_cvt_scalef32_pk_bf16_fp4 v56, v105, 1.0 op_sel:[0,1,0]
	v_cvt_scalef32_pk_bf16_fp4 v60, v105, 1.0 op_sel:[1,1,0]
	s_lshr_b32 s26, s26, 7
	v_dot2c_f32_bf16_e32 v58, v52, v14
	v_dot2c_f32_bf16_e32 v50, v54, v12
	s_mov_b32 s27, s86
	v_dot2c_f32_bf16_e32 v58, v56, v18
	v_dot2c_f32_bf16_e32 v50, v60, v16
	v_cvt_scalef32_pk_bf16_fp4 v52, v106, 1.0
	v_cvt_scalef32_pk_bf16_fp4 v54, v106, 1.0 op_sel:[1,0,0]
	v_cvt_scalef32_pk_bf16_fp4 v56, v106, 1.0 op_sel:[0,1,0]
	v_cvt_scalef32_pk_bf16_fp4 v60, v106, 1.0 op_sel:[1,1,0]
	s_lshl_b64 s[26:27], s[26:27], 10
	v_dot2c_f32_bf16_e32 v58, v52, v22
	v_dot2c_f32_bf16_e32 v50, v54, v20
	s_add_u32 s26, s13, s26
	v_dot2c_f32_bf16_e32 v58, v56, v26
	v_dot2c_f32_bf16_e32 v50, v60, v24
	v_cvt_scalef32_pk_bf16_fp4 v52, v107, 1.0
	v_cvt_scalef32_pk_bf16_fp4 v54, v107, 1.0 op_sel:[1,0,0]
	v_cvt_scalef32_pk_bf16_fp4 v56, v107, 1.0 op_sel:[0,1,0]
	v_cvt_scalef32_pk_bf16_fp4 v60, v107, 1.0 op_sel:[1,1,0]
	s_addc_u32 s27, s12, s27
	v_dot2c_f32_bf16_e32 v58, v52, v30
	v_dot2c_f32_bf16_e32 v50, v54, v28
	s_nop 0
	v_dot2c_f32_bf16_e32 v58, v56, v36
	v_dot2c_f32_bf16_e32 v50, v60, v34
	v_mov_b32_e32 v60, 0
	s_nop 2
	v_add_f32_e32 v50, v58, v50
	global_load_dwordx4 v[104:107], v32, s[26:27]
	s_waitcnt vmcnt(15)
	v_cvt_scalef32_pk_bf16_fp4 v52, v108, 1.0
	v_cvt_scalef32_pk_bf16_fp4 v54, v108, 1.0 op_sel:[1,0,0]
	v_cvt_scalef32_pk_bf16_fp4 v56, v108, 1.0 op_sel:[0,1,0]
	v_cvt_scalef32_pk_bf16_fp4 v58, v108, 1.0 op_sel:[1,1,0]
	v_readlane_b32 s26, v2, 10
	v_dot2c_f32_bf16_e32 v60, v52, v6
	v_mov_b32_e32 v52, 0
	v_dot2c_f32_bf16_e32 v52, v54, v4
	v_dot2c_f32_bf16_e32 v60, v56, v10
	s_lshr_b32 s26, s26, 7
	v_dot2c_f32_bf16_e32 v52, v58, v8
	v_cvt_scalef32_pk_bf16_fp4 v54, v109, 1.0
	v_cvt_scalef32_pk_bf16_fp4 v56, v109, 1.0 op_sel:[1,0,0]
	v_cvt_scalef32_pk_bf16_fp4 v58, v109, 1.0 op_sel:[0,1,0]
	v_cvt_scalef32_pk_bf16_fp4 v62, v109, 1.0 op_sel:[1,1,0]
	s_mov_b32 s27, s86
	v_dot2c_f32_bf16_e32 v60, v54, v14
	v_dot2c_f32_bf16_e32 v52, v56, v12
	s_lshl_b64 s[26:27], s[26:27], 10
	v_dot2c_f32_bf16_e32 v60, v58, v18
	v_dot2c_f32_bf16_e32 v52, v62, v16
	v_cvt_scalef32_pk_bf16_fp4 v54, v110, 1.0
	v_cvt_scalef32_pk_bf16_fp4 v56, v110, 1.0 op_sel:[1,0,0]
	v_cvt_scalef32_pk_bf16_fp4 v58, v110, 1.0 op_sel:[0,1,0]
	v_cvt_scalef32_pk_bf16_fp4 v62, v110, 1.0 op_sel:[1,1,0]
	s_add_u32 s26, s13, s26
	v_dot2c_f32_bf16_e32 v60, v54, v22
	v_dot2c_f32_bf16_e32 v52, v56, v20
	s_addc_u32 s27, s12, s27
	v_dot2c_f32_bf16_e32 v60, v58, v26
	v_dot2c_f32_bf16_e32 v52, v62, v24
	v_cvt_scalef32_pk_bf16_fp4 v54, v111, 1.0
	v_cvt_scalef32_pk_bf16_fp4 v56, v111, 1.0 op_sel:[1,0,0]
	v_cvt_scalef32_pk_bf16_fp4 v58, v111, 1.0 op_sel:[0,1,0]
	v_cvt_scalef32_pk_bf16_fp4 v62, v111, 1.0 op_sel:[1,1,0]
	s_nop 0
	v_dot2c_f32_bf16_e32 v60, v54, v30
	v_dot2c_f32_bf16_e32 v52, v56, v28
	s_nop 0
	v_dot2c_f32_bf16_e32 v60, v58, v36
	v_dot2c_f32_bf16_e32 v52, v62, v34
	s_nop 0
	s_nop 2
	v_add_f32_e32 v51, v60, v52
	global_load_dwordx4 v[108:111], v32, s[26:27]
	s_waitcnt vmcnt(15)
	v_cvt_scalef32_pk_bf16_fp4 v52, v112, 1.0
	v_mov_b32_e32 v60, 0
	v_cvt_scalef32_pk_bf16_fp4 v54, v112, 1.0 op_sel:[1,0,0]
	v_cvt_scalef32_pk_bf16_fp4 v56, v112, 1.0 op_sel:[0,1,0]
	v_cvt_scalef32_pk_bf16_fp4 v58, v112, 1.0 op_sel:[1,1,0]
	v_dot2c_f32_bf16_e32 v60, v52, v6
	v_mov_b32_e32 v52, 0
	v_dot2c_f32_bf16_e32 v52, v54, v4
	v_dot2c_f32_bf16_e32 v60, v56, v10
	v_readlane_b32 s26, v2, 11
	v_dot2c_f32_bf16_e32 v52, v58, v8
	v_cvt_scalef32_pk_bf16_fp4 v54, v113, 1.0
	v_cvt_scalef32_pk_bf16_fp4 v56, v113, 1.0 op_sel:[1,0,0]
	v_cvt_scalef32_pk_bf16_fp4 v58, v113, 1.0 op_sel:[0,1,0]
	v_cvt_scalef32_pk_bf16_fp4 v62, v113, 1.0 op_sel:[1,1,0]
	s_lshr_b32 s26, s26, 7
	v_dot2c_f32_bf16_e32 v60, v54, v14
	v_dot2c_f32_bf16_e32 v52, v56, v12
	s_mov_b32 s27, s86
	v_dot2c_f32_bf16_e32 v60, v58, v18
	v_dot2c_f32_bf16_e32 v52, v62, v16
	v_cvt_scalef32_pk_bf16_fp4 v54, v114, 1.0
	v_cvt_scalef32_pk_bf16_fp4 v56, v114, 1.0 op_sel:[1,0,0]
	v_cvt_scalef32_pk_bf16_fp4 v58, v114, 1.0 op_sel:[0,1,0]
	v_cvt_scalef32_pk_bf16_fp4 v62, v114, 1.0 op_sel:[1,1,0]
	s_lshl_b64 s[26:27], s[26:27], 10
	v_dot2c_f32_bf16_e32 v60, v54, v22
	v_dot2c_f32_bf16_e32 v52, v56, v20
	s_add_u32 s26, s13, s26
	v_dot2c_f32_bf16_e32 v60, v58, v26
	v_dot2c_f32_bf16_e32 v52, v62, v24
	v_cvt_scalef32_pk_bf16_fp4 v54, v115, 1.0
	v_cvt_scalef32_pk_bf16_fp4 v56, v115, 1.0 op_sel:[1,0,0]
	v_cvt_scalef32_pk_bf16_fp4 v58, v115, 1.0 op_sel:[0,1,0]
	v_cvt_scalef32_pk_bf16_fp4 v62, v115, 1.0 op_sel:[1,1,0]
	s_addc_u32 s27, s12, s27
	v_dot2c_f32_bf16_e32 v60, v54, v30
	v_dot2c_f32_bf16_e32 v52, v56, v28
	s_nop 0
	v_dot2c_f32_bf16_e32 v60, v58, v36
	v_dot2c_f32_bf16_e32 v52, v62, v34
	s_nop 0
	s_nop 2
	v_add_f32_e32 v80, v60, v52
	global_load_dwordx4 v[112:115], v32, s[26:27]
	s_waitcnt vmcnt(15)
; #define P4_FOR16(M) M(0) M(1) M(2) M(3) M(4) M(5) M(6) M(7) M(8) M(9) M(10) M(11) M(12) M(13) M(14) M(15)
; #define P4_U(i) { P4_DOT(b##i, part[i]); const int nk_ = __builtin_amdgcn_readlane(ksel, nb + i); P4_LOAD(b##i, Ug, nk_); }
; #define P4_U(i) { P4_DOT(b##i, part[i]); const int nk_ = __builtin_amdgcn_readlane(kn, i); P4_LOAD(b##i, nbase, nk_); }
; __device__ __forceinline__ void peer_gather_f4p(const float* X, const int* __restrict__ IDX, const float* __restrict__ G, ...
;     ...
;         {
;     ...
;             P4_FOR16(P4_U)
	v_cvt_scalef32_pk_bf16_fp4 v52, v116, 1.0
	v_mov_b32_e32 v60, 0
	v_cvt_scalef32_pk_bf16_fp4 v54, v116, 1.0 op_sel:[1,0,0]
	v_cvt_scalef32_pk_bf16_fp4 v56, v116, 1.0 op_sel:[0,1,0]
	v_cvt_scalef32_pk_bf16_fp4 v58, v116, 1.0 op_sel:[1,1,0]
	v_dot2c_f32_bf16_e32 v60, v52, v6
	v_mov_b32_e32 v52, 0
	v_dot2c_f32_bf16_e32 v52, v54, v4
	v_dot2c_f32_bf16_e32 v60, v56, v10
	v_readlane_b32 s26, v2, 12
	v_dot2c_f32_bf16_e32 v52, v58, v8
	v_cvt_scalef32_pk_bf16_fp4 v54, v117, 1.0
	v_cvt_scalef32_pk_bf16_fp4 v56, v117, 1.0 op_sel:[1,0,0]
	v_cvt_scalef32_pk_bf16_fp4 v58, v117, 1.0 op_sel:[0,1,0]
	v_cvt_scalef32_pk_bf16_fp4 v62, v117, 1.0 op_sel:[1,1,0]
	s_lshr_b32 s26, s26, 7
	v_dot2c_f32_bf16_e32 v60, v54, v14
	v_dot2c_f32_bf16_e32 v52, v56, v12
	s_mov_b32 s27, s86
	v_dot2c_f32_bf16_e32 v60, v58, v18
	v_dot2c_f32_bf16_e32 v52, v62, v16
	v_cvt_scalef32_pk_bf16_fp4 v54, v118, 1.0
	v_cvt_scalef32_pk_bf16_fp4 v56, v118, 1.0 op_sel:[1,0,0]
	v_cvt_scalef32_pk_bf16_fp4 v58, v118, 1.0 op_sel:[0,1,0]
	v_cvt_scalef32_pk_bf16_fp4 v62, v118, 1.0 op_sel:[1,1,0]
	s_lshl_b64 s[26:27], s[26:27], 10
	v_dot2c_f32_bf16_e32 v60, v54, v22
	v_dot2c_f32_bf16_e32 v52, v56, v20
	s_add_u32 s26, s13, s26
	v_dot2c_f32_bf16_e32 v60, v58, v26
	v_dot2c_f32_bf16_e32 v52, v62, v24
	v_cvt_scalef32_pk_bf16_fp4 v54, v119, 1.0
	v_cvt_scalef32_pk_bf16_fp4 v56, v119, 1.0 op_sel:[1,0,0]
	v_cvt_scalef32_pk_bf16_fp4 v58, v119, 1.0 op_sel:[0,1,0]
	v_cvt_scalef32_pk_bf16_fp4 v62, v119, 1.0 op_sel:[1,1,0]
	s_addc_u32 s27, s12, s27
	v_dot2c_f32_bf16_e32 v60, v54, v30
	v_dot2c_f32_bf16_e32 v52, v56, v28
	s_nop 0
	v_dot2c_f32_bf16_e32 v60, v58, v36
	v_dot2c_f32_bf16_e32 v52, v62, v34
	s_nop 0
	s_nop 2
	v_add_f32_e32 v81, v60, v52
	global_load_dwordx4 v[116:119], v32, s[26:27]
	s_waitcnt vmcnt(15)
	v_cvt_scalef32_pk_bf16_fp4 v52, v120, 1.0
	v_mov_b32_e32 v60, 0
	v_cvt_scalef32_pk_bf16_fp4 v54, v120, 1.0 op_sel:[1,0,0]
	v_cvt_scalef32_pk_bf16_fp4 v56, v120, 1.0 op_sel:[0,1,0]
	v_cvt_scalef32_pk_bf16_fp4 v58, v120, 1.0 op_sel:[1,1,0]
	v_dot2c_f32_bf16_e32 v60, v52, v6
	v_mov_b32_e32 v52, 0
	v_dot2c_f32_bf16_e32 v52, v54, v4
	v_dot2c_f32_bf16_e32 v60, v56, v10
	v_readlane_b32 s26, v2, 13
	v_dot2c_f32_bf16_e32 v52, v58, v8
	v_cvt_scalef32_pk_bf16_fp4 v54, v121, 1.0
	v_cvt_scalef32_pk_bf16_fp4 v56, v121, 1.0 op_sel:[1,0,0]
	v_cvt_scalef32_pk_bf16_fp4 v58, v121, 1.0 op_sel:[0,1,0]
	v_cvt_scalef32_pk_bf16_fp4 v62, v121, 1.0 op_sel:[1,1,0]
	s_lshr_b32 s26, s26, 7
	v_dot2c_f32_bf16_e32 v60, v54, v14
	v_dot2c_f32_bf16_e32 v52, v56, v12
	s_mov_b32 s27, s86
	v_dot2c_f32_bf16_e32 v60, v58, v18
	v_dot2c_f32_bf16_e32 v52, v62, v16
	v_cvt_scalef32_pk_bf16_fp4 v54, v122, 1.0
	v_cvt_scalef32_pk_bf16_fp4 v56, v122, 1.0 op_sel:[1,0,0]
	v_cvt_scalef32_pk_bf16_fp4 v58, v122, 1.0 op_sel:[0,1,0]
	v_cvt_scalef32_pk_bf16_fp4 v62, v122, 1.0 op_sel:[1,1,0]
	s_lshl_b64 s[26:27], s[26:27], 10
	v_dot2c_f32_bf16_e32 v60, v54, v22
	v_dot2c_f32_bf16_e32 v52, v56, v20
	s_add_u32 s26, s13, s26
	v_dot2c_f32_bf16_e32 v60, v58, v26
	v_dot2c_f32_bf16_e32 v52, v62, v24
	v_cvt_scalef32_pk_bf16_fp4 v54, v123, 1.0
	v_cvt_scalef32_pk_bf16_fp4 v56, v123, 1.0 op_sel:[1,0,0]
	v_cvt_scalef32_pk_bf16_fp4 v58, v123, 1.0 op_sel:[0,1,0]
	v_cvt_scalef32_pk_bf16_fp4 v62, v123, 1.0 op_sel:[1,1,0]
	s_addc_u32 s27, s12, s27
	v_dot2c_f32_bf16_e32 v60, v54, v30
	v_dot2c_f32_bf16_e32 v52, v56, v28
	s_nop 0
	v_dot2c_f32_bf16_e32 v60, v58, v36
	v_dot2c_f32_bf16_e32 v52, v62, v34
	s_nop 0
	s_nop 2
	v_add_f32_e32 v82, v60, v52
	global_load_dwordx4 v[120:123], v32, s[26:27]
	s_waitcnt vmcnt(15)
	v_cvt_scalef32_pk_bf16_fp4 v52, v124, 1.0
	v_mov_b32_e32 v60, 0
	v_cvt_scalef32_pk_bf16_fp4 v54, v124, 1.0 op_sel:[1,0,0]
	v_cvt_scalef32_pk_bf16_fp4 v56, v124, 1.0 op_sel:[0,1,0]
	v_cvt_scalef32_pk_bf16_fp4 v58, v124, 1.0 op_sel:[1,1,0]
	v_dot2c_f32_bf16_e32 v60, v52, v6
	v_mov_b32_e32 v52, 0
	v_dot2c_f32_bf16_e32 v52, v54, v4
	v_dot2c_f32_bf16_e32 v60, v56, v10
	v_readlane_b32 s26, v2, 14
	v_dot2c_f32_bf16_e32 v52, v58, v8
	v_cvt_scalef32_pk_bf16_fp4 v54, v125, 1.0
	v_cvt_scalef32_pk_bf16_fp4 v56, v125, 1.0 op_sel:[1,0,0]
	v_cvt_scalef32_pk_bf16_fp4 v58, v125, 1.0 op_sel:[0,1,0]
	v_cvt_scalef32_pk_bf16_fp4 v62, v125, 1.0 op_sel:[1,1,0]
	s_lshr_b32 s26, s26, 7
	v_dot2c_f32_bf16_e32 v60, v54, v14
	v_dot2c_f32_bf16_e32 v52, v56, v12
	s_mov_b32 s27, s86
	v_dot2c_f32_bf16_e32 v60, v58, v18
	v_dot2c_f32_bf16_e32 v52, v62, v16
	v_cvt_scalef32_pk_bf16_fp4 v54, v126, 1.0
	v_cvt_scalef32_pk_bf16_fp4 v56, v126, 1.0 op_sel:[1,0,0]
	v_cvt_scalef32_pk_bf16_fp4 v58, v126, 1.0 op_sel:[0,1,0]
	v_cvt_scalef32_pk_bf16_fp4 v62, v126, 1.0 op_sel:[1,1,0]
	s_lshl_b64 s[26:27], s[26:27], 10
	v_dot2c_f32_bf16_e32 v60, v54, v22
	v_dot2c_f32_bf16_e32 v52, v56, v20
	s_add_u32 s26, s13, s26
	v_dot2c_f32_bf16_e32 v60, v58, v26
	v_dot2c_f32_bf16_e32 v52, v62, v24
	v_cvt_scalef32_pk_bf16_fp4 v54, v127, 1.0
	v_cvt_scalef32_pk_bf16_fp4 v56, v127, 1.0 op_sel:[1,0,0]
	v_cvt_scalef32_pk_bf16_fp4 v58, v127, 1.0 op_sel:[0,1,0]
	v_cvt_scalef32_pk_bf16_fp4 v62, v127, 1.0 op_sel:[1,1,0]
	s_addc_u32 s27, s12, s27
	v_dot2c_f32_bf16_e32 v60, v54, v30
	v_dot2c_f32_bf16_e32 v52, v56, v28
	s_nop 0
	v_dot2c_f32_bf16_e32 v60, v58, v36
	v_dot2c_f32_bf16_e32 v52, v62, v34
	s_nop 0
	s_nop 2
	v_add_f32_e32 v62, v60, v52
	v_lshl_add_u64 v[52:53], s[26:27], 0, v[32:33]
	v_mov_b32_e32 v60, 0
	global_load_dwordx4 v[124:127], v[52:53], off
	s_waitcnt vmcnt(15)
; __device__ __forceinline__ float gelu_tanh(float h) {
;     return 0.5f * h * (1.f + tanhf(0.7978845608028654f * (h + 0.044715f * h * h * h)));
; }
	v_cvt_scalef32_pk_bf16_fp4 v52, v128, 1.0
	v_cvt_scalef32_pk_bf16_fp4 v54, v128, 1.0 op_sel:[1,0,0]
	v_cvt_scalef32_pk_bf16_fp4 v56, v128, 1.0 op_sel:[0,1,0]
	v_cvt_scalef32_pk_bf16_fp4 v58, v128, 1.0 op_sel:[1,1,0]
	v_readlane_b32 s26, v2, 15
	v_dot2c_f32_bf16_e32 v60, v52, v6
	v_dot2c_f32_bf16_e32 v38, v54, v4
	s_lshr_b32 s26, s26, 7
	v_dot2c_f32_bf16_e32 v60, v56, v10
	v_dot2c_f32_bf16_e32 v38, v58, v8
	v_cvt_scalef32_pk_bf16_fp4 v4, v129, 1.0
	v_cvt_scalef32_pk_bf16_fp4 v6, v129, 1.0 op_sel:[1,0,0]
	v_cvt_scalef32_pk_bf16_fp4 v8, v129, 1.0 op_sel:[0,1,0]
	v_cvt_scalef32_pk_bf16_fp4 v10, v129, 1.0 op_sel:[1,1,0]
	s_mov_b32 s27, s86
	v_dot2c_f32_bf16_e32 v60, v4, v14
	v_dot2c_f32_bf16_e32 v38, v6, v12
	s_lshl_b64 s[26:27], s[26:27], 10
	v_dot2c_f32_bf16_e32 v60, v8, v18
	v_dot2c_f32_bf16_e32 v38, v10, v16
	v_cvt_scalef32_pk_bf16_fp4 v4, v130, 1.0
	v_cvt_scalef32_pk_bf16_fp4 v6, v130, 1.0 op_sel:[1,0,0]
	v_cvt_scalef32_pk_bf16_fp4 v8, v130, 1.0 op_sel:[0,1,0]
	v_cvt_scalef32_pk_bf16_fp4 v10, v130, 1.0 op_sel:[1,1,0]
	s_add_u32 s26, s13, s26
	v_dot2c_f32_bf16_e32 v60, v4, v22
	v_dot2c_f32_bf16_e32 v38, v6, v20
	s_addc_u32 s27, s12, s27
	v_dot2c_f32_bf16_e32 v60, v8, v26
	v_dot2c_f32_bf16_e32 v38, v10, v24
	v_cvt_scalef32_pk_bf16_fp4 v4, v131, 1.0
	v_cvt_scalef32_pk_bf16_fp4 v6, v131, 1.0 op_sel:[1,0,0]
	v_cvt_scalef32_pk_bf16_fp4 v8, v131, 1.0 op_sel:[0,1,0]
	v_cvt_scalef32_pk_bf16_fp4 v10, v131, 1.0 op_sel:[1,1,0]
	v_cndmask_b32_e64 v2, v49, v41, s[46:47]
	v_dot2c_f32_bf16_e32 v60, v4, v30
	v_dot2c_f32_bf16_e32 v38, v6, v28
	v_cndmask_b32_e64 v7, v43, v51, s[46:47]
	v_dot2c_f32_bf16_e32 v60, v8, v36
	v_dot2c_f32_bf16_e32 v38, v10, v34
	ds_swizzle_b32 v7, v7 offset:swizzle(SWAP,8)
	s_nop 2
	v_add_f32_e32 v6, v60, v38
	global_load_dwordx4 v[128:131], v32, s[26:27]
	v_cndmask_b32_e64 v4, v41, v49, s[46:47]
	ds_swizzle_b32 v4, v4 offset:swizzle(SWAP,8)
	v_cndmask_b32_e64 v5, v42, v50, s[46:47]
	ds_swizzle_b32 v5, v5 offset:swizzle(SWAP,8)
	v_cndmask_b32_e64 v8, v44, v80, s[46:47]
	ds_swizzle_b32 v8, v8 offset:swizzle(SWAP,8)
	v_cndmask_b32_e64 v9, v45, v81, s[46:47]
	ds_swizzle_b32 v9, v9 offset:swizzle(SWAP,8)
	v_cndmask_b32_e64 v10, v46, v82, s[46:47]
	s_waitcnt lgkmcnt(3)
	v_add_f32_e32 v2, v2, v4
	v_cndmask_b32_e64 v4, v50, v42, s[46:47]
	ds_swizzle_b32 v10, v10 offset:swizzle(SWAP,8)
	v_cndmask_b32_e64 v11, v47, v62, s[46:47]
	s_waitcnt lgkmcnt(3)
	v_add_f32_e32 v4, v4, v5
	v_cndmask_b32_e64 v5, v51, v43, s[46:47]
	ds_swizzle_b32 v11, v11 offset:swizzle(SWAP,8)
	v_add_f32_e32 v5, v5, v7
	v_cndmask_b32_e64 v7, v80, v44, s[46:47]
	s_waitcnt lgkmcnt(3)
	v_add_f32_e32 v7, v7, v8
	v_cndmask_b32_e64 v8, v81, v45, s[46:47]
	s_waitcnt lgkmcnt(2)
	v_add_f32_e32 v8, v8, v9
	v_cndmask_b32_e64 v9, v82, v46, s[46:47]
	s_waitcnt lgkmcnt(1)
	v_add_f32_e32 v9, v9, v10
	v_cndmask_b32_e64 v10, v62, v47, s[46:47]
	s_waitcnt lgkmcnt(0)
	v_add_f32_e32 v10, v10, v11
	v_cndmask_b32_e64 v11, v6, v48, s[46:47]
	v_cndmask_b32_e64 v6, v48, v6, s[46:47]
	ds_swizzle_b32 v6, v6 offset:swizzle(SWAP,8)
	s_waitcnt lgkmcnt(0)
	v_add_f32_e32 v6, v11, v6
	v_cndmask_b32_e64 v11, v8, v2, s[44:45]
	v_cndmask_b32_e64 v2, v2, v8, s[44:45]
	v_cndmask_b32_e64 v8, v9, v4, s[44:45]
	v_cndmask_b32_e64 v4, v4, v9, s[44:45]
	ds_swizzle_b32 v4, v4 offset:swizzle(SWAP,4)
	ds_swizzle_b32 v2, v2 offset:swizzle(SWAP,4)
	s_waitcnt lgkmcnt(1)
	v_add_f32_e32 v4, v8, v4
	v_cndmask_b32_e64 v8, v10, v5, s[44:45]
	v_cndmask_b32_e64 v5, v5, v10, s[44:45]
	ds_swizzle_b32 v5, v5 offset:swizzle(SWAP,4)
	s_waitcnt lgkmcnt(1)
	v_add_f32_e32 v2, v11, v2
	s_waitcnt lgkmcnt(0)
	v_add_f32_e32 v5, v8, v5
	v_cndmask_b32_e64 v8, v6, v7, s[44:45]
	v_cndmask_b32_e64 v6, v7, v6, s[44:45]
	ds_swizzle_b32 v6, v6 offset:swizzle(SWAP,4)
	v_cndmask_b32_e64 v7, v5, v2, s[42:43]
	v_cndmask_b32_e64 v2, v2, v5, s[42:43]
	ds_swizzle_b32 v2, v2 offset:swizzle(SWAP,2)
	s_waitcnt lgkmcnt(1)
	v_add_f32_e32 v6, v8, v6
	v_cndmask_b32_e64 v5, v6, v4, s[42:43]
	v_cndmask_b32_e64 v4, v4, v6, s[42:43]
	ds_swizzle_b32 v4, v4 offset:swizzle(SWAP,2)
	s_waitcnt lgkmcnt(1)
	v_add_f32_e32 v2, v7, v2
	s_waitcnt lgkmcnt(0)
	v_add_f32_e32 v4, v5, v4
	v_cndmask_b32_e64 v5, v4, v2, s[40:41]
	v_cndmask_b32_e64 v2, v2, v4, s[40:41]
	ds_swizzle_b32 v2, v2 offset:swizzle(SWAP,1)
	s_waitcnt lgkmcnt(0)
	v_add_f32_e32 v2, v5, v2
	ds_swizzle_b32 v4, v2 offset:swizzle(SWAP,16)
	s_waitcnt lgkmcnt(0)
	v_add_f32_e32 v2, v2, v4
	v_mov_b32_e32 v4, v2
	s_nop 1
	v_permlane32_swap_b32_e32 v2, v4
	v_add_f32_e32 v6, v2, v4
	v_lshl_add_u32 v2, v40, 2, s14
	v_add_u32_e32 v4, 0xc0, v2
	ds_read2st64_b32 v[4:5], v4 offset0:9 offset1:17
	s_waitcnt lgkmcnt(0)
	v_mul_f32_e32 v4, v4, v6
	v_mul_f32_e32 v6, 0x3d372713, v4
	v_mul_f32_e32 v6, v4, v6
	v_fma_f32 v6, v4, v6, v4
	v_mul_f32_e32 v6, 0x3f4c422a, v6
	v_cmp_nlt_f32_e64 s[12:13], |v6|, s25
	s_and_saveexec_b64 s[26:27], s[12:13]
	s_xor_b64 s[12:13], exec, s[26:27]
	s_cbranch_execz .LBB0_1240
	v_add_f32_e64 v7, |v6|, |v6|
	v_mul_f32_e32 v8, 0x3fb8aa3b, v7
	v_rndne_f32_e32 v9, v8
	v_sub_f32_e32 v10, v8, v9
	v_fma_f32 v8, v7, s70, -v8
	v_fmac_f32_e32 v8, 0x32a5705f, v7
	v_add_f32_e32 v8, v10, v8
	v_cvt_i32_f32_e32 v9, v9
	v_exp_f32_e32 v8, v8
	v_cmp_ngt_f32_e64 s[40:41], s67, v7
	v_ldexp_f32 v8, v8, v9
	s_nop 0
	v_cndmask_b32_e64 v8, 0, v8, s[40:41]
	v_cmp_nlt_f32_e64 s[40:41], s68, v7
	s_nop 1
	v_cndmask_b32_e64 v7, v205, v8, s[40:41]
	v_add_f32_e32 v7, 1.0, v7
	v_rcp_f32_e32 v7, v7
	s_nop 0
	v_fma_f32 v7, v7, -2.0, 1.0
	s_andn2_saveexec_b64 s[12:13], s[12:13]
	s_cbranch_execnz .LBB0_1241
